# GEMM K-loops: MFMA-segment barrier issued 6 MFMAs before the segment end (was 2), trailing six at priority 2
# baseline (speedup 1.0000x reference)
;     __host__ __device__ bool next(int i, Unit& u) const { const int L = i * G + c; if (L >= 4 * nM) return false; u.pm = L >> 2; u.pn = 0; u.kq = L & 3; return true; }
; #define PG8_WAIT_V(n) asm volatile("s_waitcnt vmcnt(" #n ")" ::: "memory")
; #define PG8_BAR __builtin_amdgcn_s_barrier()
; template <class Epi, class Sched, bool ALIGN_EPI = false, bool SP2 = false>
; __device__ __forceinline__ void gemm_phase(PG8_LAS unsigned char* lds, const Gemm g, const Sched& S, const Epi& E) {
;     ...
;         const bool has_next = S.next(ui + 1, nxt);
;         const char* nA = has_next ? (const char*)g.A + (size_t)nxt.pm * tstepA + nxt.kq * g.kq_bytes : cA; const char* nB = has_next ? (const char*)g.Bt + (size_t)nxt.pn * tstepB + nxt.kq * g.kq_bytes : cB;
;         for (int t = 0; t < nt; t += 2) {
;             const bool last = (t == nt - 2);
;             const char* a1 = cA + (size_t)(t + 1) * kstep + (t >= g.kj_t ? g.kj_bytes : 0);
;             const char* a2 = last ? nA : cA + (size_t)(t + 2) * kstep + (t + 2 >= g.kj_t ? g.kj_bytes : 0); const char* b2 = last ? nB : cB + (size_t)(t + 2) * kstep;
;             const char* a3 = a2 + kstep; const char* b3 = b2 + kstep;
;             if (last && has_next) S.a_ready(nxt);
;             if constexpr (Epi::MIDK) { if (t == g.kj_t) E.midk(acc, cur, wr, fr); }
;             if constexpr (SP2) {
;             PG8_LDB(B0, 0, 0); PG8_LDB(B1, 0, 1); PG8_SCHED; PG8_LDA(At, 0, 0); PG8_STAGE(PG8_SA(1, 1), a1 + hstepA, voffA);
;             PG8_WAIT_V(8); PG8_WAIT_L(0); PG8_BAR; PG8_MMA(0, 0, At, B0); PG8_MMA(0, 1, At, B1); PG8_BAR; PG8_SCHED;
;             PG8_LDA(At, 0, 1); PG8_STAGE(PG8_SB(0, 0), b2, voffB); PG8_STAGE(PG8_SB(0, 1), b2 + hstepB, voffB); PG8_STAGE(PG8_SA(0, 0), a2, voffA);
;             PG8_WAIT_V(8); PG8_WAIT_L(0); PG8_BAR; PG8_MMA(1, 0, At, B0); PG8_MMA(1, 1, At, B1); PG8_BAR; PG8_SCHED;
;             PG8_LDB(B0, 1, 0); PG8_LDB(B1, 1, 1); PG8_SCHED; PG8_LDA(At, 1, 0); PG8_STAGE(PG8_SA(0, 1), a2 + hstepA, voffA);
;             PG8_WAIT_V(8); PG8_WAIT_L(0); PG8_BAR; PG8_MMA(0, 0, At, B0); PG8_MMA(0, 1, At, B1); PG8_BAR; PG8_SCHED;
;             PG8_LDA(At, 1, 1); PG8_STAGE(PG8_SB(1, 0), b3, voffB); PG8_STAGE(PG8_SB(1, 1), b3 + hstepB, voffB); PG8_STAGE(PG8_SA(1, 0), a3, voffA);
;             PG8_WAIT_V(8); PG8_WAIT_L(0); PG8_BAR; PG8_MMA(1, 0, At, B0); PG8_MMA(1, 1, At, B1); PG8_BAR; PG8_SCHED;
.LBB0_78:
	s_ashr_i32 s17, s16, 31
	s_lshl_b64 s[18:19], s[16:17], 21
	s_add_u32 s18, s42, s18
	s_addc_u32 s19, s43, s19
	s_and_b64 s[20:21], s[4:5], exec
	s_cselect_b32 s17, s19, s23
	s_cselect_b32 s60, s18, s22
	s_ashr_i32 s15, s14, 31
	s_lshl_b64 s[20:21], s[14:15], 21
	s_add_u32 s20, s70, s20
	s_addc_u32 s21, s71, s21
	s_and_b64 s[26:27], s[4:5], exec
	s_cselect_b32 s15, s21, s25
	s_cselect_b32 s61, s20, s24
	s_add_u32 s22, s22, 0x100080
	s_addc_u32 s23, s23, 0
	s_add_u32 s62, s24, 0x100
	s_addc_u32 s63, s25, 0
	s_mov_b32 s64, -2
	ds_read_b128 v[152:155], v148
	ds_read_b128 v[156:159], v148 offset:1024
	ds_read_b128 v[160:163], v148 offset:2048
	ds_read_b128 v[168:171], v148 offset:3072
	ds_read_b128 v[172:175], v149
	ds_read_b128 v[176:179], v149 offset:1024
	ds_read_b128 v[180:183], v149 offset:2048
	ds_read_b128 v[184:187], v149 offset:3072
	s_add_u32 s24, s22, 0xfff00080
	s_addc_u32 s25, s23, -1
	s_cmp_eq_u32 s64, 60
	s_cselect_b32 s27, s17, s25
	s_cselect_b32 s26, s60, s24
	s_cselect_b32 s25, s15, s63
	s_cselect_b32 s24, s61, s62
	s_add_u32 s98, s24, 0x80
	s_addc_u32 s99, s25, 0
	s_add_u32 s100, s26, 0x80
	s_addc_u32 s101, s27, 0
	s_add_i32 m0, s13, 0xc000
	ds_read_b128 v[188:191], v150
	ds_read_b128 v[192:195], v150 offset:1024
	ds_read_b128 v[196:199], v150 offset:2048
	ds_read_b128 v[200:203], v150 offset:3072
	ds_read_b128 v[204:207], v150 offset:4096
	ds_read_b128 v[208:211], v150 offset:5120
	ds_read_b128 v[212:215], v150 offset:6144
	ds_read_b128 v[216:219], v150 offset:7168
	global_load_lds_dwordx4 v138, s[22:23]
	s_add_i32 m0, s13, 0xe000
	s_nop 0
	global_load_lds_dwordx4 v140, s[22:23]
	s_waitcnt vmcnt(8)
	s_waitcnt lgkmcnt(0)
	s_barrier
	s_setprio 1
	s_waitcnt lgkmcnt(0)
	v_mfma_f32_16x16x32_bf16 v[126:129], v[152:155], v[188:191], 0
	v_mfma_f32_16x16x32_bf16 v[126:129], v[156:159], v[192:195], v[126:129]
	v_mfma_f32_16x16x32_bf16 v[122:125], v[168:171], v[192:195], 0
	v_mfma_f32_16x16x32_bf16 v[122:125], v[160:163], v[188:191], v[122:125]
	v_mfma_f32_16x16x32_bf16 v[114:117], v[160:163], v[196:199], 0
	v_mfma_f32_16x16x32_bf16 v[114:117], v[168:171], v[200:203], v[114:117]
	v_mfma_f32_16x16x32_bf16 v[118:121], v[156:159], v[200:203], 0
	v_mfma_f32_16x16x32_bf16 v[118:121], v[152:155], v[196:199], v[118:121]
	v_mfma_f32_16x16x32_bf16 v[102:105], v[152:155], v[204:207], 0
	v_mfma_f32_16x16x32_bf16 v[102:105], v[156:159], v[208:211], v[102:105]
	v_mfma_f32_16x16x32_bf16 v[98:101], v[168:171], v[208:211], 0
	v_mfma_f32_16x16x32_bf16 v[98:101], v[160:163], v[204:207], v[98:101]
	v_mfma_f32_16x16x32_bf16 v[82:85], v[160:163], v[212:215], 0
	v_mfma_f32_16x16x32_bf16 v[82:85], v[168:171], v[216:219], v[82:85]
	v_mfma_f32_16x16x32_bf16 v[86:89], v[156:159], v[216:219], 0
	v_mfma_f32_16x16x32_bf16 v[86:89], v[152:155], v[212:215], v[86:89]
	v_mfma_f32_16x16x32_bf16 v[110:113], v[172:175], v[188:191], 0
	v_mfma_f32_16x16x32_bf16 v[110:113], v[176:179], v[192:195], v[110:113]
	v_mfma_f32_16x16x32_bf16 v[106:109], v[184:187], v[192:195], 0
	v_mfma_f32_16x16x32_bf16 v[106:109], v[180:183], v[188:191], v[106:109]
	v_mfma_f32_16x16x32_bf16 v[90:93], v[180:183], v[196:199], 0
	v_mfma_f32_16x16x32_bf16 v[90:93], v[184:187], v[200:203], v[90:93]
	v_mfma_f32_16x16x32_bf16 v[94:97], v[176:179], v[200:203], 0
	v_mfma_f32_16x16x32_bf16 v[94:97], v[172:175], v[196:199], v[94:97]
	v_mfma_f32_16x16x32_bf16 v[78:81], v[172:175], v[204:207], 0
	v_mfma_f32_16x16x32_bf16 v[78:81], v[176:179], v[208:211], v[78:81]
	s_setprio 2
	s_barrier
	v_mfma_f32_16x16x32_bf16 v[74:77], v[184:187], v[208:211], 0
	v_mfma_f32_16x16x32_bf16 v[74:77], v[180:183], v[204:207], v[74:77]
	v_mfma_f32_16x16x32_bf16 v[66:69], v[180:183], v[212:215], 0
	v_mfma_f32_16x16x32_bf16 v[66:69], v[184:187], v[216:219], v[66:69]
	v_mfma_f32_16x16x32_bf16 v[70:73], v[176:179], v[216:219], 0
	v_mfma_f32_16x16x32_bf16 v[70:73], v[172:175], v[212:215], v[70:73]
	s_setprio 0
	s_add_i32 s65, s38, s3
	s_mov_b32 m0, s65
	ds_read_b128 v[188:191], v150 offset:16384
	ds_read_b128 v[192:195], v150 offset:17408
	ds_read_b128 v[196:199], v150 offset:18432
	ds_read_b128 v[200:203], v150 offset:19456
	ds_read_b128 v[204:207], v150 offset:20480
	ds_read_b128 v[208:211], v150 offset:21504
	ds_read_b128 v[212:215], v150 offset:22528
	ds_read_b128 v[216:219], v150 offset:23552
	global_load_lds_dwordx4 v134, s[24:25]
	s_add_i32 m0, s65, 0x2000
	s_add_u32 s66, s24, 0x100000
	s_addc_u32 s67, s25, 0
	s_add_i32 s65, s39, s3
	global_load_lds_dwordx4 v130, s[24:25]
	s_mov_b32 m0, s65
	s_nop 0
	global_load_lds_dwordx4 v134, s[66:67]
	s_add_i32 m0, s65, 0x2000
	s_nop 0
	global_load_lds_dwordx4 v130, s[66:67]
	s_mov_b32 m0, s13
	s_nop 0
	global_load_lds_dwordx4 v136, s[26:27]
	s_mov_b32 m0, s30
	s_nop 0
	global_load_lds_dwordx4 v132, s[26:27]
	s_waitcnt vmcnt(8)
	s_waitcnt lgkmcnt(0)
	s_barrier
; #define PG8_STAGE(bufoff, gbase, voff) do { _Pragma("unroll") for (int _i = 0; _i < 2; ++_i) \
;         __builtin_amdgcn_global_load_lds((const unsigned*)((const char*)(gbase) + (voff)[_i]), (PG8_LAS unsigned*)(lds + (bufoff) + ldsw + _i * 8192), 16, 0, 0); } while (0)
; #define PG8_LDA(dst, b, h) do { _Pragma("unroll") for (int m = 0; m < 4; ++m) _Pragma("unroll") for (int k = 0; k < 2; ++k) dst[m][k] = *(const PG8_LAS bf16x8*)(lds + PG8_SA(b, h) + aoff + m * 2048 + k * 1024); } while (0)
; #define PG8_LDB(dst, b, h) do { _Pragma("unroll") for (int n = 0; n < 2; ++n) _Pragma("unroll") for (int k = 0; k < 2; ++k) dst[n][k] = *(const PG8_LAS bf16x8*)(lds + PG8_SB(b, h) + boff + n * 2048 + k * 1024); } while (0)
; #define PG8_MMA(ai, bj, At, Bt) do { __builtin_amdgcn_s_setprio(1); _Pragma("unroll") for (int m = 0; m < 4; ++m) _Pragma("unroll") for (int n = 0; n < 2; ++n) _Pragma("unroll") for (int k = 0; k < 2; ++k) \
;         acc[ai][bj][m][n] = __builtin_amdgcn_mfma_f32_16x16x32_bf16(Bt[n][k], At[m][k], acc[ai][bj][m][n], 0, 0, 0); __builtin_amdgcn_s_setprio(0); } while (0)
; template <class Epi, class Sched, bool ALIGN_EPI = false, bool SP2 = false>
; __device__ __forceinline__ void gemm_phase(PG8_LAS unsigned char* lds, const Gemm g, const Sched& S, const Epi& E) {
;     ...
;             if constexpr (SP2) {
;             PG8_LDB(B0, 0, 0); PG8_LDB(B1, 0, 1); PG8_SCHED; PG8_LDA(At, 0, 0); PG8_STAGE(PG8_SA(1, 1), a1 + hstepA, voffA);
;             PG8_WAIT_V(8); PG8_WAIT_L(0); PG8_BAR; PG8_MMA(0, 0, At, B0); PG8_MMA(0, 1, At, B1); PG8_BAR; PG8_SCHED;
;             PG8_LDA(At, 0, 1); PG8_STAGE(PG8_SB(0, 0), b2, voffB); PG8_STAGE(PG8_SB(0, 1), b2 + hstepB, voffB); PG8_STAGE(PG8_SA(0, 0), a2, voffA);
;             PG8_WAIT_V(8); PG8_WAIT_L(0); PG8_BAR; PG8_MMA(1, 0, At, B0); PG8_MMA(1, 1, At, B1); PG8_BAR; PG8_SCHED;
;             PG8_LDB(B0, 1, 0); PG8_LDB(B1, 1, 1); PG8_SCHED; PG8_LDA(At, 1, 0); PG8_STAGE(PG8_SA(0, 1), a2 + hstepA, voffA);
;             PG8_WAIT_V(8); PG8_WAIT_L(0); PG8_BAR; PG8_MMA(0, 0, At, B0); PG8_MMA(0, 1, At, B1); PG8_BAR; PG8_SCHED;
;             PG8_LDA(At, 1, 1); PG8_STAGE(PG8_SB(1, 0), b3, voffB); PG8_STAGE(PG8_SB(1, 1), b3 + hstepB, voffB); PG8_STAGE(PG8_SA(1, 0), a3, voffA);
;             PG8_WAIT_V(8); PG8_WAIT_L(0); PG8_BAR; PG8_MMA(1, 0, At, B0); PG8_MMA(1, 1, At, B1); PG8_BAR; PG8_SCHED;
	s_setprio 1
	s_waitcnt lgkmcnt(0)
	v_mfma_f32_16x16x32_bf16 v[62:65], v[152:155], v[188:191], 0
	v_mfma_f32_16x16x32_bf16 v[62:65], v[156:159], v[192:195], v[62:65]
	v_mfma_f32_16x16x32_bf16 v[58:61], v[168:171], v[192:195], 0
	v_mfma_f32_16x16x32_bf16 v[58:61], v[160:163], v[188:191], v[58:61]
	v_mfma_f32_16x16x32_bf16 v[50:53], v[160:163], v[196:199], 0
	v_mfma_f32_16x16x32_bf16 v[50:53], v[168:171], v[200:203], v[50:53]
	v_mfma_f32_16x16x32_bf16 v[54:57], v[156:159], v[200:203], 0
	v_mfma_f32_16x16x32_bf16 v[54:57], v[152:155], v[196:199], v[54:57]
	v_mfma_f32_16x16x32_bf16 v[38:41], v[152:155], v[204:207], 0
	v_mfma_f32_16x16x32_bf16 v[38:41], v[156:159], v[208:211], v[38:41]
	v_mfma_f32_16x16x32_bf16 v[34:37], v[168:171], v[208:211], 0
	v_mfma_f32_16x16x32_bf16 v[34:37], v[160:163], v[204:207], v[34:37]
	v_mfma_f32_16x16x32_bf16 v[18:21], v[160:163], v[212:215], 0
	v_mfma_f32_16x16x32_bf16 v[18:21], v[168:171], v[216:219], v[18:21]
	v_mfma_f32_16x16x32_bf16 v[22:25], v[156:159], v[216:219], 0
	v_mfma_f32_16x16x32_bf16 v[22:25], v[152:155], v[212:215], v[22:25]
	v_mfma_f32_16x16x32_bf16 v[46:49], v[172:175], v[188:191], 0
	v_mfma_f32_16x16x32_bf16 v[46:49], v[176:179], v[192:195], v[46:49]
	v_mfma_f32_16x16x32_bf16 v[42:45], v[184:187], v[192:195], 0
	v_mfma_f32_16x16x32_bf16 v[42:45], v[180:183], v[188:191], v[42:45]
	v_mfma_f32_16x16x32_bf16 v[26:29], v[180:183], v[196:199], 0
	v_mfma_f32_16x16x32_bf16 v[26:29], v[184:187], v[200:203], v[26:29]
	v_mfma_f32_16x16x32_bf16 v[30:33], v[176:179], v[200:203], 0
	v_mfma_f32_16x16x32_bf16 v[30:33], v[172:175], v[196:199], v[30:33]
	v_mfma_f32_16x16x32_bf16 v[14:17], v[172:175], v[204:207], 0
	v_mfma_f32_16x16x32_bf16 v[14:17], v[176:179], v[208:211], v[14:17]
	s_setprio 2
	s_barrier
	v_mfma_f32_16x16x32_bf16 v[10:13], v[184:187], v[208:211], 0
	v_mfma_f32_16x16x32_bf16 v[10:13], v[180:183], v[204:207], v[10:13]
	v_mfma_f32_16x16x32_bf16 v[2:5], v[180:183], v[212:215], 0
	v_mfma_f32_16x16x32_bf16 v[2:5], v[184:187], v[216:219], v[2:5]
	v_mfma_f32_16x16x32_bf16 v[6:9], v[176:179], v[216:219], 0
	v_mfma_f32_16x16x32_bf16 v[6:9], v[172:175], v[212:215], v[6:9]
	s_setprio 0
	s_add_i32 s65, 0, 0x18000
	v_add_u32_e32 v151, s65, v146
	s_add_i32 s66, 0, 0x1c000
	ds_read_b128 v[152:155], v151
	ds_read_b128 v[156:159], v151 offset:1024
	ds_read_b128 v[160:163], v151 offset:2048
	ds_read_b128 v[168:171], v151 offset:3072
	v_add_u32_e32 v151, s66, v146
	ds_read_b128 v[172:175], v151
	ds_read_b128 v[176:179], v151 offset:1024
	ds_read_b128 v[180:183], v151 offset:2048
	ds_read_b128 v[184:187], v151 offset:3072
	s_add_u32 s26, s26, 0x100000
	s_addc_u32 s27, s27, 0
	s_mov_b32 m0, s31
	ds_read_b128 v[188:191], v150 offset:32768
	ds_read_b128 v[192:195], v150 offset:33792
	ds_read_b128 v[196:199], v150 offset:34816
	ds_read_b128 v[200:203], v150 offset:35840
	ds_read_b128 v[204:207], v150 offset:36864
	ds_read_b128 v[208:211], v150 offset:37888
	ds_read_b128 v[212:215], v150 offset:38912
	ds_read_b128 v[216:219], v150 offset:39936
	global_load_lds_dwordx4 v136, s[26:27]
	s_mov_b32 m0, s33
	s_nop 0
	global_load_lds_dwordx4 v132, s[26:27]
	s_waitcnt vmcnt(8)
	s_waitcnt lgkmcnt(0)
	s_barrier
	s_setprio 1
	s_waitcnt lgkmcnt(0)
	v_mfma_f32_16x16x32_bf16 v[126:129], v[152:155], v[188:191], v[126:129]
	v_mfma_f32_16x16x32_bf16 v[126:129], v[156:159], v[192:195], v[126:129]
	v_mfma_f32_16x16x32_bf16 v[122:125], v[168:171], v[192:195], v[122:125]
	v_mfma_f32_16x16x32_bf16 v[122:125], v[160:163], v[188:191], v[122:125]
	v_mfma_f32_16x16x32_bf16 v[114:117], v[160:163], v[196:199], v[114:117]
	v_mfma_f32_16x16x32_bf16 v[114:117], v[168:171], v[200:203], v[114:117]
	v_mfma_f32_16x16x32_bf16 v[118:121], v[156:159], v[200:203], v[118:121]
	v_mfma_f32_16x16x32_bf16 v[118:121], v[152:155], v[196:199], v[118:121]
	v_mfma_f32_16x16x32_bf16 v[102:105], v[152:155], v[204:207], v[102:105]
	v_mfma_f32_16x16x32_bf16 v[102:105], v[156:159], v[208:211], v[102:105]
	v_mfma_f32_16x16x32_bf16 v[98:101], v[168:171], v[208:211], v[98:101]
	v_mfma_f32_16x16x32_bf16 v[98:101], v[160:163], v[204:207], v[98:101]
	v_mfma_f32_16x16x32_bf16 v[82:85], v[160:163], v[212:215], v[82:85]
	v_mfma_f32_16x16x32_bf16 v[82:85], v[168:171], v[216:219], v[82:85]
	v_mfma_f32_16x16x32_bf16 v[86:89], v[156:159], v[216:219], v[86:89]
	v_mfma_f32_16x16x32_bf16 v[86:89], v[152:155], v[212:215], v[86:89]
	v_mfma_f32_16x16x32_bf16 v[110:113], v[172:175], v[188:191], v[110:113]
	v_mfma_f32_16x16x32_bf16 v[110:113], v[176:179], v[192:195], v[110:113]
	v_mfma_f32_16x16x32_bf16 v[106:109], v[184:187], v[192:195], v[106:109]
	v_mfma_f32_16x16x32_bf16 v[106:109], v[180:183], v[188:191], v[106:109]
	v_mfma_f32_16x16x32_bf16 v[90:93], v[180:183], v[196:199], v[90:93]
	v_mfma_f32_16x16x32_bf16 v[90:93], v[184:187], v[200:203], v[90:93]
	v_mfma_f32_16x16x32_bf16 v[94:97], v[176:179], v[200:203], v[94:97]
	v_mfma_f32_16x16x32_bf16 v[94:97], v[172:175], v[196:199], v[94:97]
	v_mfma_f32_16x16x32_bf16 v[78:81], v[172:175], v[204:207], v[78:81]
	v_mfma_f32_16x16x32_bf16 v[78:81], v[176:179], v[208:211], v[78:81]
	s_setprio 2
	s_barrier
; #define PG8_STAGE(bufoff, gbase, voff) do { _Pragma("unroll") for (int _i = 0; _i < 2; ++_i) \
;         __builtin_amdgcn_global_load_lds((const unsigned*)((const char*)(gbase) + (voff)[_i]), (PG8_LAS unsigned*)(lds + (bufoff) + ldsw + _i * 8192), 16, 0, 0); } while (0)
; #define PG8_LDA(dst, b, h) do { _Pragma("unroll") for (int m = 0; m < 4; ++m) _Pragma("unroll") for (int k = 0; k < 2; ++k) dst[m][k] = *(const PG8_LAS bf16x8*)(lds + PG8_SA(b, h) + aoff + m * 2048 + k * 1024); } while (0)
; #define PG8_BAR __builtin_amdgcn_s_barrier()
; template <class Epi, class Sched, bool ALIGN_EPI = false, bool SP2 = false>
; __device__ __forceinline__ void gemm_phase(PG8_LAS unsigned char* lds, const Gemm g, const Sched& S, const Epi& E) {
;     ...
;         for (int t = 0; t < nt; t += 2) {
;             const bool last = (t == nt - 2);
;             const char* a1 = cA + (size_t)(t + 1) * kstep + (t >= g.kj_t ? g.kj_bytes : 0);
;             const char* a2 = last ? nA : cA + (size_t)(t + 2) * kstep + (t + 2 >= g.kj_t ? g.kj_bytes : 0); const char* b2 = last ? nB : cB + (size_t)(t + 2) * kstep;
;             const char* a3 = a2 + kstep; const char* b3 = b2 + kstep;
;             if (last && has_next) S.a_ready(nxt);
;             if constexpr (Epi::MIDK) { if (t == g.kj_t) E.midk(acc, cur, wr, fr); }
;             if constexpr (SP2) {
;             PG8_LDB(B0, 0, 0); PG8_LDB(B1, 0, 1); PG8_SCHED; PG8_LDA(At, 0, 0); PG8_STAGE(PG8_SA(1, 1), a1 + hstepA, voffA);
;             PG8_WAIT_V(8); PG8_WAIT_L(0); PG8_BAR; PG8_MMA(0, 0, At, B0); PG8_MMA(0, 1, At, B1); PG8_BAR; PG8_SCHED;
;             PG8_LDA(At, 0, 1); PG8_STAGE(PG8_SB(0, 0), b2, voffB); PG8_STAGE(PG8_SB(0, 1), b2 + hstepB, voffB); PG8_STAGE(PG8_SA(0, 0), a2, voffA);
;             PG8_WAIT_V(8); PG8_WAIT_L(0); PG8_BAR; PG8_MMA(1, 0, At, B0); PG8_MMA(1, 1, At, B1); PG8_BAR; PG8_SCHED;
;             PG8_LDB(B0, 1, 0); PG8_LDB(B1, 1, 1); PG8_SCHED; PG8_LDA(At, 1, 0); PG8_STAGE(PG8_SA(0, 1), a2 + hstepA, voffA);
;             PG8_WAIT_V(8); PG8_WAIT_L(0); PG8_BAR; PG8_MMA(0, 0, At, B0); PG8_MMA(0, 1, At, B1); PG8_BAR; PG8_SCHED;
;             PG8_LDA(At, 1, 1); PG8_STAGE(PG8_SB(1, 0), b3, voffB); PG8_STAGE(PG8_SB(1, 1), b3 + hstepB, voffB); PG8_STAGE(PG8_SA(1, 0), a3, voffA);
;             PG8_WAIT_V(8); PG8_WAIT_L(0); PG8_BAR; PG8_MMA(1, 0, At, B0); PG8_MMA(1, 1, At, B1); PG8_BAR; PG8_SCHED;
	v_mfma_f32_16x16x32_bf16 v[74:77], v[184:187], v[208:211], v[74:77]
	v_mfma_f32_16x16x32_bf16 v[74:77], v[180:183], v[204:207], v[74:77]
	v_mfma_f32_16x16x32_bf16 v[66:69], v[180:183], v[212:215], v[66:69]
	v_mfma_f32_16x16x32_bf16 v[66:69], v[184:187], v[216:219], v[66:69]
	v_mfma_f32_16x16x32_bf16 v[70:73], v[176:179], v[216:219], v[70:73]
	v_mfma_f32_16x16x32_bf16 v[70:73], v[172:175], v[212:215], v[70:73]
	s_setprio 0
	s_add_i32 s26, s65, s3
	s_mov_b32 m0, s26
	ds_read_b128 v[188:191], v150 offset:49152
	ds_read_b128 v[192:195], v150 offset:50176
	ds_read_b128 v[196:199], v150 offset:51200
	ds_read_b128 v[200:203], v150 offset:52224
	ds_read_b128 v[204:207], v150 offset:53248
	ds_read_b128 v[208:211], v150 offset:54272
	ds_read_b128 v[212:215], v150 offset:55296
	ds_read_b128 v[216:219], v150 offset:56320
	global_load_lds_dwordx4 v134, s[98:99]
	s_add_i32 m0, s26, 0x2000
	s_add_u32 s24, s24, 0x100080
	s_addc_u32 s25, s25, 0
	s_add_i32 s26, s66, s3
	global_load_lds_dwordx4 v130, s[98:99]
	s_mov_b32 m0, s26
	s_nop 0
	global_load_lds_dwordx4 v134, s[24:25]
	s_add_i32 m0, s26, 0x2000
	s_nop 0
	global_load_lds_dwordx4 v130, s[24:25]
	s_mov_b32 m0, s35
	s_nop 0
	global_load_lds_dwordx4 v136, s[100:101]
	s_mov_b32 m0, s36
	s_nop 0
	global_load_lds_dwordx4 v132, s[100:101]
	s_waitcnt vmcnt(8)
	s_waitcnt lgkmcnt(0)
	s_barrier
	s_setprio 1
	s_waitcnt lgkmcnt(0)
	v_mfma_f32_16x16x32_bf16 v[62:65], v[152:155], v[188:191], v[62:65]
	v_mfma_f32_16x16x32_bf16 v[62:65], v[156:159], v[192:195], v[62:65]
	v_mfma_f32_16x16x32_bf16 v[58:61], v[168:171], v[192:195], v[58:61]
	v_mfma_f32_16x16x32_bf16 v[58:61], v[160:163], v[188:191], v[58:61]
	v_mfma_f32_16x16x32_bf16 v[50:53], v[160:163], v[196:199], v[50:53]
	v_mfma_f32_16x16x32_bf16 v[50:53], v[168:171], v[200:203], v[50:53]
	v_mfma_f32_16x16x32_bf16 v[54:57], v[156:159], v[200:203], v[54:57]
	v_mfma_f32_16x16x32_bf16 v[54:57], v[152:155], v[196:199], v[54:57]
	v_mfma_f32_16x16x32_bf16 v[38:41], v[152:155], v[204:207], v[38:41]
	v_mfma_f32_16x16x32_bf16 v[38:41], v[156:159], v[208:211], v[38:41]
	v_mfma_f32_16x16x32_bf16 v[34:37], v[168:171], v[208:211], v[34:37]
	v_mfma_f32_16x16x32_bf16 v[34:37], v[160:163], v[204:207], v[34:37]
	v_mfma_f32_16x16x32_bf16 v[18:21], v[160:163], v[212:215], v[18:21]
	v_mfma_f32_16x16x32_bf16 v[18:21], v[168:171], v[216:219], v[18:21]
	v_mfma_f32_16x16x32_bf16 v[22:25], v[156:159], v[216:219], v[22:25]
	v_mfma_f32_16x16x32_bf16 v[22:25], v[152:155], v[212:215], v[22:25]
	v_mfma_f32_16x16x32_bf16 v[46:49], v[172:175], v[188:191], v[46:49]
	v_mfma_f32_16x16x32_bf16 v[46:49], v[176:179], v[192:195], v[46:49]
	v_mfma_f32_16x16x32_bf16 v[42:45], v[184:187], v[192:195], v[42:45]
	v_mfma_f32_16x16x32_bf16 v[42:45], v[180:183], v[188:191], v[42:45]
	v_mfma_f32_16x16x32_bf16 v[26:29], v[180:183], v[196:199], v[26:29]
	v_mfma_f32_16x16x32_bf16 v[26:29], v[184:187], v[200:203], v[26:29]
	v_mfma_f32_16x16x32_bf16 v[30:33], v[176:179], v[200:203], v[30:33]
	v_mfma_f32_16x16x32_bf16 v[30:33], v[172:175], v[196:199], v[30:33]
	v_mfma_f32_16x16x32_bf16 v[14:17], v[172:175], v[204:207], v[14:17]
	v_mfma_f32_16x16x32_bf16 v[14:17], v[176:179], v[208:211], v[14:17]
	s_setprio 2
	s_barrier
	v_mfma_f32_16x16x32_bf16 v[10:13], v[184:187], v[208:211], v[10:13]
	v_mfma_f32_16x16x32_bf16 v[10:13], v[180:183], v[204:207], v[10:13]
	v_mfma_f32_16x16x32_bf16 v[2:5], v[180:183], v[212:215], v[2:5]
	v_mfma_f32_16x16x32_bf16 v[2:5], v[184:187], v[216:219], v[2:5]
	v_mfma_f32_16x16x32_bf16 v[6:9], v[176:179], v[216:219], v[6:9]
	v_mfma_f32_16x16x32_bf16 v[6:9], v[172:175], v[212:215], v[6:9]
	s_setprio 0
	s_add_i32 s64, s64, 2
	s_add_u32 s22, s22, 0x100
	s_addc_u32 s23, s23, 0
	s_add_u32 s62, s62, 0x100
	s_addc_u32 s63, s63, 0
.LBB0_79:
	ds_read_b128 v[152:155], v148
	ds_read_b128 v[156:159], v148 offset:1024
	ds_read_b128 v[160:163], v148 offset:2048
	ds_read_b128 v[168:171], v148 offset:3072
	ds_read_b128 v[172:175], v149
	ds_read_b128 v[176:179], v149 offset:1024
	ds_read_b128 v[180:183], v149 offset:2048
	ds_read_b128 v[184:187], v149 offset:3072
	s_add_u32 s24, s22, 0xfff00080
	s_addc_u32 s25, s23, -1
	s_cmp_eq_u32 s64, 60
	s_cselect_b32 s27, s17, s25
	s_cselect_b32 s26, s60, s24
	s_cselect_b32 s25, s15, s63
	s_cselect_b32 s24, s61, s62
	s_add_u32 s98, s24, 0x80
	s_addc_u32 s99, s25, 0
	s_add_u32 s100, s26, 0x80
	s_addc_u32 s101, s27, 0
	s_add_i32 m0, s13, 0xc000
	ds_read_b128 v[188:191], v150
	ds_read_b128 v[192:195], v150 offset:1024
	ds_read_b128 v[196:199], v150 offset:2048
	ds_read_b128 v[200:203], v150 offset:3072
	ds_read_b128 v[204:207], v150 offset:4096
	ds_read_b128 v[208:211], v150 offset:5120
	ds_read_b128 v[212:215], v150 offset:6144
	ds_read_b128 v[216:219], v150 offset:7168
	global_load_lds_dwordx4 v138, s[22:23]
	s_add_i32 m0, s13, 0xe000
	s_nop 0
	global_load_lds_dwordx4 v140, s[22:23]
	s_waitcnt vmcnt(8)
	s_waitcnt lgkmcnt(0)
	s_barrier
; #define PG8_STAGE(bufoff, gbase, voff) do { _Pragma("unroll") for (int _i = 0; _i < 2; ++_i) \
;         __builtin_amdgcn_global_load_lds((const unsigned*)((const char*)(gbase) + (voff)[_i]), (PG8_LAS unsigned*)(lds + (bufoff) + ldsw + _i * 8192), 16, 0, 0); } while (0)
; #define PG8_LDA(dst, b, h) do { _Pragma("unroll") for (int m = 0; m < 4; ++m) _Pragma("unroll") for (int k = 0; k < 2; ++k) dst[m][k] = *(const PG8_LAS bf16x8*)(lds + PG8_SA(b, h) + aoff + m * 2048 + k * 1024); } while (0)
; #define PG8_LDB(dst, b, h) do { _Pragma("unroll") for (int n = 0; n < 2; ++n) _Pragma("unroll") for (int k = 0; k < 2; ++k) dst[n][k] = *(const PG8_LAS bf16x8*)(lds + PG8_SB(b, h) + boff + n * 2048 + k * 1024); } while (0)
; #define PG8_MMA(ai, bj, At, Bt) do { __builtin_amdgcn_s_setprio(1); _Pragma("unroll") for (int m = 0; m < 4; ++m) _Pragma("unroll") for (int n = 0; n < 2; ++n) _Pragma("unroll") for (int k = 0; k < 2; ++k) \
;         acc[ai][bj][m][n] = __builtin_amdgcn_mfma_f32_16x16x32_bf16(Bt[n][k], At[m][k], acc[ai][bj][m][n], 0, 0, 0); __builtin_amdgcn_s_setprio(0); } while (0)
; template <class Epi, class Sched, bool ALIGN_EPI = false, bool SP2 = false>
; __device__ __forceinline__ void gemm_phase(PG8_LAS unsigned char* lds, const Gemm g, const Sched& S, const Epi& E) {
;     ...
;             if constexpr (SP2) {
;             PG8_LDB(B0, 0, 0); PG8_LDB(B1, 0, 1); PG8_SCHED; PG8_LDA(At, 0, 0); PG8_STAGE(PG8_SA(1, 1), a1 + hstepA, voffA);
;             PG8_WAIT_V(8); PG8_WAIT_L(0); PG8_BAR; PG8_MMA(0, 0, At, B0); PG8_MMA(0, 1, At, B1); PG8_BAR; PG8_SCHED;
;             PG8_LDA(At, 0, 1); PG8_STAGE(PG8_SB(0, 0), b2, voffB); PG8_STAGE(PG8_SB(0, 1), b2 + hstepB, voffB); PG8_STAGE(PG8_SA(0, 0), a2, voffA);
;             PG8_WAIT_V(8); PG8_WAIT_L(0); PG8_BAR; PG8_MMA(1, 0, At, B0); PG8_MMA(1, 1, At, B1); PG8_BAR; PG8_SCHED;
;             PG8_LDB(B0, 1, 0); PG8_LDB(B1, 1, 1); PG8_SCHED; PG8_LDA(At, 1, 0); PG8_STAGE(PG8_SA(0, 1), a2 + hstepA, voffA);
;             PG8_WAIT_V(8); PG8_WAIT_L(0); PG8_BAR; PG8_MMA(0, 0, At, B0); PG8_MMA(0, 1, At, B1); PG8_BAR; PG8_SCHED;
;             PG8_LDA(At, 1, 1); PG8_STAGE(PG8_SB(1, 0), b3, voffB); PG8_STAGE(PG8_SB(1, 1), b3 + hstepB, voffB); PG8_STAGE(PG8_SA(1, 0), a3, voffA);
;             PG8_WAIT_V(8); PG8_WAIT_L(0); PG8_BAR; PG8_MMA(1, 0, At, B0); PG8_MMA(1, 1, At, B1); PG8_BAR; PG8_SCHED;
	s_setprio 1
	s_waitcnt lgkmcnt(0)
	v_mfma_f32_16x16x32_bf16 v[126:129], v[152:155], v[188:191], v[126:129]
	v_mfma_f32_16x16x32_bf16 v[126:129], v[156:159], v[192:195], v[126:129]
	v_mfma_f32_16x16x32_bf16 v[122:125], v[168:171], v[192:195], v[122:125]
	v_mfma_f32_16x16x32_bf16 v[122:125], v[160:163], v[188:191], v[122:125]
	v_mfma_f32_16x16x32_bf16 v[114:117], v[160:163], v[196:199], v[114:117]
	v_mfma_f32_16x16x32_bf16 v[114:117], v[168:171], v[200:203], v[114:117]
	v_mfma_f32_16x16x32_bf16 v[118:121], v[156:159], v[200:203], v[118:121]
	v_mfma_f32_16x16x32_bf16 v[118:121], v[152:155], v[196:199], v[118:121]
	v_mfma_f32_16x16x32_bf16 v[102:105], v[152:155], v[204:207], v[102:105]
	v_mfma_f32_16x16x32_bf16 v[102:105], v[156:159], v[208:211], v[102:105]
	v_mfma_f32_16x16x32_bf16 v[98:101], v[168:171], v[208:211], v[98:101]
	v_mfma_f32_16x16x32_bf16 v[98:101], v[160:163], v[204:207], v[98:101]
	v_mfma_f32_16x16x32_bf16 v[82:85], v[160:163], v[212:215], v[82:85]
	v_mfma_f32_16x16x32_bf16 v[82:85], v[168:171], v[216:219], v[82:85]
	v_mfma_f32_16x16x32_bf16 v[86:89], v[156:159], v[216:219], v[86:89]
	v_mfma_f32_16x16x32_bf16 v[86:89], v[152:155], v[212:215], v[86:89]
	v_mfma_f32_16x16x32_bf16 v[110:113], v[172:175], v[188:191], v[110:113]
	v_mfma_f32_16x16x32_bf16 v[110:113], v[176:179], v[192:195], v[110:113]
	v_mfma_f32_16x16x32_bf16 v[106:109], v[184:187], v[192:195], v[106:109]
	v_mfma_f32_16x16x32_bf16 v[106:109], v[180:183], v[188:191], v[106:109]
	v_mfma_f32_16x16x32_bf16 v[90:93], v[180:183], v[196:199], v[90:93]
	v_mfma_f32_16x16x32_bf16 v[90:93], v[184:187], v[200:203], v[90:93]
	v_mfma_f32_16x16x32_bf16 v[94:97], v[176:179], v[200:203], v[94:97]
	v_mfma_f32_16x16x32_bf16 v[94:97], v[172:175], v[196:199], v[94:97]
	v_mfma_f32_16x16x32_bf16 v[78:81], v[172:175], v[204:207], v[78:81]
	v_mfma_f32_16x16x32_bf16 v[78:81], v[176:179], v[208:211], v[78:81]
	s_setprio 2
	s_barrier
	v_mfma_f32_16x16x32_bf16 v[74:77], v[184:187], v[208:211], v[74:77]
	v_mfma_f32_16x16x32_bf16 v[74:77], v[180:183], v[204:207], v[74:77]
	v_mfma_f32_16x16x32_bf16 v[66:69], v[180:183], v[212:215], v[66:69]
	v_mfma_f32_16x16x32_bf16 v[66:69], v[184:187], v[216:219], v[66:69]
	v_mfma_f32_16x16x32_bf16 v[70:73], v[176:179], v[216:219], v[70:73]
	v_mfma_f32_16x16x32_bf16 v[70:73], v[172:175], v[212:215], v[70:73]
	s_setprio 0
	s_add_i32 s65, s38, s3
	s_mov_b32 m0, s65
	ds_read_b128 v[188:191], v150 offset:16384
	ds_read_b128 v[192:195], v150 offset:17408
	ds_read_b128 v[196:199], v150 offset:18432
	ds_read_b128 v[200:203], v150 offset:19456
	ds_read_b128 v[204:207], v150 offset:20480
	ds_read_b128 v[208:211], v150 offset:21504
	ds_read_b128 v[212:215], v150 offset:22528
	ds_read_b128 v[216:219], v150 offset:23552
	global_load_lds_dwordx4 v134, s[24:25]
	s_add_i32 m0, s65, 0x2000
	s_add_u32 s66, s24, 0x100000
	s_addc_u32 s67, s25, 0
	s_add_i32 s65, s39, s3
	global_load_lds_dwordx4 v130, s[24:25]
	s_mov_b32 m0, s65
	s_nop 0
	global_load_lds_dwordx4 v134, s[66:67]
	s_add_i32 m0, s65, 0x2000
	s_nop 0
	global_load_lds_dwordx4 v130, s[66:67]
	s_mov_b32 m0, s13
	s_nop 0
	global_load_lds_dwordx4 v136, s[26:27]
	s_mov_b32 m0, s30
	s_nop 0
	global_load_lds_dwordx4 v132, s[26:27]
	s_waitcnt vmcnt(8)
	s_waitcnt lgkmcnt(0)
	s_barrier
	s_setprio 1
	s_waitcnt lgkmcnt(0)
	v_mfma_f32_16x16x32_bf16 v[62:65], v[152:155], v[188:191], v[62:65]
	v_mfma_f32_16x16x32_bf16 v[62:65], v[156:159], v[192:195], v[62:65]
	v_mfma_f32_16x16x32_bf16 v[58:61], v[168:171], v[192:195], v[58:61]
	v_mfma_f32_16x16x32_bf16 v[58:61], v[160:163], v[188:191], v[58:61]
	v_mfma_f32_16x16x32_bf16 v[50:53], v[160:163], v[196:199], v[50:53]
	v_mfma_f32_16x16x32_bf16 v[50:53], v[168:171], v[200:203], v[50:53]
	v_mfma_f32_16x16x32_bf16 v[54:57], v[156:159], v[200:203], v[54:57]
	v_mfma_f32_16x16x32_bf16 v[54:57], v[152:155], v[196:199], v[54:57]
	v_mfma_f32_16x16x32_bf16 v[38:41], v[152:155], v[204:207], v[38:41]
	v_mfma_f32_16x16x32_bf16 v[38:41], v[156:159], v[208:211], v[38:41]
	v_mfma_f32_16x16x32_bf16 v[34:37], v[168:171], v[208:211], v[34:37]
	v_mfma_f32_16x16x32_bf16 v[34:37], v[160:163], v[204:207], v[34:37]
	v_mfma_f32_16x16x32_bf16 v[18:21], v[160:163], v[212:215], v[18:21]
	v_mfma_f32_16x16x32_bf16 v[18:21], v[168:171], v[216:219], v[18:21]
	v_mfma_f32_16x16x32_bf16 v[22:25], v[156:159], v[216:219], v[22:25]
	v_mfma_f32_16x16x32_bf16 v[22:25], v[152:155], v[212:215], v[22:25]
	v_mfma_f32_16x16x32_bf16 v[46:49], v[172:175], v[188:191], v[46:49]
	v_mfma_f32_16x16x32_bf16 v[46:49], v[176:179], v[192:195], v[46:49]
	v_mfma_f32_16x16x32_bf16 v[42:45], v[184:187], v[192:195], v[42:45]
	v_mfma_f32_16x16x32_bf16 v[42:45], v[180:183], v[188:191], v[42:45]
	v_mfma_f32_16x16x32_bf16 v[26:29], v[180:183], v[196:199], v[26:29]
	v_mfma_f32_16x16x32_bf16 v[26:29], v[184:187], v[200:203], v[26:29]
	v_mfma_f32_16x16x32_bf16 v[30:33], v[176:179], v[200:203], v[30:33]
	v_mfma_f32_16x16x32_bf16 v[30:33], v[172:175], v[196:199], v[30:33]
	v_mfma_f32_16x16x32_bf16 v[14:17], v[172:175], v[204:207], v[14:17]
	v_mfma_f32_16x16x32_bf16 v[14:17], v[176:179], v[208:211], v[14:17]
	s_setprio 2
	s_barrier
; #define PG8_STAGE(bufoff, gbase, voff) do { _Pragma("unroll") for (int _i = 0; _i < 2; ++_i) \
;         __builtin_amdgcn_global_load_lds((const unsigned*)((const char*)(gbase) + (voff)[_i]), (PG8_LAS unsigned*)(lds + (bufoff) + ldsw + _i * 8192), 16, 0, 0); } while (0)
; #define PG8_LDA(dst, b, h) do { _Pragma("unroll") for (int m = 0; m < 4; ++m) _Pragma("unroll") for (int k = 0; k < 2; ++k) dst[m][k] = *(const PG8_LAS bf16x8*)(lds + PG8_SA(b, h) + aoff + m * 2048 + k * 1024); } while (0)
; #define PG8_LDB(dst, b, h) do { _Pragma("unroll") for (int n = 0; n < 2; ++n) _Pragma("unroll") for (int k = 0; k < 2; ++k) dst[n][k] = *(const PG8_LAS bf16x8*)(lds + PG8_SB(b, h) + boff + n * 2048 + k * 1024); } while (0)
; #define PG8_MMA(ai, bj, At, Bt) do { __builtin_amdgcn_s_setprio(1); _Pragma("unroll") for (int m = 0; m < 4; ++m) _Pragma("unroll") for (int n = 0; n < 2; ++n) _Pragma("unroll") for (int k = 0; k < 2; ++k) \
;         acc[ai][bj][m][n] = __builtin_amdgcn_mfma_f32_16x16x32_bf16(Bt[n][k], At[m][k], acc[ai][bj][m][n], 0, 0, 0); __builtin_amdgcn_s_setprio(0); } while (0)
; template <class Epi, class Sched, bool ALIGN_EPI = false, bool SP2 = false>
; __device__ __forceinline__ void gemm_phase(PG8_LAS unsigned char* lds, const Gemm g, const Sched& S, const Epi& E) {
;     ...
;             if constexpr (SP2) {
;             PG8_LDB(B0, 0, 0); PG8_LDB(B1, 0, 1); PG8_SCHED; PG8_LDA(At, 0, 0); PG8_STAGE(PG8_SA(1, 1), a1 + hstepA, voffA);
;             PG8_WAIT_V(8); PG8_WAIT_L(0); PG8_BAR; PG8_MMA(0, 0, At, B0); PG8_MMA(0, 1, At, B1); PG8_BAR; PG8_SCHED;
;             PG8_LDA(At, 0, 1); PG8_STAGE(PG8_SB(0, 0), b2, voffB); PG8_STAGE(PG8_SB(0, 1), b2 + hstepB, voffB); PG8_STAGE(PG8_SA(0, 0), a2, voffA);
;             PG8_WAIT_V(8); PG8_WAIT_L(0); PG8_BAR; PG8_MMA(1, 0, At, B0); PG8_MMA(1, 1, At, B1); PG8_BAR; PG8_SCHED;
;             PG8_LDB(B0, 1, 0); PG8_LDB(B1, 1, 1); PG8_SCHED; PG8_LDA(At, 1, 0); PG8_STAGE(PG8_SA(0, 1), a2 + hstepA, voffA);
;             PG8_WAIT_V(8); PG8_WAIT_L(0); PG8_BAR; PG8_MMA(0, 0, At, B0); PG8_MMA(0, 1, At, B1); PG8_BAR; PG8_SCHED;
;             PG8_LDA(At, 1, 1); PG8_STAGE(PG8_SB(1, 0), b3, voffB); PG8_STAGE(PG8_SB(1, 1), b3 + hstepB, voffB); PG8_STAGE(PG8_SA(1, 0), a3, voffA);
;             PG8_WAIT_V(8); PG8_WAIT_L(0); PG8_BAR; PG8_MMA(1, 0, At, B0); PG8_MMA(1, 1, At, B1); PG8_BAR; PG8_SCHED;
	v_mfma_f32_16x16x32_bf16 v[10:13], v[184:187], v[208:211], v[10:13]
	v_mfma_f32_16x16x32_bf16 v[10:13], v[180:183], v[204:207], v[10:13]
	v_mfma_f32_16x16x32_bf16 v[2:5], v[180:183], v[212:215], v[2:5]
	v_mfma_f32_16x16x32_bf16 v[2:5], v[184:187], v[216:219], v[2:5]
	v_mfma_f32_16x16x32_bf16 v[6:9], v[176:179], v[216:219], v[6:9]
	v_mfma_f32_16x16x32_bf16 v[6:9], v[172:175], v[212:215], v[6:9]
	s_setprio 0
	s_add_i32 s65, 0, 0x18000
	v_add_u32_e32 v151, s65, v146
	s_add_i32 s66, 0, 0x1c000
	ds_read_b128 v[152:155], v151
	ds_read_b128 v[156:159], v151 offset:1024
	ds_read_b128 v[160:163], v151 offset:2048
	ds_read_b128 v[168:171], v151 offset:3072
	v_add_u32_e32 v151, s66, v146
	ds_read_b128 v[172:175], v151
	ds_read_b128 v[176:179], v151 offset:1024
	ds_read_b128 v[180:183], v151 offset:2048
	ds_read_b128 v[184:187], v151 offset:3072
	s_add_u32 s26, s26, 0x100000
	s_addc_u32 s27, s27, 0
	s_mov_b32 m0, s31
	ds_read_b128 v[188:191], v150 offset:32768
	ds_read_b128 v[192:195], v150 offset:33792
	ds_read_b128 v[196:199], v150 offset:34816
	ds_read_b128 v[200:203], v150 offset:35840
	ds_read_b128 v[204:207], v150 offset:36864
	ds_read_b128 v[208:211], v150 offset:37888
	ds_read_b128 v[212:215], v150 offset:38912
	ds_read_b128 v[216:219], v150 offset:39936
	global_load_lds_dwordx4 v136, s[26:27]
	s_mov_b32 m0, s33
	s_nop 0
	global_load_lds_dwordx4 v132, s[26:27]
	s_waitcnt vmcnt(8)
	s_waitcnt lgkmcnt(0)
	s_barrier
	s_setprio 1
	s_waitcnt lgkmcnt(0)
	v_mfma_f32_16x16x32_bf16 v[126:129], v[152:155], v[188:191], v[126:129]
	v_mfma_f32_16x16x32_bf16 v[126:129], v[156:159], v[192:195], v[126:129]
	v_mfma_f32_16x16x32_bf16 v[122:125], v[168:171], v[192:195], v[122:125]
	v_mfma_f32_16x16x32_bf16 v[122:125], v[160:163], v[188:191], v[122:125]
	v_mfma_f32_16x16x32_bf16 v[114:117], v[160:163], v[196:199], v[114:117]
	v_mfma_f32_16x16x32_bf16 v[114:117], v[168:171], v[200:203], v[114:117]
	v_mfma_f32_16x16x32_bf16 v[118:121], v[156:159], v[200:203], v[118:121]
	v_mfma_f32_16x16x32_bf16 v[118:121], v[152:155], v[196:199], v[118:121]
	v_mfma_f32_16x16x32_bf16 v[102:105], v[152:155], v[204:207], v[102:105]
	v_mfma_f32_16x16x32_bf16 v[102:105], v[156:159], v[208:211], v[102:105]
	v_mfma_f32_16x16x32_bf16 v[98:101], v[168:171], v[208:211], v[98:101]
	v_mfma_f32_16x16x32_bf16 v[98:101], v[160:163], v[204:207], v[98:101]
	v_mfma_f32_16x16x32_bf16 v[82:85], v[160:163], v[212:215], v[82:85]
	v_mfma_f32_16x16x32_bf16 v[82:85], v[168:171], v[216:219], v[82:85]
	v_mfma_f32_16x16x32_bf16 v[86:89], v[156:159], v[216:219], v[86:89]
	v_mfma_f32_16x16x32_bf16 v[86:89], v[152:155], v[212:215], v[86:89]
	v_mfma_f32_16x16x32_bf16 v[110:113], v[172:175], v[188:191], v[110:113]
	v_mfma_f32_16x16x32_bf16 v[110:113], v[176:179], v[192:195], v[110:113]
	v_mfma_f32_16x16x32_bf16 v[106:109], v[184:187], v[192:195], v[106:109]
	v_mfma_f32_16x16x32_bf16 v[106:109], v[180:183], v[188:191], v[106:109]
	v_mfma_f32_16x16x32_bf16 v[90:93], v[180:183], v[196:199], v[90:93]
	v_mfma_f32_16x16x32_bf16 v[90:93], v[184:187], v[200:203], v[90:93]
	v_mfma_f32_16x16x32_bf16 v[94:97], v[176:179], v[200:203], v[94:97]
	v_mfma_f32_16x16x32_bf16 v[94:97], v[172:175], v[196:199], v[94:97]
	v_mfma_f32_16x16x32_bf16 v[78:81], v[172:175], v[204:207], v[78:81]
	v_mfma_f32_16x16x32_bf16 v[78:81], v[176:179], v[208:211], v[78:81]
	s_setprio 2
	s_barrier
; #define PG8_STAGE(bufoff, gbase, voff) do { _Pragma("unroll") for (int _i = 0; _i < 2; ++_i) \
;         __builtin_amdgcn_global_load_lds((const unsigned*)((const char*)(gbase) + (voff)[_i]), (PG8_LAS unsigned*)(lds + (bufoff) + ldsw + _i * 8192), 16, 0, 0); } while (0)
; #define PG8_LDA(dst, b, h) do { _Pragma("unroll") for (int m = 0; m < 4; ++m) _Pragma("unroll") for (int k = 0; k < 2; ++k) dst[m][k] = *(const PG8_LAS bf16x8*)(lds + PG8_SA(b, h) + aoff + m * 2048 + k * 1024); } while (0)
; #define PG8_LDB(dst, b, h) do { _Pragma("unroll") for (int n = 0; n < 2; ++n) _Pragma("unroll") for (int k = 0; k < 2; ++k) dst[n][k] = *(const PG8_LAS bf16x8*)(lds + PG8_SB(b, h) + boff + n * 2048 + k * 1024); } while (0)
; #define PG8_MMA(ai, bj, At, Bt) do { __builtin_amdgcn_s_setprio(1); _Pragma("unroll") for (int m = 0; m < 4; ++m) _Pragma("unroll") for (int n = 0; n < 2; ++n) _Pragma("unroll") for (int k = 0; k < 2; ++k) \
;         acc[ai][bj][m][n] = __builtin_amdgcn_mfma_f32_16x16x32_bf16(Bt[n][k], At[m][k], acc[ai][bj][m][n], 0, 0, 0); __builtin_amdgcn_s_setprio(0); } while (0)
; template <class Epi, class Sched, bool ALIGN_EPI = false, bool SP2 = false>
; __device__ __forceinline__ void gemm_phase(PG8_LAS unsigned char* lds, const Gemm g, const Sched& S, const Epi& E) {
;     ...
;             if constexpr (SP2) {
;             PG8_LDB(B0, 0, 0); PG8_LDB(B1, 0, 1); PG8_SCHED; PG8_LDA(At, 0, 0); PG8_STAGE(PG8_SA(1, 1), a1 + hstepA, voffA);
;             PG8_WAIT_V(8); PG8_WAIT_L(0); PG8_BAR; PG8_MMA(0, 0, At, B0); PG8_MMA(0, 1, At, B1); PG8_BAR; PG8_SCHED;
;             PG8_LDA(At, 0, 1); PG8_STAGE(PG8_SB(0, 0), b2, voffB); PG8_STAGE(PG8_SB(0, 1), b2 + hstepB, voffB); PG8_STAGE(PG8_SA(0, 0), a2, voffA);
;             PG8_WAIT_V(8); PG8_WAIT_L(0); PG8_BAR; PG8_MMA(1, 0, At, B0); PG8_MMA(1, 1, At, B1); PG8_BAR; PG8_SCHED;
;             PG8_LDB(B0, 1, 0); PG8_LDB(B1, 1, 1); PG8_SCHED; PG8_LDA(At, 1, 0); PG8_STAGE(PG8_SA(0, 1), a2 + hstepA, voffA);
;             PG8_WAIT_V(8); PG8_WAIT_L(0); PG8_BAR; PG8_MMA(0, 0, At, B0); PG8_MMA(0, 1, At, B1); PG8_BAR; PG8_SCHED;
;             PG8_LDA(At, 1, 1); PG8_STAGE(PG8_SB(1, 0), b3, voffB); PG8_STAGE(PG8_SB(1, 1), b3 + hstepB, voffB); PG8_STAGE(PG8_SA(1, 0), a3, voffA);
;             PG8_WAIT_V(8); PG8_WAIT_L(0); PG8_BAR; PG8_MMA(1, 0, At, B0); PG8_MMA(1, 1, At, B1); PG8_BAR; PG8_SCHED;
	v_mfma_f32_16x16x32_bf16 v[74:77], v[184:187], v[208:211], v[74:77]
	v_mfma_f32_16x16x32_bf16 v[74:77], v[180:183], v[204:207], v[74:77]
	v_mfma_f32_16x16x32_bf16 v[66:69], v[180:183], v[212:215], v[66:69]
	v_mfma_f32_16x16x32_bf16 v[66:69], v[184:187], v[216:219], v[66:69]
	v_mfma_f32_16x16x32_bf16 v[70:73], v[176:179], v[216:219], v[70:73]
	v_mfma_f32_16x16x32_bf16 v[70:73], v[172:175], v[212:215], v[70:73]
	s_setprio 0
	s_add_i32 s26, s65, s3
	s_mov_b32 m0, s26
	ds_read_b128 v[188:191], v150 offset:49152
	ds_read_b128 v[192:195], v150 offset:50176
	ds_read_b128 v[196:199], v150 offset:51200
	ds_read_b128 v[200:203], v150 offset:52224
	ds_read_b128 v[204:207], v150 offset:53248
	ds_read_b128 v[208:211], v150 offset:54272
	ds_read_b128 v[212:215], v150 offset:55296
	ds_read_b128 v[216:219], v150 offset:56320
	global_load_lds_dwordx4 v134, s[98:99]
	s_add_i32 m0, s26, 0x2000
	s_add_u32 s24, s24, 0x100080
	s_addc_u32 s25, s25, 0
	s_add_i32 s26, s66, s3
	global_load_lds_dwordx4 v130, s[98:99]
	s_mov_b32 m0, s26
	s_nop 0
	global_load_lds_dwordx4 v134, s[24:25]
	s_add_i32 m0, s26, 0x2000
	s_nop 0
	global_load_lds_dwordx4 v130, s[24:25]
	s_mov_b32 m0, s35
	s_nop 0
	global_load_lds_dwordx4 v136, s[100:101]
	s_mov_b32 m0, s36
	s_nop 0
	global_load_lds_dwordx4 v132, s[100:101]
	s_waitcnt vmcnt(8)
	s_waitcnt lgkmcnt(0)
	s_barrier
	s_setprio 1
	s_waitcnt lgkmcnt(0)
	v_mfma_f32_16x16x32_bf16 v[62:65], v[152:155], v[188:191], v[62:65]
	v_mfma_f32_16x16x32_bf16 v[62:65], v[156:159], v[192:195], v[62:65]
	v_mfma_f32_16x16x32_bf16 v[58:61], v[168:171], v[192:195], v[58:61]
	v_mfma_f32_16x16x32_bf16 v[58:61], v[160:163], v[188:191], v[58:61]
	v_mfma_f32_16x16x32_bf16 v[50:53], v[160:163], v[196:199], v[50:53]
	v_mfma_f32_16x16x32_bf16 v[50:53], v[168:171], v[200:203], v[50:53]
	v_mfma_f32_16x16x32_bf16 v[54:57], v[156:159], v[200:203], v[54:57]
	v_mfma_f32_16x16x32_bf16 v[54:57], v[152:155], v[196:199], v[54:57]
	v_mfma_f32_16x16x32_bf16 v[38:41], v[152:155], v[204:207], v[38:41]
	v_mfma_f32_16x16x32_bf16 v[38:41], v[156:159], v[208:211], v[38:41]
	v_mfma_f32_16x16x32_bf16 v[34:37], v[168:171], v[208:211], v[34:37]
	v_mfma_f32_16x16x32_bf16 v[34:37], v[160:163], v[204:207], v[34:37]
	v_mfma_f32_16x16x32_bf16 v[18:21], v[160:163], v[212:215], v[18:21]
	v_mfma_f32_16x16x32_bf16 v[18:21], v[168:171], v[216:219], v[18:21]
	v_mfma_f32_16x16x32_bf16 v[22:25], v[156:159], v[216:219], v[22:25]
	v_mfma_f32_16x16x32_bf16 v[22:25], v[152:155], v[212:215], v[22:25]
	v_mfma_f32_16x16x32_bf16 v[46:49], v[172:175], v[188:191], v[46:49]
	v_mfma_f32_16x16x32_bf16 v[46:49], v[176:179], v[192:195], v[46:49]
	v_mfma_f32_16x16x32_bf16 v[42:45], v[184:187], v[192:195], v[42:45]
	v_mfma_f32_16x16x32_bf16 v[42:45], v[180:183], v[188:191], v[42:45]
	v_mfma_f32_16x16x32_bf16 v[26:29], v[180:183], v[196:199], v[26:29]
	v_mfma_f32_16x16x32_bf16 v[26:29], v[184:187], v[200:203], v[26:29]
	v_mfma_f32_16x16x32_bf16 v[30:33], v[176:179], v[200:203], v[30:33]
	v_mfma_f32_16x16x32_bf16 v[30:33], v[172:175], v[196:199], v[30:33]
	v_mfma_f32_16x16x32_bf16 v[14:17], v[172:175], v[204:207], v[14:17]
	v_mfma_f32_16x16x32_bf16 v[14:17], v[176:179], v[208:211], v[14:17]
	s_setprio 2
	s_barrier
	v_mfma_f32_16x16x32_bf16 v[10:13], v[184:187], v[208:211], v[10:13]
	v_mfma_f32_16x16x32_bf16 v[10:13], v[180:183], v[204:207], v[10:13]
	v_mfma_f32_16x16x32_bf16 v[2:5], v[180:183], v[212:215], v[2:5]
	v_mfma_f32_16x16x32_bf16 v[2:5], v[184:187], v[216:219], v[2:5]
	v_mfma_f32_16x16x32_bf16 v[6:9], v[176:179], v[216:219], v[6:9]
	v_mfma_f32_16x16x32_bf16 v[6:9], v[172:175], v[212:215], v[6:9]
	s_setprio 0
	s_add_i32 s64, s64, 2
	s_add_u32 s22, s22, 0x100
	s_addc_u32 s23, s23, 0
	s_add_u32 s62, s62, 0x100
	s_addc_u32 s63, s63, 0
	s_cmp_gt_u32 s64, 61
	s_cbranch_scc0 .LBB0_79
	s_and_b64 vcc, exec, s[10:11]
	s_cbranch_vccz .LBB0_82

; #define PG8_STAGE(bufoff, gbase, voff) do { _Pragma("unroll") for (int _i = 0; _i < 2; ++_i) \
;         __builtin_amdgcn_global_load_lds((const unsigned*)((const char*)(gbase) + (voff)[_i]), (PG8_LAS unsigned*)(lds + (bufoff) + ldsw + _i * 8192), 16, 0, 0); } while (0)
; #define PG8_LDA(dst, b, h) do { _Pragma("unroll") for (int m = 0; m < 4; ++m) _Pragma("unroll") for (int k = 0; k < 2; ++k) dst[m][k] = *(const PG8_LAS bf16x8*)(lds + PG8_SA(b, h) + aoff + m * 2048 + k * 1024); } while (0)
; #define PG8_BAR __builtin_amdgcn_s_barrier()
; template <class Epi, class Sched, bool ALIGN_EPI = false, bool SP2 = false>
; __device__ __forceinline__ void gemm_phase(PG8_LAS unsigned char* lds, const Gemm g, const Sched& S, const Epi& E) {
;     ...
;         for (int t = 0; t < nt; t += 2) {
;             const bool last = (t == nt - 2);
;             const char* a1 = cA + (size_t)(t + 1) * kstep + (t >= g.kj_t ? g.kj_bytes : 0);
;             const char* a2 = last ? nA : cA + (size_t)(t + 2) * kstep + (t + 2 >= g.kj_t ? g.kj_bytes : 0); const char* b2 = last ? nB : cB + (size_t)(t + 2) * kstep;
;             const char* a3 = a2 + kstep; const char* b3 = b2 + kstep;
;             if (last && has_next) S.a_ready(nxt);
;             if constexpr (Epi::MIDK) { if (t == g.kj_t) E.midk(acc, cur, wr, fr); }
;             if constexpr (SP2) {
;             PG8_LDB(B0, 0, 0); PG8_LDB(B1, 0, 1); PG8_SCHED; PG8_LDA(At, 0, 0); PG8_STAGE(PG8_SA(1, 1), a1 + hstepA, voffA);
;             PG8_WAIT_V(8); PG8_WAIT_L(0); PG8_BAR; PG8_MMA(0, 0, At, B0); PG8_MMA(0, 1, At, B1); PG8_BAR; PG8_SCHED;
;             PG8_LDA(At, 0, 1); PG8_STAGE(PG8_SB(0, 0), b2, voffB); PG8_STAGE(PG8_SB(0, 1), b2 + hstepB, voffB); PG8_STAGE(PG8_SA(0, 0), a2, voffA);
;             PG8_WAIT_V(8); PG8_WAIT_L(0); PG8_BAR; PG8_MMA(1, 0, At, B0); PG8_MMA(1, 1, At, B1); PG8_BAR; PG8_SCHED;
;             PG8_LDB(B0, 1, 0); PG8_LDB(B1, 1, 1); PG8_SCHED; PG8_LDA(At, 1, 0); PG8_STAGE(PG8_SA(0, 1), a2 + hstepA, voffA);
;             PG8_WAIT_V(8); PG8_WAIT_L(0); PG8_BAR; PG8_MMA(0, 0, At, B0); PG8_MMA(0, 1, At, B1); PG8_BAR; PG8_SCHED;
;             PG8_LDA(At, 1, 1); PG8_STAGE(PG8_SB(1, 0), b3, voffB); PG8_STAGE(PG8_SB(1, 1), b3 + hstepB, voffB); PG8_STAGE(PG8_SA(1, 0), a3, voffA);
;             PG8_WAIT_V(8); PG8_WAIT_L(0); PG8_BAR; PG8_MMA(1, 0, At, B0); PG8_MMA(1, 1, At, B1); PG8_BAR; PG8_SCHED;
.LBB0_436:
	s_cmp_lt_u32 s65, 64
	s_cselect_b32 s67, 0, 0x4000
	s_add_i32 s66, s65, 2
	s_cmp_lt_u32 s65, 62
	s_cselect_b32 s30, 0, 0x4000
	s_add_u32 s30, s30, s4
	v_add_u32_e32 v3, s53, v167
	s_addc_u32 s31, 0, s5
	ds_read_b128 v[140:143], v3
	ds_read_b128 v[144:147], v3 offset:1024
	ds_read_b128 v[148:151], v3 offset:2048
	ds_read_b128 v[152:155], v3 offset:3072
	v_add_u32_e32 v3, s60, v167
	s_add_u32 s30, s28, s30
	ds_read_b128 v[156:159], v3
	ds_read_b128 v[160:163], v3 offset:1024
	ds_read_b128 v[186:189], v3 offset:2048
	ds_read_b128 v[196:199], v3 offset:3072
	s_addc_u32 s31, s29, s31
	s_add_u32 s30, s30, 0x100
	s_addc_u32 s31, s31, 0
	s_add_u32 s68, s63, s4
	s_addc_u32 s69, s64, s5
	s_cmpk_eq_i32 s4, 0x3f00
	s_cselect_b32 s35, s23, s31
	s_cselect_b32 s34, s22, s30
	s_cselect_b32 s31, s21, s69
	s_cselect_b32 s30, s62, s68
	s_add_u32 s98, s30, 0x80
	s_addc_u32 s99, s31, 0
	s_add_u32 s100, s34, 0x80
	s_addc_u32 s101, s35, 0
	s_add_u32 s68, s67, s4
	s_addc_u32 s69, 0, s5
	s_add_u32 s68, s68, s28
	s_addc_u32 s69, s69, s29
	s_add_i32 m0, s27, 0xc000
	ds_read_b128 v[200:203], v194
	ds_read_b128 v[204:207], v194 offset:1024
	ds_read_b128 v[208:211], v194 offset:2048
	ds_read_b128 v[212:215], v194 offset:3072
	ds_read_b128 v[216:219], v194 offset:4096
	ds_read_b128 v[220:223], v194 offset:5120
	ds_read_b128 v[224:227], v194 offset:6144
	ds_read_b128 v[228:231], v194 offset:7168
	global_load_lds_dwordx4 v178, s[68:69]
	s_add_i32 m0, s27, 0xe000
	s_nop 0
	global_load_lds_dwordx4 v176, s[68:69]
	s_waitcnt vmcnt(8)
	s_waitcnt lgkmcnt(0)
	s_barrier
	s_setprio 1
	s_waitcnt lgkmcnt(0)
	v_mfma_f32_16x16x32_bf16 v[130:133], v[140:143], v[200:203], v[130:133]
	v_mfma_f32_16x16x32_bf16 v[130:133], v[144:147], v[204:207], v[130:133]
	v_mfma_f32_16x16x32_bf16 v[126:129], v[152:155], v[204:207], v[126:129]
	v_mfma_f32_16x16x32_bf16 v[126:129], v[148:151], v[200:203], v[126:129]
	v_mfma_f32_16x16x32_bf16 v[110:113], v[148:151], v[208:211], v[110:113]
	v_mfma_f32_16x16x32_bf16 v[110:113], v[152:155], v[212:215], v[110:113]
	v_mfma_f32_16x16x32_bf16 v[114:117], v[144:147], v[212:215], v[114:117]
	v_mfma_f32_16x16x32_bf16 v[114:117], v[140:143], v[208:211], v[114:117]
	v_mfma_f32_16x16x32_bf16 v[98:101], v[140:143], v[216:219], v[98:101]
	v_mfma_f32_16x16x32_bf16 v[98:101], v[144:147], v[220:223], v[98:101]
	v_mfma_f32_16x16x32_bf16 v[94:97], v[152:155], v[220:223], v[94:97]
	v_mfma_f32_16x16x32_bf16 v[94:97], v[148:151], v[216:219], v[94:97]
	v_mfma_f32_16x16x32_bf16 v[78:81], v[148:151], v[224:227], v[78:81]
	v_mfma_f32_16x16x32_bf16 v[78:81], v[152:155], v[228:231], v[78:81]
	v_mfma_f32_16x16x32_bf16 v[82:85], v[144:147], v[228:231], v[82:85]
	v_mfma_f32_16x16x32_bf16 v[82:85], v[140:143], v[224:227], v[82:85]
	v_mfma_f32_16x16x32_bf16 v[122:125], v[156:159], v[200:203], v[122:125]
	v_mfma_f32_16x16x32_bf16 v[122:125], v[160:163], v[204:207], v[122:125]
	v_mfma_f32_16x16x32_bf16 v[118:121], v[196:199], v[204:207], v[118:121]
	v_mfma_f32_16x16x32_bf16 v[118:121], v[186:189], v[200:203], v[118:121]
	v_mfma_f32_16x16x32_bf16 v[102:105], v[186:189], v[208:211], v[102:105]
	v_mfma_f32_16x16x32_bf16 v[102:105], v[196:199], v[212:215], v[102:105]
	v_mfma_f32_16x16x32_bf16 v[106:109], v[160:163], v[212:215], v[106:109]
	v_mfma_f32_16x16x32_bf16 v[106:109], v[156:159], v[208:211], v[106:109]
	v_mfma_f32_16x16x32_bf16 v[90:93], v[156:159], v[216:219], v[90:93]
	v_mfma_f32_16x16x32_bf16 v[90:93], v[160:163], v[220:223], v[90:93]
	s_setprio 2
	s_barrier
	v_mfma_f32_16x16x32_bf16 v[86:89], v[196:199], v[220:223], v[86:89]
	v_mfma_f32_16x16x32_bf16 v[86:89], v[186:189], v[216:219], v[86:89]
	v_mfma_f32_16x16x32_bf16 v[70:73], v[186:189], v[224:227], v[70:73]
	v_mfma_f32_16x16x32_bf16 v[70:73], v[196:199], v[228:231], v[70:73]
	v_mfma_f32_16x16x32_bf16 v[74:77], v[160:163], v[228:231], v[74:77]
	v_mfma_f32_16x16x32_bf16 v[74:77], v[156:159], v[224:227], v[74:77]
	s_setprio 0
	s_add_i32 s67, s53, s36
	s_mov_b32 m0, s67
	ds_read_b128 v[200:203], v194 offset:16384
	ds_read_b128 v[204:207], v194 offset:17408
	ds_read_b128 v[208:211], v194 offset:18432
	ds_read_b128 v[212:215], v194 offset:19456
	ds_read_b128 v[216:219], v194 offset:20480
	ds_read_b128 v[220:223], v194 offset:21504
	ds_read_b128 v[224:227], v194 offset:22528
	ds_read_b128 v[228:231], v194 offset:23552
	global_load_lds_dwordx4 v170, s[30:31]
	s_add_i32 m0, s67, 0x2000
	s_add_u32 s68, s30, 0x200000
	s_addc_u32 s69, s31, 0
	s_add_i32 s67, s60, s36
	global_load_lds_dwordx4 v174, s[30:31]
	s_mov_b32 m0, s67
	s_nop 0
	global_load_lds_dwordx4 v170, s[68:69]
	s_add_i32 m0, s67, 0x2000
	s_nop 0
	global_load_lds_dwordx4 v174, s[68:69]
	s_mov_b32 m0, s27
	s_nop 0
	global_load_lds_dwordx4 v168, s[34:35]
	s_mov_b32 m0, s37
	s_nop 0
	global_load_lds_dwordx4 v172, s[34:35]
	s_waitcnt vmcnt(8)
	s_waitcnt lgkmcnt(0)
	s_barrier
; #define PG8_STAGE(bufoff, gbase, voff) do { _Pragma("unroll") for (int _i = 0; _i < 2; ++_i) \
;         __builtin_amdgcn_global_load_lds((const unsigned*)((const char*)(gbase) + (voff)[_i]), (PG8_LAS unsigned*)(lds + (bufoff) + ldsw + _i * 8192), 16, 0, 0); } while (0)
; #define PG8_LDA(dst, b, h) do { _Pragma("unroll") for (int m = 0; m < 4; ++m) _Pragma("unroll") for (int k = 0; k < 2; ++k) dst[m][k] = *(const PG8_LAS bf16x8*)(lds + PG8_SA(b, h) + aoff + m * 2048 + k * 1024); } while (0)
; #define PG8_LDB(dst, b, h) do { _Pragma("unroll") for (int n = 0; n < 2; ++n) _Pragma("unroll") for (int k = 0; k < 2; ++k) dst[n][k] = *(const PG8_LAS bf16x8*)(lds + PG8_SB(b, h) + boff + n * 2048 + k * 1024); } while (0)
; #define PG8_MMA(ai, bj, At, Bt) do { __builtin_amdgcn_s_setprio(1); _Pragma("unroll") for (int m = 0; m < 4; ++m) _Pragma("unroll") for (int n = 0; n < 2; ++n) _Pragma("unroll") for (int k = 0; k < 2; ++k) \
;         acc[ai][bj][m][n] = __builtin_amdgcn_mfma_f32_16x16x32_bf16(Bt[n][k], At[m][k], acc[ai][bj][m][n], 0, 0, 0); __builtin_amdgcn_s_setprio(0); } while (0)
; template <class Epi, class Sched, bool ALIGN_EPI = false, bool SP2 = false>
; __device__ __forceinline__ void gemm_phase(PG8_LAS unsigned char* lds, const Gemm g, const Sched& S, const Epi& E) {
;     ...
;             if constexpr (SP2) {
;             PG8_LDB(B0, 0, 0); PG8_LDB(B1, 0, 1); PG8_SCHED; PG8_LDA(At, 0, 0); PG8_STAGE(PG8_SA(1, 1), a1 + hstepA, voffA);
;             PG8_WAIT_V(8); PG8_WAIT_L(0); PG8_BAR; PG8_MMA(0, 0, At, B0); PG8_MMA(0, 1, At, B1); PG8_BAR; PG8_SCHED;
;             PG8_LDA(At, 0, 1); PG8_STAGE(PG8_SB(0, 0), b2, voffB); PG8_STAGE(PG8_SB(0, 1), b2 + hstepB, voffB); PG8_STAGE(PG8_SA(0, 0), a2, voffA);
;             PG8_WAIT_V(8); PG8_WAIT_L(0); PG8_BAR; PG8_MMA(1, 0, At, B0); PG8_MMA(1, 1, At, B1); PG8_BAR; PG8_SCHED;
;             PG8_LDB(B0, 1, 0); PG8_LDB(B1, 1, 1); PG8_SCHED; PG8_LDA(At, 1, 0); PG8_STAGE(PG8_SA(0, 1), a2 + hstepA, voffA);
;             PG8_WAIT_V(8); PG8_WAIT_L(0); PG8_BAR; PG8_MMA(0, 0, At, B0); PG8_MMA(0, 1, At, B1); PG8_BAR; PG8_SCHED;
;             PG8_LDA(At, 1, 1); PG8_STAGE(PG8_SB(1, 0), b3, voffB); PG8_STAGE(PG8_SB(1, 1), b3 + hstepB, voffB); PG8_STAGE(PG8_SA(1, 0), a3, voffA);
;             PG8_WAIT_V(8); PG8_WAIT_L(0); PG8_BAR; PG8_MMA(1, 0, At, B0); PG8_MMA(1, 1, At, B1); PG8_BAR; PG8_SCHED;
	s_setprio 1
	s_waitcnt lgkmcnt(0)
	v_mfma_f32_16x16x32_bf16 v[66:69], v[140:143], v[200:203], v[66:69]
	v_mfma_f32_16x16x32_bf16 v[66:69], v[144:147], v[204:207], v[66:69]
	v_mfma_f32_16x16x32_bf16 v[62:65], v[152:155], v[204:207], v[62:65]
	v_mfma_f32_16x16x32_bf16 v[62:65], v[148:151], v[200:203], v[62:65]
	v_mfma_f32_16x16x32_bf16 v[46:49], v[148:151], v[208:211], v[46:49]
	v_mfma_f32_16x16x32_bf16 v[46:49], v[152:155], v[212:215], v[46:49]
	v_mfma_f32_16x16x32_bf16 v[50:53], v[144:147], v[212:215], v[50:53]
	v_mfma_f32_16x16x32_bf16 v[50:53], v[140:143], v[208:211], v[50:53]
	v_mfma_f32_16x16x32_bf16 v[34:37], v[140:143], v[216:219], v[34:37]
	v_mfma_f32_16x16x32_bf16 v[34:37], v[144:147], v[220:223], v[34:37]
	v_mfma_f32_16x16x32_bf16 v[30:33], v[152:155], v[220:223], v[30:33]
	v_mfma_f32_16x16x32_bf16 v[30:33], v[148:151], v[216:219], v[30:33]
	v_mfma_f32_16x16x32_bf16 v[14:17], v[148:151], v[224:227], v[14:17]
	v_mfma_f32_16x16x32_bf16 v[14:17], v[152:155], v[228:231], v[14:17]
	v_mfma_f32_16x16x32_bf16 v[18:21], v[144:147], v[228:231], v[18:21]
	v_mfma_f32_16x16x32_bf16 v[18:21], v[140:143], v[224:227], v[18:21]
	v_mfma_f32_16x16x32_bf16 v[58:61], v[156:159], v[200:203], v[58:61]
	v_mfma_f32_16x16x32_bf16 v[58:61], v[160:163], v[204:207], v[58:61]
	v_mfma_f32_16x16x32_bf16 v[54:57], v[196:199], v[204:207], v[54:57]
	v_mfma_f32_16x16x32_bf16 v[54:57], v[186:189], v[200:203], v[54:57]
	v_mfma_f32_16x16x32_bf16 v[38:41], v[186:189], v[208:211], v[38:41]
	v_mfma_f32_16x16x32_bf16 v[38:41], v[196:199], v[212:215], v[38:41]
	v_mfma_f32_16x16x32_bf16 v[42:45], v[160:163], v[212:215], v[42:45]
	v_mfma_f32_16x16x32_bf16 v[42:45], v[156:159], v[208:211], v[42:45]
	v_mfma_f32_16x16x32_bf16 v[26:29], v[156:159], v[216:219], v[26:29]
	v_mfma_f32_16x16x32_bf16 v[26:29], v[160:163], v[220:223], v[26:29]
	s_setprio 2
	s_barrier
	v_mfma_f32_16x16x32_bf16 v[22:25], v[196:199], v[220:223], v[22:25]
	v_mfma_f32_16x16x32_bf16 v[22:25], v[186:189], v[216:219], v[22:25]
	v_mfma_f32_16x16x32_bf16 v[4:7], v[186:189], v[224:227], v[6:9]
	v_mfma_f32_16x16x32_bf16 v[4:7], v[196:199], v[228:231], v[4:7]
	v_mfma_f32_16x16x32_bf16 v[10:13], v[160:163], v[228:231], v[10:13]
	v_mfma_f32_16x16x32_bf16 v[10:13], v[156:159], v[224:227], v[10:13]
	s_setprio 0
	s_add_i32 s67, 0, 0x18000
	v_add_u32_e32 v3, s67, v167
	s_add_i32 s68, 0, 0x1c000
	ds_read_b128 v[140:143], v3
	ds_read_b128 v[144:147], v3 offset:1024
	ds_read_b128 v[148:151], v3 offset:2048
	ds_read_b128 v[152:155], v3 offset:3072
	v_add_u32_e32 v3, s68, v167
	ds_read_b128 v[156:159], v3
	ds_read_b128 v[160:163], v3 offset:1024
	ds_read_b128 v[186:189], v3 offset:2048
	ds_read_b128 v[196:199], v3 offset:3072
	s_add_u32 s34, s34, 0x600000
	s_addc_u32 s35, s35, 0
	s_mov_b32 m0, s38
	ds_read_b128 v[200:203], v194 offset:32768
	ds_read_b128 v[204:207], v194 offset:33792
	ds_read_b128 v[208:211], v194 offset:34816
	ds_read_b128 v[212:215], v194 offset:35840
	ds_read_b128 v[216:219], v194 offset:36864
	ds_read_b128 v[220:223], v194 offset:37888
	ds_read_b128 v[224:227], v194 offset:38912
	ds_read_b128 v[228:231], v194 offset:39936
	global_load_lds_dwordx4 v168, s[34:35]
	s_mov_b32 m0, s39
	s_nop 0
	global_load_lds_dwordx4 v172, s[34:35]
	s_waitcnt vmcnt(8)
	s_waitcnt lgkmcnt(0)
	s_barrier
	s_setprio 1
	s_waitcnt lgkmcnt(0)
	v_mfma_f32_16x16x32_bf16 v[130:133], v[140:143], v[200:203], v[130:133]
	v_mfma_f32_16x16x32_bf16 v[130:133], v[144:147], v[204:207], v[130:133]
	v_mfma_f32_16x16x32_bf16 v[126:129], v[152:155], v[204:207], v[126:129]
	v_mfma_f32_16x16x32_bf16 v[126:129], v[148:151], v[200:203], v[126:129]
	v_mfma_f32_16x16x32_bf16 v[110:113], v[148:151], v[208:211], v[110:113]
	v_mfma_f32_16x16x32_bf16 v[110:113], v[152:155], v[212:215], v[110:113]
	v_mfma_f32_16x16x32_bf16 v[114:117], v[144:147], v[212:215], v[114:117]
	v_mfma_f32_16x16x32_bf16 v[114:117], v[140:143], v[208:211], v[114:117]
	v_mfma_f32_16x16x32_bf16 v[98:101], v[140:143], v[216:219], v[98:101]
	v_mfma_f32_16x16x32_bf16 v[98:101], v[144:147], v[220:223], v[98:101]
	v_mfma_f32_16x16x32_bf16 v[94:97], v[152:155], v[220:223], v[94:97]
	v_mfma_f32_16x16x32_bf16 v[94:97], v[148:151], v[216:219], v[94:97]
	v_mfma_f32_16x16x32_bf16 v[78:81], v[148:151], v[224:227], v[78:81]
	v_mfma_f32_16x16x32_bf16 v[78:81], v[152:155], v[228:231], v[78:81]
	v_mfma_f32_16x16x32_bf16 v[82:85], v[144:147], v[228:231], v[82:85]
	v_mfma_f32_16x16x32_bf16 v[82:85], v[140:143], v[224:227], v[82:85]
	v_mfma_f32_16x16x32_bf16 v[122:125], v[156:159], v[200:203], v[122:125]
	v_mfma_f32_16x16x32_bf16 v[122:125], v[160:163], v[204:207], v[122:125]
	v_mfma_f32_16x16x32_bf16 v[118:121], v[196:199], v[204:207], v[118:121]
	v_mfma_f32_16x16x32_bf16 v[118:121], v[186:189], v[200:203], v[118:121]
	v_mfma_f32_16x16x32_bf16 v[102:105], v[186:189], v[208:211], v[102:105]
	v_mfma_f32_16x16x32_bf16 v[102:105], v[196:199], v[212:215], v[102:105]
	v_mfma_f32_16x16x32_bf16 v[106:109], v[160:163], v[212:215], v[106:109]
	v_mfma_f32_16x16x32_bf16 v[106:109], v[156:159], v[208:211], v[106:109]
	v_mfma_f32_16x16x32_bf16 v[90:93], v[156:159], v[216:219], v[90:93]
	v_mfma_f32_16x16x32_bf16 v[90:93], v[160:163], v[220:223], v[90:93]
	s_setprio 2
	s_barrier
; #define PG8_STAGE(bufoff, gbase, voff) do { _Pragma("unroll") for (int _i = 0; _i < 2; ++_i) \
;         __builtin_amdgcn_global_load_lds((const unsigned*)((const char*)(gbase) + (voff)[_i]), (PG8_LAS unsigned*)(lds + (bufoff) + ldsw + _i * 8192), 16, 0, 0); } while (0)
; #define PG8_LDA(dst, b, h) do { _Pragma("unroll") for (int m = 0; m < 4; ++m) _Pragma("unroll") for (int k = 0; k < 2; ++k) dst[m][k] = *(const PG8_LAS bf16x8*)(lds + PG8_SA(b, h) + aoff + m * 2048 + k * 1024); } while (0)
; #define PG8_BAR __builtin_amdgcn_s_barrier()
; template <class Epi, class Sched, bool ALIGN_EPI = false, bool SP2 = false>
; __device__ __forceinline__ void gemm_phase(PG8_LAS unsigned char* lds, const Gemm g, const Sched& S, const Epi& E) {
;     ...
;         for (int t = 0; t < nt; t += 2) {
;             const bool last = (t == nt - 2);
;             const char* a1 = cA + (size_t)(t + 1) * kstep + (t >= g.kj_t ? g.kj_bytes : 0);
;             const char* a2 = last ? nA : cA + (size_t)(t + 2) * kstep + (t + 2 >= g.kj_t ? g.kj_bytes : 0); const char* b2 = last ? nB : cB + (size_t)(t + 2) * kstep;
;             const char* a3 = a2 + kstep; const char* b3 = b2 + kstep;
;             if (last && has_next) S.a_ready(nxt);
;             if constexpr (Epi::MIDK) { if (t == g.kj_t) E.midk(acc, cur, wr, fr); }
;             if constexpr (SP2) {
;             PG8_LDB(B0, 0, 0); PG8_LDB(B1, 0, 1); PG8_SCHED; PG8_LDA(At, 0, 0); PG8_STAGE(PG8_SA(1, 1), a1 + hstepA, voffA);
;             PG8_WAIT_V(8); PG8_WAIT_L(0); PG8_BAR; PG8_MMA(0, 0, At, B0); PG8_MMA(0, 1, At, B1); PG8_BAR; PG8_SCHED;
;             PG8_LDA(At, 0, 1); PG8_STAGE(PG8_SB(0, 0), b2, voffB); PG8_STAGE(PG8_SB(0, 1), b2 + hstepB, voffB); PG8_STAGE(PG8_SA(0, 0), a2, voffA);
;             PG8_WAIT_V(8); PG8_WAIT_L(0); PG8_BAR; PG8_MMA(1, 0, At, B0); PG8_MMA(1, 1, At, B1); PG8_BAR; PG8_SCHED;
;             PG8_LDB(B0, 1, 0); PG8_LDB(B1, 1, 1); PG8_SCHED; PG8_LDA(At, 1, 0); PG8_STAGE(PG8_SA(0, 1), a2 + hstepA, voffA);
;             PG8_WAIT_V(8); PG8_WAIT_L(0); PG8_BAR; PG8_MMA(0, 0, At, B0); PG8_MMA(0, 1, At, B1); PG8_BAR; PG8_SCHED;
;             PG8_LDA(At, 1, 1); PG8_STAGE(PG8_SB(1, 0), b3, voffB); PG8_STAGE(PG8_SB(1, 1), b3 + hstepB, voffB); PG8_STAGE(PG8_SA(1, 0), a3, voffA);
;             PG8_WAIT_V(8); PG8_WAIT_L(0); PG8_BAR; PG8_MMA(1, 0, At, B0); PG8_MMA(1, 1, At, B1); PG8_BAR; PG8_SCHED;
	v_mfma_f32_16x16x32_bf16 v[86:89], v[196:199], v[220:223], v[86:89]
	v_mfma_f32_16x16x32_bf16 v[86:89], v[186:189], v[216:219], v[86:89]
	v_mfma_f32_16x16x32_bf16 v[70:73], v[186:189], v[224:227], v[70:73]
	v_mfma_f32_16x16x32_bf16 v[70:73], v[196:199], v[228:231], v[70:73]
	v_mfma_f32_16x16x32_bf16 v[74:77], v[160:163], v[228:231], v[74:77]
	v_mfma_f32_16x16x32_bf16 v[74:77], v[156:159], v[224:227], v[74:77]
	s_setprio 0
	s_add_i32 s34, s67, s36
	s_mov_b32 m0, s34
	ds_read_b128 v[200:203], v194 offset:49152
	ds_read_b128 v[204:207], v194 offset:50176
	ds_read_b128 v[208:211], v194 offset:51200
	ds_read_b128 v[212:215], v194 offset:52224
	ds_read_b128 v[216:219], v194 offset:53248
	ds_read_b128 v[220:223], v194 offset:54272
	ds_read_b128 v[224:227], v194 offset:55296
	ds_read_b128 v[228:231], v194 offset:56320
	global_load_lds_dwordx4 v170, s[98:99]
	s_add_i32 m0, s34, 0x2000
	s_add_u32 s30, s30, 0x200080
	s_addc_u32 s31, s31, 0
	s_add_i32 s34, s68, s36
	global_load_lds_dwordx4 v174, s[98:99]
	s_mov_b32 m0, s34
	s_nop 0
	global_load_lds_dwordx4 v170, s[30:31]
	s_add_i32 m0, s34, 0x2000
	s_nop 0
	global_load_lds_dwordx4 v174, s[30:31]
	s_mov_b32 m0, s41
	s_nop 0
	global_load_lds_dwordx4 v168, s[100:101]
	s_mov_b32 m0, s50
	s_nop 0
	global_load_lds_dwordx4 v172, s[100:101]
	s_waitcnt vmcnt(8)
	s_waitcnt lgkmcnt(0)
	s_barrier
	s_setprio 1
	s_waitcnt lgkmcnt(0)
	v_mfma_f32_16x16x32_bf16 v[66:69], v[140:143], v[200:203], v[66:69]
	v_mfma_f32_16x16x32_bf16 v[66:69], v[144:147], v[204:207], v[66:69]
	v_mfma_f32_16x16x32_bf16 v[62:65], v[152:155], v[204:207], v[62:65]
	v_mfma_f32_16x16x32_bf16 v[62:65], v[148:151], v[200:203], v[62:65]
	v_mfma_f32_16x16x32_bf16 v[46:49], v[148:151], v[208:211], v[46:49]
	v_mfma_f32_16x16x32_bf16 v[46:49], v[152:155], v[212:215], v[46:49]
	v_mfma_f32_16x16x32_bf16 v[50:53], v[144:147], v[212:215], v[50:53]
	v_mfma_f32_16x16x32_bf16 v[50:53], v[140:143], v[208:211], v[50:53]
	v_mfma_f32_16x16x32_bf16 v[34:37], v[140:143], v[216:219], v[34:37]
	v_mfma_f32_16x16x32_bf16 v[34:37], v[144:147], v[220:223], v[34:37]
	v_mfma_f32_16x16x32_bf16 v[30:33], v[152:155], v[220:223], v[30:33]
	v_mfma_f32_16x16x32_bf16 v[30:33], v[148:151], v[216:219], v[30:33]
	v_mfma_f32_16x16x32_bf16 v[14:17], v[148:151], v[224:227], v[14:17]
	v_mfma_f32_16x16x32_bf16 v[14:17], v[152:155], v[228:231], v[14:17]
	v_mfma_f32_16x16x32_bf16 v[18:21], v[144:147], v[228:231], v[18:21]
	v_mfma_f32_16x16x32_bf16 v[18:21], v[140:143], v[224:227], v[18:21]
	v_mfma_f32_16x16x32_bf16 v[58:61], v[156:159], v[200:203], v[58:61]
	v_mfma_f32_16x16x32_bf16 v[58:61], v[160:163], v[204:207], v[58:61]
	v_mfma_f32_16x16x32_bf16 v[54:57], v[196:199], v[204:207], v[54:57]
	v_mfma_f32_16x16x32_bf16 v[54:57], v[186:189], v[200:203], v[54:57]
	v_mfma_f32_16x16x32_bf16 v[38:41], v[186:189], v[208:211], v[38:41]
	v_mfma_f32_16x16x32_bf16 v[38:41], v[196:199], v[212:215], v[38:41]
	v_mfma_f32_16x16x32_bf16 v[42:45], v[160:163], v[212:215], v[42:45]
	v_mfma_f32_16x16x32_bf16 v[42:45], v[156:159], v[208:211], v[42:45]
	v_mfma_f32_16x16x32_bf16 v[26:29], v[156:159], v[216:219], v[26:29]
	v_mfma_f32_16x16x32_bf16 v[26:29], v[160:163], v[220:223], v[26:29]
	s_setprio 2
	s_barrier
	v_mfma_f32_16x16x32_bf16 v[22:25], v[196:199], v[220:223], v[22:25]
	v_mfma_f32_16x16x32_bf16 v[22:25], v[186:189], v[216:219], v[22:25]
	v_mfma_f32_16x16x32_bf16 v[8:11], v[156:159], v[224:227], v[10:13]
	v_mfma_f32_16x16x32_bf16 v[10:13], v[160:163], v[228:231], v[8:11]
	v_mfma_f32_16x16x32_bf16 v[4:7], v[186:189], v[224:227], v[4:7]
	v_mfma_f32_16x16x32_bf16 v[6:9], v[196:199], v[228:231], v[4:7]
	s_setprio 0
	s_add_u32 s4, s4, 0x100
	s_addc_u32 s5, 0, s5
	s_cmpk_gt_u32 s65, 0x7d
	s_cbranch_scc0 .LBB0_434
	s_and_b64 vcc, exec, s[16:17]
	s_cbranch_vccz .LBB0_439
	s_barrier

; #define PG8_LDA(dst, b, h) do { _Pragma("unroll") for (int m = 0; m < 4; ++m) _Pragma("unroll") for (int k = 0; k < 2; ++k) dst[m][k] = *(const PG8_LAS bf16x8*)(lds + PG8_SA(b, h) + aoff + m * 2048 + k * 1024); } while (0)
;     DI void operator()(const f32x4 (&acc)[2][2][4][2], const Unit& u, int wr, int wc, int fr, int fq) const {
;     ...
;         for (int ai = 0; ai < 2; ++ai)
; #pragma unroll
;             for (int m = 0; m < 4; ++m) rs[ai][m] = ssq ? __builtin_amdgcn_rsqf(ssq[row0 + ai * HALF + m * 16] * (1.0f / 4096.0f) + 1e-6f) : 1.0f;
; template <class Epi, class Sched, bool ALIGN_EPI = false, bool SP2 = false>
; __device__ __forceinline__ void gemm_phase(PG8_LAS unsigned char* lds, const Gemm g, const Sched& S, const Epi& E) {
;     ...
;         for (int t = 0; t < nt; t += 2) {
;             const bool last = (t == nt - 2);
;             const char* a1 = cA + (size_t)(t + 1) * kstep + (t >= g.kj_t ? g.kj_bytes : 0);
;             const char* a2 = last ? nA : cA + (size_t)(t + 2) * kstep + (t + 2 >= g.kj_t ? g.kj_bytes : 0); const char* b2 = last ? nB : cB + (size_t)(t + 2) * kstep;
;             const char* a3 = a2 + kstep; const char* b3 = b2 + kstep;
;             if (last && has_next) S.a_ready(nxt);
;             if constexpr (Epi::MIDK) { if (t == g.kj_t) E.midk(acc, cur, wr, fr); }
;             if constexpr (SP2) {
;             PG8_LDB(B0, 0, 0); PG8_LDB(B1, 0, 1); PG8_SCHED; PG8_LDA(At, 0, 0); PG8_STAGE(PG8_SA(1, 1), a1 + hstepA, voffA);
;             PG8_WAIT_V(8); PG8_WAIT_L(0); PG8_BAR; PG8_MMA(0, 0, At, B0); PG8_MMA(0, 1, At, B1); PG8_BAR; PG8_SCHED;
;             PG8_LDA(At, 0, 1); PG8_STAGE(PG8_SB(0, 0), b2, voffB); PG8_STAGE(PG8_SB(0, 1), b2 + hstepB, voffB); PG8_STAGE(PG8_SA(0, 0), a2, voffA);
;             PG8_WAIT_V(8); PG8_WAIT_L(0); PG8_BAR; PG8_MMA(1, 0, At, B0); PG8_MMA(1, 1, At, B1); PG8_BAR; PG8_SCHED;
;             PG8_LDB(B0, 1, 0); PG8_LDB(B1, 1, 1); PG8_SCHED; PG8_LDA(At, 1, 0); PG8_STAGE(PG8_SA(0, 1), a2 + hstepA, voffA);
;             PG8_WAIT_V(8); PG8_WAIT_L(0); PG8_BAR; PG8_MMA(0, 0, At, B0); PG8_MMA(0, 1, At, B1); PG8_BAR; PG8_SCHED;
;             PG8_LDA(At, 1, 1); PG8_STAGE(PG8_SB(1, 0), b3, voffB); PG8_STAGE(PG8_SB(1, 1), b3 + hstepB, voffB); PG8_STAGE(PG8_SA(1, 0), a3, voffA);
;             PG8_WAIT_V(8); PG8_WAIT_L(0); PG8_BAR; PG8_MMA(1, 0, At, B0); PG8_MMA(1, 1, At, B1); PG8_BAR; PG8_SCHED;
.LBB0_524:
	s_ashr_i32 s15, s14, 31
	s_lshl_b64 s[16:17], s[14:15], 21
	s_add_u32 s16, s42, s16
	s_addc_u32 s17, s43, s17
	s_and_b64 s[18:19], s[0:1], exec
	s_cselect_b32 s15, s17, s23
	s_cselect_b32 s50, s16, s22
	s_ashr_i32 s13, s12, 31
	s_lshl_b64 s[18:19], s[12:13], 21
	v_readlane_b32 s26, v253, 37
	v_readlane_b32 s27, v253, 38
	s_add_u32 s18, s26, s18
	s_addc_u32 s19, s27, s19
	s_and_b64 s[26:27], s[0:1], exec
	s_cselect_b32 s13, s19, s25
	s_cselect_b32 s51, s18, s24
	s_add_u32 s22, s22, 0x100080
	s_addc_u32 s23, s23, 0
	s_add_u32 s52, s24, 0x100
	s_addc_u32 s53, s25, 0
	s_waitcnt lgkmcnt(0)
	s_mov_b32 s60, -2
	v_lshl_add_u32 v244, s20, 8, v157
	v_ashrrev_i32_e32 v245, 31, v244
	v_lshl_add_u64 v[244:245], v[244:245], 2, s[8:9]
	global_load_dword v236, v[244:245], off
	global_load_dword v237, v[244:245], off offset:64
	global_load_dword v238, v[244:245], off offset:128
	global_load_dword v239, v[244:245], off offset:192
	global_load_dword v240, v[244:245], off offset:512
	global_load_dword v241, v[244:245], off offset:576
	global_load_dword v242, v[244:245], off offset:640
	global_load_dword v243, v[244:245], off offset:704
	s_waitcnt vmcnt(0)
	ds_read_b128 v[146:149], v160
	ds_read_b128 v[168:171], v160 offset:1024
	ds_read_b128 v[172:175], v160 offset:2048
	ds_read_b128 v[176:179], v160 offset:3072
	ds_read_b128 v[180:183], v161
	ds_read_b128 v[184:187], v161 offset:1024
	ds_read_b128 v[188:191], v161 offset:2048
	ds_read_b128 v[192:195], v161 offset:3072
	s_add_u32 s24, s22, 0xfff00080
	s_addc_u32 s25, s23, -1
	s_cmp_eq_u32 s60, 60
	s_cselect_b32 s27, s15, s25
	s_cselect_b32 s26, s50, s24
	s_cselect_b32 s25, s13, s53
	s_cselect_b32 s24, s51, s52
	s_add_u32 s98, s24, 0x80
	s_addc_u32 s99, s25, 0
	s_add_u32 s100, s26, 0x80
	s_addc_u32 s101, s27, 0
	s_add_i32 m0, s21, 0xc000
	ds_read_b128 v[196:199], v162
	ds_read_b128 v[200:203], v162 offset:1024
	ds_read_b128 v[204:207], v162 offset:2048
	ds_read_b128 v[208:211], v162 offset:3072
	ds_read_b128 v[212:215], v162 offset:4096
	ds_read_b128 v[216:219], v162 offset:5120
	ds_read_b128 v[220:223], v162 offset:6144
	ds_read_b128 v[224:227], v162 offset:7168
	global_load_lds_dwordx4 v138, s[22:23]
	s_add_i32 m0, s21, 0xe000
	s_nop 0
	global_load_lds_dwordx4 v140, s[22:23]
	s_waitcnt vmcnt(8)
	s_waitcnt lgkmcnt(0)
	s_barrier
	s_setprio 1
	s_waitcnt lgkmcnt(0)
	v_mfma_f32_16x16x32_bf16 v[126:129], v[146:149], v[196:199], 0
	v_mfma_f32_16x16x32_bf16 v[126:129], v[168:171], v[200:203], v[126:129]
	v_mfma_f32_16x16x32_bf16 v[122:125], v[176:179], v[200:203], 0
	v_mfma_f32_16x16x32_bf16 v[122:125], v[172:175], v[196:199], v[122:125]
	v_mfma_f32_16x16x32_bf16 v[114:117], v[172:175], v[204:207], 0
	v_mfma_f32_16x16x32_bf16 v[114:117], v[176:179], v[208:211], v[114:117]
	v_mfma_f32_16x16x32_bf16 v[118:121], v[168:171], v[208:211], 0
	v_mfma_f32_16x16x32_bf16 v[118:121], v[146:149], v[204:207], v[118:121]
	v_mfma_f32_16x16x32_bf16 v[110:113], v[146:149], v[212:215], 0
	v_mfma_f32_16x16x32_bf16 v[110:113], v[168:171], v[216:219], v[110:113]
	v_mfma_f32_16x16x32_bf16 v[98:101], v[176:179], v[216:219], 0
	v_mfma_f32_16x16x32_bf16 v[98:101], v[172:175], v[212:215], v[98:101]
	v_mfma_f32_16x16x32_bf16 v[78:81], v[172:175], v[220:223], 0
	v_mfma_f32_16x16x32_bf16 v[78:81], v[176:179], v[224:227], v[78:81]
	v_mfma_f32_16x16x32_bf16 v[82:85], v[168:171], v[224:227], 0
	v_mfma_f32_16x16x32_bf16 v[82:85], v[146:149], v[220:223], v[82:85]
	v_mfma_f32_16x16x32_bf16 v[106:109], v[180:183], v[196:199], 0
	v_mfma_f32_16x16x32_bf16 v[106:109], v[184:187], v[200:203], v[106:109]
	v_mfma_f32_16x16x32_bf16 v[102:105], v[192:195], v[200:203], 0
	v_mfma_f32_16x16x32_bf16 v[102:105], v[188:191], v[196:199], v[102:105]
	v_mfma_f32_16x16x32_bf16 v[90:93], v[188:191], v[204:207], 0
	v_mfma_f32_16x16x32_bf16 v[90:93], v[192:195], v[208:211], v[90:93]
	v_mfma_f32_16x16x32_bf16 v[94:97], v[184:187], v[208:211], 0
	v_mfma_f32_16x16x32_bf16 v[94:97], v[180:183], v[204:207], v[94:97]
	v_mfma_f32_16x16x32_bf16 v[86:89], v[180:183], v[212:215], 0
	v_mfma_f32_16x16x32_bf16 v[86:89], v[184:187], v[216:219], v[86:89]
	s_setprio 2
	s_barrier
	v_mfma_f32_16x16x32_bf16 v[74:77], v[192:195], v[216:219], 0
	v_mfma_f32_16x16x32_bf16 v[74:77], v[188:191], v[212:215], v[74:77]
	v_mfma_f32_16x16x32_bf16 v[66:69], v[188:191], v[220:223], 0
	v_mfma_f32_16x16x32_bf16 v[66:69], v[192:195], v[224:227], v[66:69]
	v_mfma_f32_16x16x32_bf16 v[70:73], v[184:187], v[224:227], 0
	v_mfma_f32_16x16x32_bf16 v[70:73], v[180:183], v[220:223], v[70:73]
	s_setprio 0
	s_add_i32 s61, s38, s3
	s_mov_b32 m0, s61
	ds_read_b128 v[196:199], v162 offset:16384
	ds_read_b128 v[200:203], v162 offset:17408
	ds_read_b128 v[204:207], v162 offset:18432
	ds_read_b128 v[208:211], v162 offset:19456
	ds_read_b128 v[212:215], v162 offset:20480
	ds_read_b128 v[216:219], v162 offset:21504
	ds_read_b128 v[220:223], v162 offset:22528
	ds_read_b128 v[224:227], v162 offset:23552
	global_load_lds_dwordx4 v136, s[24:25]
	s_add_i32 m0, s61, 0x2000
	s_add_u32 s62, s24, 0x100000
	s_addc_u32 s63, s25, 0
	s_add_i32 s61, s39, s3
	global_load_lds_dwordx4 v134, s[24:25]
	s_mov_b32 m0, s61
	s_nop 0
	global_load_lds_dwordx4 v136, s[62:63]
	s_add_i32 m0, s61, 0x2000
	s_nop 0
	global_load_lds_dwordx4 v134, s[62:63]
	s_mov_b32 m0, s21
	s_nop 0
	global_load_lds_dwordx4 v130, s[26:27]
	s_mov_b32 m0, s30
	s_nop 0
	global_load_lds_dwordx4 v132, s[26:27]
	s_waitcnt vmcnt(8)
	s_waitcnt lgkmcnt(0)
	s_barrier
; #define PG8_STAGE(bufoff, gbase, voff) do { _Pragma("unroll") for (int _i = 0; _i < 2; ++_i) \
;         __builtin_amdgcn_global_load_lds((const unsigned*)((const char*)(gbase) + (voff)[_i]), (PG8_LAS unsigned*)(lds + (bufoff) + ldsw + _i * 8192), 16, 0, 0); } while (0)
; #define PG8_LDA(dst, b, h) do { _Pragma("unroll") for (int m = 0; m < 4; ++m) _Pragma("unroll") for (int k = 0; k < 2; ++k) dst[m][k] = *(const PG8_LAS bf16x8*)(lds + PG8_SA(b, h) + aoff + m * 2048 + k * 1024); } while (0)
; #define PG8_LDB(dst, b, h) do { _Pragma("unroll") for (int n = 0; n < 2; ++n) _Pragma("unroll") for (int k = 0; k < 2; ++k) dst[n][k] = *(const PG8_LAS bf16x8*)(lds + PG8_SB(b, h) + boff + n * 2048 + k * 1024); } while (0)
; #define PG8_MMA(ai, bj, At, Bt) do { __builtin_amdgcn_s_setprio(1); _Pragma("unroll") for (int m = 0; m < 4; ++m) _Pragma("unroll") for (int n = 0; n < 2; ++n) _Pragma("unroll") for (int k = 0; k < 2; ++k) \
;         acc[ai][bj][m][n] = __builtin_amdgcn_mfma_f32_16x16x32_bf16(Bt[n][k], At[m][k], acc[ai][bj][m][n], 0, 0, 0); __builtin_amdgcn_s_setprio(0); } while (0)
; template <class Epi, class Sched, bool ALIGN_EPI = false, bool SP2 = false>
; __device__ __forceinline__ void gemm_phase(PG8_LAS unsigned char* lds, const Gemm g, const Sched& S, const Epi& E) {
;     ...
;             if constexpr (SP2) {
;             PG8_LDB(B0, 0, 0); PG8_LDB(B1, 0, 1); PG8_SCHED; PG8_LDA(At, 0, 0); PG8_STAGE(PG8_SA(1, 1), a1 + hstepA, voffA);
;             PG8_WAIT_V(8); PG8_WAIT_L(0); PG8_BAR; PG8_MMA(0, 0, At, B0); PG8_MMA(0, 1, At, B1); PG8_BAR; PG8_SCHED;
;             PG8_LDA(At, 0, 1); PG8_STAGE(PG8_SB(0, 0), b2, voffB); PG8_STAGE(PG8_SB(0, 1), b2 + hstepB, voffB); PG8_STAGE(PG8_SA(0, 0), a2, voffA);
;             PG8_WAIT_V(8); PG8_WAIT_L(0); PG8_BAR; PG8_MMA(1, 0, At, B0); PG8_MMA(1, 1, At, B1); PG8_BAR; PG8_SCHED;
;             PG8_LDB(B0, 1, 0); PG8_LDB(B1, 1, 1); PG8_SCHED; PG8_LDA(At, 1, 0); PG8_STAGE(PG8_SA(0, 1), a2 + hstepA, voffA);
;             PG8_WAIT_V(8); PG8_WAIT_L(0); PG8_BAR; PG8_MMA(0, 0, At, B0); PG8_MMA(0, 1, At, B1); PG8_BAR; PG8_SCHED;
;             PG8_LDA(At, 1, 1); PG8_STAGE(PG8_SB(1, 0), b3, voffB); PG8_STAGE(PG8_SB(1, 1), b3 + hstepB, voffB); PG8_STAGE(PG8_SA(1, 0), a3, voffA);
;             PG8_WAIT_V(8); PG8_WAIT_L(0); PG8_BAR; PG8_MMA(1, 0, At, B0); PG8_MMA(1, 1, At, B1); PG8_BAR; PG8_SCHED;
	s_setprio 1
	s_waitcnt lgkmcnt(0)
	v_mfma_f32_16x16x32_bf16 v[62:65], v[146:149], v[196:199], 0
	v_mfma_f32_16x16x32_bf16 v[62:65], v[168:171], v[200:203], v[62:65]
	v_mfma_f32_16x16x32_bf16 v[58:61], v[176:179], v[200:203], 0
	v_mfma_f32_16x16x32_bf16 v[58:61], v[172:175], v[196:199], v[58:61]
	v_mfma_f32_16x16x32_bf16 v[46:49], v[172:175], v[204:207], 0
	v_mfma_f32_16x16x32_bf16 v[46:49], v[176:179], v[208:211], v[46:49]
	v_mfma_f32_16x16x32_bf16 v[54:57], v[168:171], v[208:211], 0
	v_mfma_f32_16x16x32_bf16 v[54:57], v[146:149], v[204:207], v[54:57]
	v_mfma_f32_16x16x32_bf16 v[38:41], v[146:149], v[212:215], 0
	v_mfma_f32_16x16x32_bf16 v[38:41], v[168:171], v[216:219], v[38:41]
	v_mfma_f32_16x16x32_bf16 v[30:33], v[176:179], v[216:219], 0
	v_mfma_f32_16x16x32_bf16 v[30:33], v[172:175], v[212:215], v[30:33]
	v_mfma_f32_16x16x32_bf16 v[14:17], v[172:175], v[220:223], 0
	v_mfma_f32_16x16x32_bf16 v[14:17], v[176:179], v[224:227], v[14:17]
	v_mfma_f32_16x16x32_bf16 v[22:25], v[168:171], v[224:227], 0
	v_mfma_f32_16x16x32_bf16 v[22:25], v[146:149], v[220:223], v[22:25]
	v_mfma_f32_16x16x32_bf16 v[50:53], v[180:183], v[196:199], 0
	v_mfma_f32_16x16x32_bf16 v[50:53], v[184:187], v[200:203], v[50:53]
	v_mfma_f32_16x16x32_bf16 v[42:45], v[192:195], v[200:203], 0
	v_mfma_f32_16x16x32_bf16 v[42:45], v[188:191], v[196:199], v[42:45]
	v_mfma_f32_16x16x32_bf16 v[26:29], v[188:191], v[204:207], 0
	v_mfma_f32_16x16x32_bf16 v[26:29], v[192:195], v[208:211], v[26:29]
	v_mfma_f32_16x16x32_bf16 v[34:37], v[184:187], v[208:211], 0
	v_mfma_f32_16x16x32_bf16 v[34:37], v[180:183], v[204:207], v[34:37]
	v_mfma_f32_16x16x32_bf16 v[18:21], v[180:183], v[212:215], 0
	v_mfma_f32_16x16x32_bf16 v[18:21], v[184:187], v[216:219], v[18:21]
	s_setprio 2
	s_barrier
	v_mfma_f32_16x16x32_bf16 v[10:13], v[192:195], v[216:219], 0
	v_mfma_f32_16x16x32_bf16 v[10:13], v[188:191], v[212:215], v[10:13]
	v_mfma_f32_16x16x32_bf16 v[2:5], v[188:191], v[220:223], 0
	v_mfma_f32_16x16x32_bf16 v[2:5], v[192:195], v[224:227], v[2:5]
	v_mfma_f32_16x16x32_bf16 v[6:9], v[184:187], v[224:227], 0
	v_mfma_f32_16x16x32_bf16 v[6:9], v[180:183], v[220:223], v[6:9]
	s_setprio 0
	s_add_i32 s61, 0, 0x18000
	v_add_u32_e32 v150, s61, v158
	s_add_i32 s62, 0, 0x1c000
	ds_read_b128 v[146:149], v150
	ds_read_b128 v[168:171], v150 offset:1024
	ds_read_b128 v[172:175], v150 offset:2048
	ds_read_b128 v[176:179], v150 offset:3072
	v_add_u32_e32 v150, s62, v158
	ds_read_b128 v[180:183], v150
	ds_read_b128 v[184:187], v150 offset:1024
	ds_read_b128 v[188:191], v150 offset:2048
	ds_read_b128 v[192:195], v150 offset:3072
	s_add_u32 s26, s26, 0x100000
	s_addc_u32 s27, s27, 0
	s_mov_b32 m0, s31
	ds_read_b128 v[196:199], v162 offset:32768
	ds_read_b128 v[200:203], v162 offset:33792
	ds_read_b128 v[204:207], v162 offset:34816
	ds_read_b128 v[208:211], v162 offset:35840
	ds_read_b128 v[212:215], v162 offset:36864
	ds_read_b128 v[216:219], v162 offset:37888
	ds_read_b128 v[220:223], v162 offset:38912
	ds_read_b128 v[224:227], v162 offset:39936
	global_load_lds_dwordx4 v130, s[26:27]
	s_mov_b32 m0, s33
	s_nop 0
	global_load_lds_dwordx4 v132, s[26:27]
	s_waitcnt vmcnt(8)
	s_waitcnt lgkmcnt(0)
	s_barrier
	s_setprio 1
	s_waitcnt lgkmcnt(0)
	v_mfma_f32_16x16x32_bf16 v[126:129], v[146:149], v[196:199], v[126:129]
	v_mfma_f32_16x16x32_bf16 v[126:129], v[168:171], v[200:203], v[126:129]
	v_mfma_f32_16x16x32_bf16 v[122:125], v[176:179], v[200:203], v[122:125]
	v_mfma_f32_16x16x32_bf16 v[122:125], v[172:175], v[196:199], v[122:125]
	v_mfma_f32_16x16x32_bf16 v[114:117], v[172:175], v[204:207], v[114:117]
	v_mfma_f32_16x16x32_bf16 v[114:117], v[176:179], v[208:211], v[114:117]
	v_mfma_f32_16x16x32_bf16 v[118:121], v[168:171], v[208:211], v[118:121]
	v_mfma_f32_16x16x32_bf16 v[118:121], v[146:149], v[204:207], v[118:121]
	v_mfma_f32_16x16x32_bf16 v[110:113], v[146:149], v[212:215], v[110:113]
	v_mfma_f32_16x16x32_bf16 v[110:113], v[168:171], v[216:219], v[110:113]
	v_mfma_f32_16x16x32_bf16 v[98:101], v[176:179], v[216:219], v[98:101]
	v_mfma_f32_16x16x32_bf16 v[98:101], v[172:175], v[212:215], v[98:101]
	v_mfma_f32_16x16x32_bf16 v[78:81], v[172:175], v[220:223], v[78:81]
	v_mfma_f32_16x16x32_bf16 v[78:81], v[176:179], v[224:227], v[78:81]
	v_mfma_f32_16x16x32_bf16 v[82:85], v[168:171], v[224:227], v[82:85]
	v_mfma_f32_16x16x32_bf16 v[82:85], v[146:149], v[220:223], v[82:85]
	v_mfma_f32_16x16x32_bf16 v[106:109], v[180:183], v[196:199], v[106:109]
	v_mfma_f32_16x16x32_bf16 v[106:109], v[184:187], v[200:203], v[106:109]
	v_mfma_f32_16x16x32_bf16 v[102:105], v[192:195], v[200:203], v[102:105]
	v_mfma_f32_16x16x32_bf16 v[102:105], v[188:191], v[196:199], v[102:105]
	v_mfma_f32_16x16x32_bf16 v[90:93], v[188:191], v[204:207], v[90:93]
	v_mfma_f32_16x16x32_bf16 v[90:93], v[192:195], v[208:211], v[90:93]
	v_mfma_f32_16x16x32_bf16 v[94:97], v[184:187], v[208:211], v[94:97]
	v_mfma_f32_16x16x32_bf16 v[94:97], v[180:183], v[204:207], v[94:97]
	v_mfma_f32_16x16x32_bf16 v[86:89], v[180:183], v[212:215], v[86:89]
	v_mfma_f32_16x16x32_bf16 v[86:89], v[184:187], v[216:219], v[86:89]
	s_setprio 2
	s_barrier
; #define PG8_STAGE(bufoff, gbase, voff) do { _Pragma("unroll") for (int _i = 0; _i < 2; ++_i) \
;         __builtin_amdgcn_global_load_lds((const unsigned*)((const char*)(gbase) + (voff)[_i]), (PG8_LAS unsigned*)(lds + (bufoff) + ldsw + _i * 8192), 16, 0, 0); } while (0)
; #define PG8_LDA(dst, b, h) do { _Pragma("unroll") for (int m = 0; m < 4; ++m) _Pragma("unroll") for (int k = 0; k < 2; ++k) dst[m][k] = *(const PG8_LAS bf16x8*)(lds + PG8_SA(b, h) + aoff + m * 2048 + k * 1024); } while (0)
; #define PG8_BAR __builtin_amdgcn_s_barrier()
; template <class Epi, class Sched, bool ALIGN_EPI = false, bool SP2 = false>
; __device__ __forceinline__ void gemm_phase(PG8_LAS unsigned char* lds, const Gemm g, const Sched& S, const Epi& E) {
;     ...
;         for (int t = 0; t < nt; t += 2) {
;             const bool last = (t == nt - 2);
;             const char* a1 = cA + (size_t)(t + 1) * kstep + (t >= g.kj_t ? g.kj_bytes : 0);
;             const char* a2 = last ? nA : cA + (size_t)(t + 2) * kstep + (t + 2 >= g.kj_t ? g.kj_bytes : 0); const char* b2 = last ? nB : cB + (size_t)(t + 2) * kstep;
;             const char* a3 = a2 + kstep; const char* b3 = b2 + kstep;
;             if (last && has_next) S.a_ready(nxt);
;             if constexpr (Epi::MIDK) { if (t == g.kj_t) E.midk(acc, cur, wr, fr); }
;             if constexpr (SP2) {
;             PG8_LDB(B0, 0, 0); PG8_LDB(B1, 0, 1); PG8_SCHED; PG8_LDA(At, 0, 0); PG8_STAGE(PG8_SA(1, 1), a1 + hstepA, voffA);
;             PG8_WAIT_V(8); PG8_WAIT_L(0); PG8_BAR; PG8_MMA(0, 0, At, B0); PG8_MMA(0, 1, At, B1); PG8_BAR; PG8_SCHED;
;             PG8_LDA(At, 0, 1); PG8_STAGE(PG8_SB(0, 0), b2, voffB); PG8_STAGE(PG8_SB(0, 1), b2 + hstepB, voffB); PG8_STAGE(PG8_SA(0, 0), a2, voffA);
;             PG8_WAIT_V(8); PG8_WAIT_L(0); PG8_BAR; PG8_MMA(1, 0, At, B0); PG8_MMA(1, 1, At, B1); PG8_BAR; PG8_SCHED;
;             PG8_LDB(B0, 1, 0); PG8_LDB(B1, 1, 1); PG8_SCHED; PG8_LDA(At, 1, 0); PG8_STAGE(PG8_SA(0, 1), a2 + hstepA, voffA);
;             PG8_WAIT_V(8); PG8_WAIT_L(0); PG8_BAR; PG8_MMA(0, 0, At, B0); PG8_MMA(0, 1, At, B1); PG8_BAR; PG8_SCHED;
;             PG8_LDA(At, 1, 1); PG8_STAGE(PG8_SB(1, 0), b3, voffB); PG8_STAGE(PG8_SB(1, 1), b3 + hstepB, voffB); PG8_STAGE(PG8_SA(1, 0), a3, voffA);
;             PG8_WAIT_V(8); PG8_WAIT_L(0); PG8_BAR; PG8_MMA(1, 0, At, B0); PG8_MMA(1, 1, At, B1); PG8_BAR; PG8_SCHED;
	v_mfma_f32_16x16x32_bf16 v[74:77], v[192:195], v[216:219], v[74:77]
	v_mfma_f32_16x16x32_bf16 v[74:77], v[188:191], v[212:215], v[74:77]
	v_mfma_f32_16x16x32_bf16 v[66:69], v[188:191], v[220:223], v[66:69]
	v_mfma_f32_16x16x32_bf16 v[66:69], v[192:195], v[224:227], v[66:69]
	v_mfma_f32_16x16x32_bf16 v[70:73], v[184:187], v[224:227], v[70:73]
	v_mfma_f32_16x16x32_bf16 v[70:73], v[180:183], v[220:223], v[70:73]
	s_setprio 0
	s_add_i32 s26, s61, s3
	s_mov_b32 m0, s26
	ds_read_b128 v[196:199], v162 offset:49152
	ds_read_b128 v[200:203], v162 offset:50176
	ds_read_b128 v[204:207], v162 offset:51200
	ds_read_b128 v[208:211], v162 offset:52224
	ds_read_b128 v[212:215], v162 offset:53248
	ds_read_b128 v[216:219], v162 offset:54272
	ds_read_b128 v[220:223], v162 offset:55296
	ds_read_b128 v[224:227], v162 offset:56320
	global_load_lds_dwordx4 v136, s[98:99]
	s_add_i32 m0, s26, 0x2000
	s_add_u32 s24, s24, 0x100080
	s_addc_u32 s25, s25, 0
	s_add_i32 s26, s62, s3
	global_load_lds_dwordx4 v134, s[98:99]
	s_mov_b32 m0, s26
	s_nop 0
	global_load_lds_dwordx4 v136, s[24:25]
	s_add_i32 m0, s26, 0x2000
	s_nop 0
	global_load_lds_dwordx4 v134, s[24:25]
	s_mov_b32 m0, s35
	s_nop 0
	global_load_lds_dwordx4 v130, s[100:101]
	s_mov_b32 m0, s36
	s_nop 0
	global_load_lds_dwordx4 v132, s[100:101]
	s_waitcnt vmcnt(8)
	s_waitcnt lgkmcnt(0)
	s_barrier
	s_setprio 1
	s_waitcnt lgkmcnt(0)
	v_mfma_f32_16x16x32_bf16 v[62:65], v[146:149], v[196:199], v[62:65]
	v_mfma_f32_16x16x32_bf16 v[62:65], v[168:171], v[200:203], v[62:65]
	v_mfma_f32_16x16x32_bf16 v[58:61], v[176:179], v[200:203], v[58:61]
	v_mfma_f32_16x16x32_bf16 v[58:61], v[172:175], v[196:199], v[58:61]
	v_mfma_f32_16x16x32_bf16 v[46:49], v[172:175], v[204:207], v[46:49]
	v_mfma_f32_16x16x32_bf16 v[46:49], v[176:179], v[208:211], v[46:49]
	v_mfma_f32_16x16x32_bf16 v[54:57], v[168:171], v[208:211], v[54:57]
	v_mfma_f32_16x16x32_bf16 v[54:57], v[146:149], v[204:207], v[54:57]
	v_mfma_f32_16x16x32_bf16 v[38:41], v[146:149], v[212:215], v[38:41]
	v_mfma_f32_16x16x32_bf16 v[38:41], v[168:171], v[216:219], v[38:41]
	v_mfma_f32_16x16x32_bf16 v[30:33], v[176:179], v[216:219], v[30:33]
	v_mfma_f32_16x16x32_bf16 v[30:33], v[172:175], v[212:215], v[30:33]
	v_mfma_f32_16x16x32_bf16 v[14:17], v[172:175], v[220:223], v[14:17]
	v_mfma_f32_16x16x32_bf16 v[14:17], v[176:179], v[224:227], v[14:17]
	v_mfma_f32_16x16x32_bf16 v[22:25], v[168:171], v[224:227], v[22:25]
	v_mfma_f32_16x16x32_bf16 v[22:25], v[146:149], v[220:223], v[22:25]
	v_mfma_f32_16x16x32_bf16 v[50:53], v[180:183], v[196:199], v[50:53]
	v_mfma_f32_16x16x32_bf16 v[50:53], v[184:187], v[200:203], v[50:53]
	v_mfma_f32_16x16x32_bf16 v[42:45], v[192:195], v[200:203], v[42:45]
	v_mfma_f32_16x16x32_bf16 v[42:45], v[188:191], v[196:199], v[42:45]
	v_mfma_f32_16x16x32_bf16 v[26:29], v[188:191], v[204:207], v[26:29]
	v_mfma_f32_16x16x32_bf16 v[26:29], v[192:195], v[208:211], v[26:29]
	v_mfma_f32_16x16x32_bf16 v[34:37], v[184:187], v[208:211], v[34:37]
	v_mfma_f32_16x16x32_bf16 v[34:37], v[180:183], v[204:207], v[34:37]
	v_mfma_f32_16x16x32_bf16 v[18:21], v[180:183], v[212:215], v[18:21]
	v_mfma_f32_16x16x32_bf16 v[18:21], v[184:187], v[216:219], v[18:21]
	s_setprio 2
	s_barrier
	v_mfma_f32_16x16x32_bf16 v[10:13], v[192:195], v[216:219], v[10:13]
	v_mfma_f32_16x16x32_bf16 v[10:13], v[188:191], v[212:215], v[10:13]
	v_mfma_f32_16x16x32_bf16 v[2:5], v[188:191], v[220:223], v[2:5]
	v_mfma_f32_16x16x32_bf16 v[2:5], v[192:195], v[224:227], v[2:5]
	v_mfma_f32_16x16x32_bf16 v[6:9], v[184:187], v[224:227], v[6:9]
	v_mfma_f32_16x16x32_bf16 v[6:9], v[180:183], v[220:223], v[6:9]
	s_setprio 0
	s_add_i32 s60, s60, 2
	s_add_u32 s22, s22, 0x100
	s_addc_u32 s23, s23, 0
	s_add_u32 s52, s52, 0x100
	s_addc_u32 s53, s53, 0
.LBB0_525:
	ds_read_b128 v[146:149], v160
	ds_read_b128 v[168:171], v160 offset:1024
	ds_read_b128 v[172:175], v160 offset:2048
	ds_read_b128 v[176:179], v160 offset:3072
	ds_read_b128 v[180:183], v161
	ds_read_b128 v[184:187], v161 offset:1024
	ds_read_b128 v[188:191], v161 offset:2048
	ds_read_b128 v[192:195], v161 offset:3072
	s_add_u32 s24, s22, 0xfff00080
	s_addc_u32 s25, s23, -1
	s_cmp_eq_u32 s60, 60
	s_cselect_b32 s27, s15, s25
	s_cselect_b32 s26, s50, s24
	s_cselect_b32 s25, s13, s53
	s_cselect_b32 s24, s51, s52
	s_add_u32 s98, s24, 0x80
	s_addc_u32 s99, s25, 0
	s_add_u32 s100, s26, 0x80
	s_addc_u32 s101, s27, 0
	s_add_i32 m0, s21, 0xc000
	ds_read_b128 v[196:199], v162
	ds_read_b128 v[200:203], v162 offset:1024
	ds_read_b128 v[204:207], v162 offset:2048
	ds_read_b128 v[208:211], v162 offset:3072
	ds_read_b128 v[212:215], v162 offset:4096
	ds_read_b128 v[216:219], v162 offset:5120
	ds_read_b128 v[220:223], v162 offset:6144
	ds_read_b128 v[224:227], v162 offset:7168
	global_load_lds_dwordx4 v138, s[22:23]
	s_add_i32 m0, s21, 0xe000
	s_nop 0
	global_load_lds_dwordx4 v140, s[22:23]
	s_waitcnt vmcnt(8)
	s_waitcnt lgkmcnt(0)
	s_barrier
; #define PG8_STAGE(bufoff, gbase, voff) do { _Pragma("unroll") for (int _i = 0; _i < 2; ++_i) \
;         __builtin_amdgcn_global_load_lds((const unsigned*)((const char*)(gbase) + (voff)[_i]), (PG8_LAS unsigned*)(lds + (bufoff) + ldsw + _i * 8192), 16, 0, 0); } while (0)
; #define PG8_LDA(dst, b, h) do { _Pragma("unroll") for (int m = 0; m < 4; ++m) _Pragma("unroll") for (int k = 0; k < 2; ++k) dst[m][k] = *(const PG8_LAS bf16x8*)(lds + PG8_SA(b, h) + aoff + m * 2048 + k * 1024); } while (0)
; #define PG8_LDB(dst, b, h) do { _Pragma("unroll") for (int n = 0; n < 2; ++n) _Pragma("unroll") for (int k = 0; k < 2; ++k) dst[n][k] = *(const PG8_LAS bf16x8*)(lds + PG8_SB(b, h) + boff + n * 2048 + k * 1024); } while (0)
; #define PG8_MMA(ai, bj, At, Bt) do { __builtin_amdgcn_s_setprio(1); _Pragma("unroll") for (int m = 0; m < 4; ++m) _Pragma("unroll") for (int n = 0; n < 2; ++n) _Pragma("unroll") for (int k = 0; k < 2; ++k) \
;         acc[ai][bj][m][n] = __builtin_amdgcn_mfma_f32_16x16x32_bf16(Bt[n][k], At[m][k], acc[ai][bj][m][n], 0, 0, 0); __builtin_amdgcn_s_setprio(0); } while (0)
; template <class Epi, class Sched, bool ALIGN_EPI = false, bool SP2 = false>
; __device__ __forceinline__ void gemm_phase(PG8_LAS unsigned char* lds, const Gemm g, const Sched& S, const Epi& E) {
;     ...
;             if constexpr (SP2) {
;             PG8_LDB(B0, 0, 0); PG8_LDB(B1, 0, 1); PG8_SCHED; PG8_LDA(At, 0, 0); PG8_STAGE(PG8_SA(1, 1), a1 + hstepA, voffA);
;             PG8_WAIT_V(8); PG8_WAIT_L(0); PG8_BAR; PG8_MMA(0, 0, At, B0); PG8_MMA(0, 1, At, B1); PG8_BAR; PG8_SCHED;
;             PG8_LDA(At, 0, 1); PG8_STAGE(PG8_SB(0, 0), b2, voffB); PG8_STAGE(PG8_SB(0, 1), b2 + hstepB, voffB); PG8_STAGE(PG8_SA(0, 0), a2, voffA);
;             PG8_WAIT_V(8); PG8_WAIT_L(0); PG8_BAR; PG8_MMA(1, 0, At, B0); PG8_MMA(1, 1, At, B1); PG8_BAR; PG8_SCHED;
;             PG8_LDB(B0, 1, 0); PG8_LDB(B1, 1, 1); PG8_SCHED; PG8_LDA(At, 1, 0); PG8_STAGE(PG8_SA(0, 1), a2 + hstepA, voffA);
;             PG8_WAIT_V(8); PG8_WAIT_L(0); PG8_BAR; PG8_MMA(0, 0, At, B0); PG8_MMA(0, 1, At, B1); PG8_BAR; PG8_SCHED;
;             PG8_LDA(At, 1, 1); PG8_STAGE(PG8_SB(1, 0), b3, voffB); PG8_STAGE(PG8_SB(1, 1), b3 + hstepB, voffB); PG8_STAGE(PG8_SA(1, 0), a3, voffA);
;             PG8_WAIT_V(8); PG8_WAIT_L(0); PG8_BAR; PG8_MMA(1, 0, At, B0); PG8_MMA(1, 1, At, B1); PG8_BAR; PG8_SCHED;
	s_setprio 1
	s_waitcnt lgkmcnt(0)
	v_mfma_f32_16x16x32_bf16 v[126:129], v[146:149], v[196:199], v[126:129]
	v_mfma_f32_16x16x32_bf16 v[126:129], v[168:171], v[200:203], v[126:129]
	v_mfma_f32_16x16x32_bf16 v[122:125], v[176:179], v[200:203], v[122:125]
	v_mfma_f32_16x16x32_bf16 v[122:125], v[172:175], v[196:199], v[122:125]
	v_mfma_f32_16x16x32_bf16 v[114:117], v[172:175], v[204:207], v[114:117]
	v_mfma_f32_16x16x32_bf16 v[114:117], v[176:179], v[208:211], v[114:117]
	v_mfma_f32_16x16x32_bf16 v[118:121], v[168:171], v[208:211], v[118:121]
	v_mfma_f32_16x16x32_bf16 v[118:121], v[146:149], v[204:207], v[118:121]
	v_mfma_f32_16x16x32_bf16 v[110:113], v[146:149], v[212:215], v[110:113]
	v_mfma_f32_16x16x32_bf16 v[110:113], v[168:171], v[216:219], v[110:113]
	v_mfma_f32_16x16x32_bf16 v[98:101], v[176:179], v[216:219], v[98:101]
	v_mfma_f32_16x16x32_bf16 v[98:101], v[172:175], v[212:215], v[98:101]
	v_mfma_f32_16x16x32_bf16 v[78:81], v[172:175], v[220:223], v[78:81]
	v_mfma_f32_16x16x32_bf16 v[78:81], v[176:179], v[224:227], v[78:81]
	v_mfma_f32_16x16x32_bf16 v[82:85], v[168:171], v[224:227], v[82:85]
	v_mfma_f32_16x16x32_bf16 v[82:85], v[146:149], v[220:223], v[82:85]
	v_mfma_f32_16x16x32_bf16 v[106:109], v[180:183], v[196:199], v[106:109]
	v_mfma_f32_16x16x32_bf16 v[106:109], v[184:187], v[200:203], v[106:109]
	v_mfma_f32_16x16x32_bf16 v[102:105], v[192:195], v[200:203], v[102:105]
	v_mfma_f32_16x16x32_bf16 v[102:105], v[188:191], v[196:199], v[102:105]
	v_mfma_f32_16x16x32_bf16 v[90:93], v[188:191], v[204:207], v[90:93]
	v_mfma_f32_16x16x32_bf16 v[90:93], v[192:195], v[208:211], v[90:93]
	v_mfma_f32_16x16x32_bf16 v[94:97], v[184:187], v[208:211], v[94:97]
	v_mfma_f32_16x16x32_bf16 v[94:97], v[180:183], v[204:207], v[94:97]
	v_mfma_f32_16x16x32_bf16 v[86:89], v[180:183], v[212:215], v[86:89]
	v_mfma_f32_16x16x32_bf16 v[86:89], v[184:187], v[216:219], v[86:89]
	s_setprio 2
	s_barrier
	v_mfma_f32_16x16x32_bf16 v[74:77], v[192:195], v[216:219], v[74:77]
	v_mfma_f32_16x16x32_bf16 v[74:77], v[188:191], v[212:215], v[74:77]
	v_mfma_f32_16x16x32_bf16 v[66:69], v[188:191], v[220:223], v[66:69]
	v_mfma_f32_16x16x32_bf16 v[66:69], v[192:195], v[224:227], v[66:69]
	v_mfma_f32_16x16x32_bf16 v[70:73], v[184:187], v[224:227], v[70:73]
	v_mfma_f32_16x16x32_bf16 v[70:73], v[180:183], v[220:223], v[70:73]
	s_setprio 0
	s_add_i32 s61, s38, s3
	s_mov_b32 m0, s61
	ds_read_b128 v[196:199], v162 offset:16384
	ds_read_b128 v[200:203], v162 offset:17408
	ds_read_b128 v[204:207], v162 offset:18432
	ds_read_b128 v[208:211], v162 offset:19456
	ds_read_b128 v[212:215], v162 offset:20480
	ds_read_b128 v[216:219], v162 offset:21504
	ds_read_b128 v[220:223], v162 offset:22528
	ds_read_b128 v[224:227], v162 offset:23552
	global_load_lds_dwordx4 v136, s[24:25]
	s_add_i32 m0, s61, 0x2000
	s_add_u32 s62, s24, 0x100000
	s_addc_u32 s63, s25, 0
	s_add_i32 s61, s39, s3
	global_load_lds_dwordx4 v134, s[24:25]
	s_mov_b32 m0, s61
	s_nop 0
	global_load_lds_dwordx4 v136, s[62:63]
	s_add_i32 m0, s61, 0x2000
	s_nop 0
	global_load_lds_dwordx4 v134, s[62:63]
	s_mov_b32 m0, s21
	s_nop 0
	global_load_lds_dwordx4 v130, s[26:27]
	s_mov_b32 m0, s30
	s_nop 0
	global_load_lds_dwordx4 v132, s[26:27]
	s_waitcnt vmcnt(8)
	s_waitcnt lgkmcnt(0)
	s_barrier
	s_setprio 1
	s_waitcnt lgkmcnt(0)
	v_mfma_f32_16x16x32_bf16 v[62:65], v[146:149], v[196:199], v[62:65]
	v_mfma_f32_16x16x32_bf16 v[62:65], v[168:171], v[200:203], v[62:65]
	v_mfma_f32_16x16x32_bf16 v[58:61], v[176:179], v[200:203], v[58:61]
	v_mfma_f32_16x16x32_bf16 v[58:61], v[172:175], v[196:199], v[58:61]
	v_mfma_f32_16x16x32_bf16 v[46:49], v[172:175], v[204:207], v[46:49]
	v_mfma_f32_16x16x32_bf16 v[46:49], v[176:179], v[208:211], v[46:49]
	v_mfma_f32_16x16x32_bf16 v[54:57], v[168:171], v[208:211], v[54:57]
	v_mfma_f32_16x16x32_bf16 v[54:57], v[146:149], v[204:207], v[54:57]
	v_mfma_f32_16x16x32_bf16 v[38:41], v[146:149], v[212:215], v[38:41]
	v_mfma_f32_16x16x32_bf16 v[38:41], v[168:171], v[216:219], v[38:41]
	v_mfma_f32_16x16x32_bf16 v[30:33], v[176:179], v[216:219], v[30:33]
	v_mfma_f32_16x16x32_bf16 v[30:33], v[172:175], v[212:215], v[30:33]
	v_mfma_f32_16x16x32_bf16 v[14:17], v[172:175], v[220:223], v[14:17]
	v_mfma_f32_16x16x32_bf16 v[14:17], v[176:179], v[224:227], v[14:17]
	v_mfma_f32_16x16x32_bf16 v[22:25], v[168:171], v[224:227], v[22:25]
	v_mfma_f32_16x16x32_bf16 v[22:25], v[146:149], v[220:223], v[22:25]
	v_mfma_f32_16x16x32_bf16 v[50:53], v[180:183], v[196:199], v[50:53]
	v_mfma_f32_16x16x32_bf16 v[50:53], v[184:187], v[200:203], v[50:53]
	v_mfma_f32_16x16x32_bf16 v[42:45], v[192:195], v[200:203], v[42:45]
	v_mfma_f32_16x16x32_bf16 v[42:45], v[188:191], v[196:199], v[42:45]
	v_mfma_f32_16x16x32_bf16 v[26:29], v[188:191], v[204:207], v[26:29]
	v_mfma_f32_16x16x32_bf16 v[26:29], v[192:195], v[208:211], v[26:29]
	v_mfma_f32_16x16x32_bf16 v[34:37], v[184:187], v[208:211], v[34:37]
	v_mfma_f32_16x16x32_bf16 v[34:37], v[180:183], v[204:207], v[34:37]
	v_mfma_f32_16x16x32_bf16 v[18:21], v[180:183], v[212:215], v[18:21]
	v_mfma_f32_16x16x32_bf16 v[18:21], v[184:187], v[216:219], v[18:21]
	s_setprio 2
	s_barrier
; #define PG8_STAGE(bufoff, gbase, voff) do { _Pragma("unroll") for (int _i = 0; _i < 2; ++_i) \
;         __builtin_amdgcn_global_load_lds((const unsigned*)((const char*)(gbase) + (voff)[_i]), (PG8_LAS unsigned*)(lds + (bufoff) + ldsw + _i * 8192), 16, 0, 0); } while (0)
; #define PG8_LDA(dst, b, h) do { _Pragma("unroll") for (int m = 0; m < 4; ++m) _Pragma("unroll") for (int k = 0; k < 2; ++k) dst[m][k] = *(const PG8_LAS bf16x8*)(lds + PG8_SA(b, h) + aoff + m * 2048 + k * 1024); } while (0)
; #define PG8_LDB(dst, b, h) do { _Pragma("unroll") for (int n = 0; n < 2; ++n) _Pragma("unroll") for (int k = 0; k < 2; ++k) dst[n][k] = *(const PG8_LAS bf16x8*)(lds + PG8_SB(b, h) + boff + n * 2048 + k * 1024); } while (0)
; #define PG8_MMA(ai, bj, At, Bt) do { __builtin_amdgcn_s_setprio(1); _Pragma("unroll") for (int m = 0; m < 4; ++m) _Pragma("unroll") for (int n = 0; n < 2; ++n) _Pragma("unroll") for (int k = 0; k < 2; ++k) \
;         acc[ai][bj][m][n] = __builtin_amdgcn_mfma_f32_16x16x32_bf16(Bt[n][k], At[m][k], acc[ai][bj][m][n], 0, 0, 0); __builtin_amdgcn_s_setprio(0); } while (0)
; template <class Epi, class Sched, bool ALIGN_EPI = false, bool SP2 = false>
; __device__ __forceinline__ void gemm_phase(PG8_LAS unsigned char* lds, const Gemm g, const Sched& S, const Epi& E) {
;     ...
;             if constexpr (SP2) {
;             PG8_LDB(B0, 0, 0); PG8_LDB(B1, 0, 1); PG8_SCHED; PG8_LDA(At, 0, 0); PG8_STAGE(PG8_SA(1, 1), a1 + hstepA, voffA);
;             PG8_WAIT_V(8); PG8_WAIT_L(0); PG8_BAR; PG8_MMA(0, 0, At, B0); PG8_MMA(0, 1, At, B1); PG8_BAR; PG8_SCHED;
;             PG8_LDA(At, 0, 1); PG8_STAGE(PG8_SB(0, 0), b2, voffB); PG8_STAGE(PG8_SB(0, 1), b2 + hstepB, voffB); PG8_STAGE(PG8_SA(0, 0), a2, voffA);
;             PG8_WAIT_V(8); PG8_WAIT_L(0); PG8_BAR; PG8_MMA(1, 0, At, B0); PG8_MMA(1, 1, At, B1); PG8_BAR; PG8_SCHED;
;             PG8_LDB(B0, 1, 0); PG8_LDB(B1, 1, 1); PG8_SCHED; PG8_LDA(At, 1, 0); PG8_STAGE(PG8_SA(0, 1), a2 + hstepA, voffA);
;             PG8_WAIT_V(8); PG8_WAIT_L(0); PG8_BAR; PG8_MMA(0, 0, At, B0); PG8_MMA(0, 1, At, B1); PG8_BAR; PG8_SCHED;
;             PG8_LDA(At, 1, 1); PG8_STAGE(PG8_SB(1, 0), b3, voffB); PG8_STAGE(PG8_SB(1, 1), b3 + hstepB, voffB); PG8_STAGE(PG8_SA(1, 0), a3, voffA);
;             PG8_WAIT_V(8); PG8_WAIT_L(0); PG8_BAR; PG8_MMA(1, 0, At, B0); PG8_MMA(1, 1, At, B1); PG8_BAR; PG8_SCHED;
	v_mfma_f32_16x16x32_bf16 v[10:13], v[192:195], v[216:219], v[10:13]
	v_mfma_f32_16x16x32_bf16 v[10:13], v[188:191], v[212:215], v[10:13]
	v_mfma_f32_16x16x32_bf16 v[2:5], v[188:191], v[220:223], v[2:5]
	v_mfma_f32_16x16x32_bf16 v[2:5], v[192:195], v[224:227], v[2:5]
	v_mfma_f32_16x16x32_bf16 v[6:9], v[184:187], v[224:227], v[6:9]
	v_mfma_f32_16x16x32_bf16 v[6:9], v[180:183], v[220:223], v[6:9]
	s_setprio 0
	s_add_i32 s61, 0, 0x18000
	v_add_u32_e32 v150, s61, v158
	s_add_i32 s62, 0, 0x1c000
	ds_read_b128 v[146:149], v150
	ds_read_b128 v[168:171], v150 offset:1024
	ds_read_b128 v[172:175], v150 offset:2048
	ds_read_b128 v[176:179], v150 offset:3072
	v_add_u32_e32 v150, s62, v158
	ds_read_b128 v[180:183], v150
	ds_read_b128 v[184:187], v150 offset:1024
	ds_read_b128 v[188:191], v150 offset:2048
	ds_read_b128 v[192:195], v150 offset:3072
	s_add_u32 s26, s26, 0x100000
	s_addc_u32 s27, s27, 0
	s_mov_b32 m0, s31
	ds_read_b128 v[196:199], v162 offset:32768
	ds_read_b128 v[200:203], v162 offset:33792
	ds_read_b128 v[204:207], v162 offset:34816
	ds_read_b128 v[208:211], v162 offset:35840
	ds_read_b128 v[212:215], v162 offset:36864
	ds_read_b128 v[216:219], v162 offset:37888
	ds_read_b128 v[220:223], v162 offset:38912
	ds_read_b128 v[224:227], v162 offset:39936
	global_load_lds_dwordx4 v130, s[26:27]
	s_mov_b32 m0, s33
	s_nop 0
	global_load_lds_dwordx4 v132, s[26:27]
	s_waitcnt vmcnt(8)
	s_waitcnt lgkmcnt(0)
	s_barrier
	s_setprio 1
	s_waitcnt lgkmcnt(0)
	v_mfma_f32_16x16x32_bf16 v[126:129], v[146:149], v[196:199], v[126:129]
	v_mfma_f32_16x16x32_bf16 v[126:129], v[168:171], v[200:203], v[126:129]
	v_mfma_f32_16x16x32_bf16 v[122:125], v[176:179], v[200:203], v[122:125]
	v_mfma_f32_16x16x32_bf16 v[122:125], v[172:175], v[196:199], v[122:125]
	v_mfma_f32_16x16x32_bf16 v[114:117], v[172:175], v[204:207], v[114:117]
	v_mfma_f32_16x16x32_bf16 v[114:117], v[176:179], v[208:211], v[114:117]
	v_mfma_f32_16x16x32_bf16 v[118:121], v[168:171], v[208:211], v[118:121]
	v_mfma_f32_16x16x32_bf16 v[118:121], v[146:149], v[204:207], v[118:121]
	v_mfma_f32_16x16x32_bf16 v[110:113], v[146:149], v[212:215], v[110:113]
	v_mfma_f32_16x16x32_bf16 v[110:113], v[168:171], v[216:219], v[110:113]
	v_mfma_f32_16x16x32_bf16 v[98:101], v[176:179], v[216:219], v[98:101]
	v_mfma_f32_16x16x32_bf16 v[98:101], v[172:175], v[212:215], v[98:101]
	v_mfma_f32_16x16x32_bf16 v[78:81], v[172:175], v[220:223], v[78:81]
	v_mfma_f32_16x16x32_bf16 v[78:81], v[176:179], v[224:227], v[78:81]
	v_mfma_f32_16x16x32_bf16 v[82:85], v[168:171], v[224:227], v[82:85]
	v_mfma_f32_16x16x32_bf16 v[82:85], v[146:149], v[220:223], v[82:85]
	v_mfma_f32_16x16x32_bf16 v[106:109], v[180:183], v[196:199], v[106:109]
	v_mfma_f32_16x16x32_bf16 v[106:109], v[184:187], v[200:203], v[106:109]
	v_mfma_f32_16x16x32_bf16 v[102:105], v[192:195], v[200:203], v[102:105]
	v_mfma_f32_16x16x32_bf16 v[102:105], v[188:191], v[196:199], v[102:105]
	v_mfma_f32_16x16x32_bf16 v[90:93], v[188:191], v[204:207], v[90:93]
	v_mfma_f32_16x16x32_bf16 v[90:93], v[192:195], v[208:211], v[90:93]
	v_mfma_f32_16x16x32_bf16 v[94:97], v[184:187], v[208:211], v[94:97]
	v_mfma_f32_16x16x32_bf16 v[94:97], v[180:183], v[204:207], v[94:97]
	v_mfma_f32_16x16x32_bf16 v[86:89], v[180:183], v[212:215], v[86:89]
	v_mfma_f32_16x16x32_bf16 v[86:89], v[184:187], v[216:219], v[86:89]
	s_setprio 2
	s_barrier
; #define PG8_STAGE(bufoff, gbase, voff) do { _Pragma("unroll") for (int _i = 0; _i < 2; ++_i) \
;         __builtin_amdgcn_global_load_lds((const unsigned*)((const char*)(gbase) + (voff)[_i]), (PG8_LAS unsigned*)(lds + (bufoff) + ldsw + _i * 8192), 16, 0, 0); } while (0)
; #define PG8_LDA(dst, b, h) do { _Pragma("unroll") for (int m = 0; m < 4; ++m) _Pragma("unroll") for (int k = 0; k < 2; ++k) dst[m][k] = *(const PG8_LAS bf16x8*)(lds + PG8_SA(b, h) + aoff + m * 2048 + k * 1024); } while (0)
; #define PG8_LDB(dst, b, h) do { _Pragma("unroll") for (int n = 0; n < 2; ++n) _Pragma("unroll") for (int k = 0; k < 2; ++k) dst[n][k] = *(const PG8_LAS bf16x8*)(lds + PG8_SB(b, h) + boff + n * 2048 + k * 1024); } while (0)
; #define PG8_MMA(ai, bj, At, Bt) do { __builtin_amdgcn_s_setprio(1); _Pragma("unroll") for (int m = 0; m < 4; ++m) _Pragma("unroll") for (int n = 0; n < 2; ++n) _Pragma("unroll") for (int k = 0; k < 2; ++k) \
;         acc[ai][bj][m][n] = __builtin_amdgcn_mfma_f32_16x16x32_bf16(Bt[n][k], At[m][k], acc[ai][bj][m][n], 0, 0, 0); __builtin_amdgcn_s_setprio(0); } while (0)
; template <class Epi, class Sched, bool ALIGN_EPI = false, bool SP2 = false>
; __device__ __forceinline__ void gemm_phase(PG8_LAS unsigned char* lds, const Gemm g, const Sched& S, const Epi& E) {
;     ...
;             if constexpr (SP2) {
;             PG8_LDB(B0, 0, 0); PG8_LDB(B1, 0, 1); PG8_SCHED; PG8_LDA(At, 0, 0); PG8_STAGE(PG8_SA(1, 1), a1 + hstepA, voffA);
;             PG8_WAIT_V(8); PG8_WAIT_L(0); PG8_BAR; PG8_MMA(0, 0, At, B0); PG8_MMA(0, 1, At, B1); PG8_BAR; PG8_SCHED;
;             PG8_LDA(At, 0, 1); PG8_STAGE(PG8_SB(0, 0), b2, voffB); PG8_STAGE(PG8_SB(0, 1), b2 + hstepB, voffB); PG8_STAGE(PG8_SA(0, 0), a2, voffA);
;             PG8_WAIT_V(8); PG8_WAIT_L(0); PG8_BAR; PG8_MMA(1, 0, At, B0); PG8_MMA(1, 1, At, B1); PG8_BAR; PG8_SCHED;
;             PG8_LDB(B0, 1, 0); PG8_LDB(B1, 1, 1); PG8_SCHED; PG8_LDA(At, 1, 0); PG8_STAGE(PG8_SA(0, 1), a2 + hstepA, voffA);
;             PG8_WAIT_V(8); PG8_WAIT_L(0); PG8_BAR; PG8_MMA(0, 0, At, B0); PG8_MMA(0, 1, At, B1); PG8_BAR; PG8_SCHED;
;             PG8_LDA(At, 1, 1); PG8_STAGE(PG8_SB(1, 0), b3, voffB); PG8_STAGE(PG8_SB(1, 1), b3 + hstepB, voffB); PG8_STAGE(PG8_SA(1, 0), a3, voffA);
;             PG8_WAIT_V(8); PG8_WAIT_L(0); PG8_BAR; PG8_MMA(1, 0, At, B0); PG8_MMA(1, 1, At, B1); PG8_BAR; PG8_SCHED;
	v_mfma_f32_16x16x32_bf16 v[74:77], v[192:195], v[216:219], v[74:77]
	v_mfma_f32_16x16x32_bf16 v[74:77], v[188:191], v[212:215], v[74:77]
	v_mfma_f32_16x16x32_bf16 v[66:69], v[188:191], v[220:223], v[66:69]
	v_mfma_f32_16x16x32_bf16 v[66:69], v[192:195], v[224:227], v[66:69]
	v_mfma_f32_16x16x32_bf16 v[70:73], v[184:187], v[224:227], v[70:73]
	v_mfma_f32_16x16x32_bf16 v[70:73], v[180:183], v[220:223], v[70:73]
	s_setprio 0
	s_add_i32 s26, s61, s3
	s_mov_b32 m0, s26
	ds_read_b128 v[196:199], v162 offset:49152
	ds_read_b128 v[200:203], v162 offset:50176
	ds_read_b128 v[204:207], v162 offset:51200
	ds_read_b128 v[208:211], v162 offset:52224
	ds_read_b128 v[212:215], v162 offset:53248
	ds_read_b128 v[216:219], v162 offset:54272
	ds_read_b128 v[220:223], v162 offset:55296
	ds_read_b128 v[224:227], v162 offset:56320
	global_load_lds_dwordx4 v136, s[98:99]
	s_add_i32 m0, s26, 0x2000
	s_add_u32 s24, s24, 0x100080
	s_addc_u32 s25, s25, 0
	s_add_i32 s26, s62, s3
	global_load_lds_dwordx4 v134, s[98:99]
	s_mov_b32 m0, s26
	s_nop 0
	global_load_lds_dwordx4 v136, s[24:25]
	s_add_i32 m0, s26, 0x2000
	s_nop 0
	global_load_lds_dwordx4 v134, s[24:25]
	s_mov_b32 m0, s35
	s_nop 0
	global_load_lds_dwordx4 v130, s[100:101]
	s_mov_b32 m0, s36
	s_nop 0
	global_load_lds_dwordx4 v132, s[100:101]
	s_waitcnt vmcnt(8)
	s_waitcnt lgkmcnt(0)
	s_barrier
	s_setprio 1
	s_waitcnt lgkmcnt(0)
	v_mfma_f32_16x16x32_bf16 v[62:65], v[146:149], v[196:199], v[62:65]
	v_mfma_f32_16x16x32_bf16 v[62:65], v[168:171], v[200:203], v[62:65]
	v_mfma_f32_16x16x32_bf16 v[58:61], v[176:179], v[200:203], v[58:61]
	v_mfma_f32_16x16x32_bf16 v[58:61], v[172:175], v[196:199], v[58:61]
	v_mfma_f32_16x16x32_bf16 v[46:49], v[172:175], v[204:207], v[46:49]
	v_mfma_f32_16x16x32_bf16 v[46:49], v[176:179], v[208:211], v[46:49]
	v_mfma_f32_16x16x32_bf16 v[54:57], v[168:171], v[208:211], v[54:57]
	v_mfma_f32_16x16x32_bf16 v[54:57], v[146:149], v[204:207], v[54:57]
	v_mfma_f32_16x16x32_bf16 v[38:41], v[146:149], v[212:215], v[38:41]
	v_mfma_f32_16x16x32_bf16 v[38:41], v[168:171], v[216:219], v[38:41]
	v_mfma_f32_16x16x32_bf16 v[30:33], v[176:179], v[216:219], v[30:33]
	v_mfma_f32_16x16x32_bf16 v[30:33], v[172:175], v[212:215], v[30:33]
	v_mfma_f32_16x16x32_bf16 v[14:17], v[172:175], v[220:223], v[14:17]
	v_mfma_f32_16x16x32_bf16 v[14:17], v[176:179], v[224:227], v[14:17]
	v_mfma_f32_16x16x32_bf16 v[22:25], v[168:171], v[224:227], v[22:25]
	v_mfma_f32_16x16x32_bf16 v[22:25], v[146:149], v[220:223], v[22:25]
	v_mfma_f32_16x16x32_bf16 v[50:53], v[180:183], v[196:199], v[50:53]
	v_mfma_f32_16x16x32_bf16 v[50:53], v[184:187], v[200:203], v[50:53]
	v_mfma_f32_16x16x32_bf16 v[42:45], v[192:195], v[200:203], v[42:45]
	v_mfma_f32_16x16x32_bf16 v[42:45], v[188:191], v[196:199], v[42:45]
	v_mfma_f32_16x16x32_bf16 v[26:29], v[188:191], v[204:207], v[26:29]
	v_mfma_f32_16x16x32_bf16 v[26:29], v[192:195], v[208:211], v[26:29]
	v_mfma_f32_16x16x32_bf16 v[34:37], v[184:187], v[208:211], v[34:37]
	v_mfma_f32_16x16x32_bf16 v[34:37], v[180:183], v[204:207], v[34:37]
	v_mfma_f32_16x16x32_bf16 v[18:21], v[180:183], v[212:215], v[18:21]
	v_mfma_f32_16x16x32_bf16 v[18:21], v[184:187], v[216:219], v[18:21]
	s_setprio 2
	s_barrier
	v_mfma_f32_16x16x32_bf16 v[10:13], v[192:195], v[216:219], v[10:13]
	v_mfma_f32_16x16x32_bf16 v[10:13], v[188:191], v[212:215], v[10:13]
	v_mfma_f32_16x16x32_bf16 v[2:5], v[188:191], v[220:223], v[2:5]
	v_mfma_f32_16x16x32_bf16 v[2:5], v[192:195], v[224:227], v[2:5]
	v_mfma_f32_16x16x32_bf16 v[6:9], v[184:187], v[224:227], v[6:9]
	v_mfma_f32_16x16x32_bf16 v[6:9], v[180:183], v[220:223], v[6:9]
	s_setprio 0
	s_add_i32 s60, s60, 2
	s_add_u32 s22, s22, 0x100
	s_addc_u32 s23, s23, 0
	s_add_u32 s52, s52, 0x100
	s_addc_u32 s53, s53, 0
	s_cmp_gt_u32 s60, 61
	s_cbranch_scc0 .LBB0_525
	s_and_b64 vcc, exec, s[10:11]
	s_cbranch_vccz .LBB0_528

; #define PG8_STAGE(bufoff, gbase, voff) do { _Pragma("unroll") for (int _i = 0; _i < 2; ++_i) \
;         __builtin_amdgcn_global_load_lds((const unsigned*)((const char*)(gbase) + (voff)[_i]), (PG8_LAS unsigned*)(lds + (bufoff) + ldsw + _i * 8192), 16, 0, 0); } while (0)
; #define PG8_LDA(dst, b, h) do { _Pragma("unroll") for (int m = 0; m < 4; ++m) _Pragma("unroll") for (int k = 0; k < 2; ++k) dst[m][k] = *(const PG8_LAS bf16x8*)(lds + PG8_SA(b, h) + aoff + m * 2048 + k * 1024); } while (0)
; #define PG8_BAR __builtin_amdgcn_s_barrier()
; template <class Epi, class Sched, bool ALIGN_EPI = false, bool SP2 = false>
; __device__ __forceinline__ void gemm_phase(PG8_LAS unsigned char* lds, const Gemm g, const Sched& S, const Epi& E) {
;     ...
;         for (int t = 0; t < nt; t += 2) {
;             const bool last = (t == nt - 2);
;             const char* a1 = cA + (size_t)(t + 1) * kstep + (t >= g.kj_t ? g.kj_bytes : 0);
;             const char* a2 = last ? nA : cA + (size_t)(t + 2) * kstep + (t + 2 >= g.kj_t ? g.kj_bytes : 0); const char* b2 = last ? nB : cB + (size_t)(t + 2) * kstep;
;             const char* a3 = a2 + kstep; const char* b3 = b2 + kstep;
;             if (last && has_next) S.a_ready(nxt);
;             if constexpr (Epi::MIDK) { if (t == g.kj_t) E.midk(acc, cur, wr, fr); }
;             if constexpr (SP2) {
;             PG8_LDB(B0, 0, 0); PG8_LDB(B1, 0, 1); PG8_SCHED; PG8_LDA(At, 0, 0); PG8_STAGE(PG8_SA(1, 1), a1 + hstepA, voffA);
;             PG8_WAIT_V(8); PG8_WAIT_L(0); PG8_BAR; PG8_MMA(0, 0, At, B0); PG8_MMA(0, 1, At, B1); PG8_BAR; PG8_SCHED;
;             PG8_LDA(At, 0, 1); PG8_STAGE(PG8_SB(0, 0), b2, voffB); PG8_STAGE(PG8_SB(0, 1), b2 + hstepB, voffB); PG8_STAGE(PG8_SA(0, 0), a2, voffA);
;             PG8_WAIT_V(8); PG8_WAIT_L(0); PG8_BAR; PG8_MMA(1, 0, At, B0); PG8_MMA(1, 1, At, B1); PG8_BAR; PG8_SCHED;
;             PG8_LDB(B0, 1, 0); PG8_LDB(B1, 1, 1); PG8_SCHED; PG8_LDA(At, 1, 0); PG8_STAGE(PG8_SA(0, 1), a2 + hstepA, voffA);
;             PG8_WAIT_V(8); PG8_WAIT_L(0); PG8_BAR; PG8_MMA(0, 0, At, B0); PG8_MMA(0, 1, At, B1); PG8_BAR; PG8_SCHED;
;             PG8_LDA(At, 1, 1); PG8_STAGE(PG8_SB(1, 0), b3, voffB); PG8_STAGE(PG8_SB(1, 1), b3 + hstepB, voffB); PG8_STAGE(PG8_SA(1, 0), a3, voffA);
;             PG8_WAIT_V(8); PG8_WAIT_L(0); PG8_BAR; PG8_MMA(1, 0, At, B0); PG8_MMA(1, 1, At, B1); PG8_BAR; PG8_SCHED;
.LBB0_881:
	s_ashr_i32 s27, s26, 31
	s_lshl_b64 s[30:31], s[26:27], 22
	v_readlane_b32 s64, v253, 39
	v_readlane_b32 s65, v253, 40
	s_add_u32 s30, s64, s30
	s_addc_u32 s31, s65, s31
	s_and_b64 s[6:7], s[6:7], exec
	s_cselect_b32 s27, s31, s37
	s_cselect_b32 s35, s30, s36
	s_add_u32 s6, s38, 0x490080
	s_addc_u32 s7, s39, 0
	s_add_u32 s63, s36, 0x100
	s_addc_u32 s64, s37, 0
	s_mov_b32 s65, -2
	ds_read_b128 v[128:131], v192
	ds_read_b128 v[132:135], v192 offset:1024
	ds_read_b128 v[136:139], v192 offset:2048
	ds_read_b128 v[140:143], v192 offset:3072
	ds_read_b128 v[160:163], v193
	ds_read_b128 v[168:171], v193 offset:1024
	ds_read_b128 v[172:175], v193 offset:2048
	ds_read_b128 v[176:179], v193 offset:3072
	s_add_u32 s36, s6, 0xffb70080
	s_addc_u32 s37, s7, -1
	s_cmpk_eq_i32 s65, 0x7c
	s_cselect_b32 s39, s29, s37
	s_cselect_b32 s38, s28, s36
	s_cselect_b32 s37, s27, s64
	s_cselect_b32 s36, s35, s63
	s_add_u32 s98, s36, 0x80
	s_addc_u32 s99, s37, 0
	s_add_u32 s100, s38, 0x80
	s_addc_u32 s101, s39, 0
	s_add_i32 m0, s41, 0xc000
	ds_read_b128 v[180:183], v194
	ds_read_b128 v[184:187], v194 offset:1024
	ds_read_b128 v[196:199], v194 offset:2048
	ds_read_b128 v[200:203], v194 offset:3072
	ds_read_b128 v[204:207], v194 offset:4096
	ds_read_b128 v[208:211], v194 offset:5120
	ds_read_b128 v[212:215], v194 offset:6144
	ds_read_b128 v[216:219], v194 offset:7168
	global_load_lds_dwordx4 v152, s[6:7]
	s_add_i32 m0, s41, 0xe000
	s_nop 0
	global_load_lds_dwordx4 v154, s[6:7]
	s_waitcnt vmcnt(8)
	s_waitcnt lgkmcnt(0)
	s_barrier
	s_setprio 1
	s_waitcnt lgkmcnt(0)
	v_mfma_f32_16x16x32_bf16 v[124:127], v[128:131], v[180:183], 0
	v_mfma_f32_16x16x32_bf16 v[124:127], v[132:135], v[184:187], v[124:127]
	v_mfma_f32_16x16x32_bf16 v[120:123], v[140:143], v[184:187], 0
	v_mfma_f32_16x16x32_bf16 v[120:123], v[136:139], v[180:183], v[120:123]
	v_mfma_f32_16x16x32_bf16 v[104:107], v[136:139], v[196:199], 0
	v_mfma_f32_16x16x32_bf16 v[104:107], v[140:143], v[200:203], v[104:107]
	v_mfma_f32_16x16x32_bf16 v[108:111], v[132:135], v[200:203], 0
	v_mfma_f32_16x16x32_bf16 v[108:111], v[128:131], v[196:199], v[108:111]
	v_mfma_f32_16x16x32_bf16 v[92:95], v[128:131], v[204:207], 0
	v_mfma_f32_16x16x32_bf16 v[92:95], v[132:135], v[208:211], v[92:95]
	v_mfma_f32_16x16x32_bf16 v[88:91], v[140:143], v[208:211], 0
	v_mfma_f32_16x16x32_bf16 v[88:91], v[136:139], v[204:207], v[88:91]
	v_mfma_f32_16x16x32_bf16 v[72:75], v[136:139], v[212:215], 0
	v_mfma_f32_16x16x32_bf16 v[72:75], v[140:143], v[216:219], v[72:75]
	v_mfma_f32_16x16x32_bf16 v[76:79], v[132:135], v[216:219], 0
	v_mfma_f32_16x16x32_bf16 v[76:79], v[128:131], v[212:215], v[76:79]
	v_mfma_f32_16x16x32_bf16 v[116:119], v[160:163], v[180:183], 0
	v_mfma_f32_16x16x32_bf16 v[116:119], v[168:171], v[184:187], v[116:119]
	v_mfma_f32_16x16x32_bf16 v[112:115], v[176:179], v[184:187], 0
	v_mfma_f32_16x16x32_bf16 v[112:115], v[172:175], v[180:183], v[112:115]
	v_mfma_f32_16x16x32_bf16 v[96:99], v[172:175], v[196:199], 0
	v_mfma_f32_16x16x32_bf16 v[96:99], v[176:179], v[200:203], v[96:99]
	v_mfma_f32_16x16x32_bf16 v[100:103], v[168:171], v[200:203], 0
	v_mfma_f32_16x16x32_bf16 v[100:103], v[160:163], v[196:199], v[100:103]
	v_mfma_f32_16x16x32_bf16 v[84:87], v[160:163], v[204:207], 0
	v_mfma_f32_16x16x32_bf16 v[84:87], v[168:171], v[208:211], v[84:87]
	s_setprio 2
	s_barrier
	v_mfma_f32_16x16x32_bf16 v[80:83], v[176:179], v[208:211], 0
	v_mfma_f32_16x16x32_bf16 v[80:83], v[172:175], v[204:207], v[80:83]
	v_mfma_f32_16x16x32_bf16 v[64:67], v[172:175], v[212:215], 0
	v_mfma_f32_16x16x32_bf16 v[64:67], v[176:179], v[216:219], v[64:67]
	v_mfma_f32_16x16x32_bf16 v[68:71], v[168:171], v[216:219], 0
	v_mfma_f32_16x16x32_bf16 v[68:71], v[160:163], v[212:215], v[68:71]
	s_setprio 0
	s_add_i32 s66, s52, s40
	s_mov_b32 m0, s66
	ds_read_b128 v[180:183], v194 offset:16384
	ds_read_b128 v[184:187], v194 offset:17408
	ds_read_b128 v[196:199], v194 offset:18432
	ds_read_b128 v[200:203], v194 offset:19456
	ds_read_b128 v[204:207], v194 offset:20480
	ds_read_b128 v[208:211], v194 offset:21504
	ds_read_b128 v[212:215], v194 offset:22528
	ds_read_b128 v[216:219], v194 offset:23552
	global_load_lds_dwordx4 v146, s[36:37]
	s_add_i32 m0, s66, 0x2000
	s_add_u32 s66, s36, 0x200000
	s_addc_u32 s67, s37, 0
	s_add_i32 s68, s53, s40
	global_load_lds_dwordx4 v150, s[36:37]
	s_mov_b32 m0, s68
	s_nop 0
	global_load_lds_dwordx4 v146, s[66:67]
	s_add_i32 m0, s68, 0x2000
	s_nop 0
	global_load_lds_dwordx4 v150, s[66:67]
	s_mov_b32 m0, s41
	s_nop 0
	global_load_lds_dwordx4 v144, s[38:39]
	s_mov_b32 m0, s44
	s_nop 0
	global_load_lds_dwordx4 v148, s[38:39]
	s_waitcnt vmcnt(8)
	s_waitcnt lgkmcnt(0)
	s_barrier
	s_setprio 1
	s_waitcnt lgkmcnt(0)
	v_mfma_f32_16x16x32_bf16 v[60:63], v[128:131], v[180:183], 0
	v_mfma_f32_16x16x32_bf16 v[60:63], v[132:135], v[184:187], v[60:63]
	v_mfma_f32_16x16x32_bf16 v[56:59], v[140:143], v[184:187], 0
	v_mfma_f32_16x16x32_bf16 v[56:59], v[136:139], v[180:183], v[56:59]
	v_mfma_f32_16x16x32_bf16 v[40:43], v[136:139], v[196:199], 0
	v_mfma_f32_16x16x32_bf16 v[40:43], v[140:143], v[200:203], v[40:43]
	v_mfma_f32_16x16x32_bf16 v[44:47], v[132:135], v[200:203], 0
	v_mfma_f32_16x16x32_bf16 v[44:47], v[128:131], v[196:199], v[44:47]
	v_mfma_f32_16x16x32_bf16 v[28:31], v[128:131], v[204:207], 0
	v_mfma_f32_16x16x32_bf16 v[28:31], v[132:135], v[208:211], v[28:31]
	v_mfma_f32_16x16x32_bf16 v[24:27], v[140:143], v[208:211], 0
	v_mfma_f32_16x16x32_bf16 v[24:27], v[136:139], v[204:207], v[24:27]
	v_mfma_f32_16x16x32_bf16 v[8:11], v[136:139], v[212:215], 0
	v_mfma_f32_16x16x32_bf16 v[8:11], v[140:143], v[216:219], v[8:11]
	v_mfma_f32_16x16x32_bf16 v[12:15], v[132:135], v[216:219], 0
	v_mfma_f32_16x16x32_bf16 v[12:15], v[128:131], v[212:215], v[12:15]
	v_mfma_f32_16x16x32_bf16 v[52:55], v[160:163], v[180:183], 0
	v_mfma_f32_16x16x32_bf16 v[52:55], v[168:171], v[184:187], v[52:55]
	v_mfma_f32_16x16x32_bf16 v[48:51], v[176:179], v[184:187], 0
	v_mfma_f32_16x16x32_bf16 v[48:51], v[172:175], v[180:183], v[48:51]
	v_mfma_f32_16x16x32_bf16 v[32:35], v[172:175], v[196:199], 0
	v_mfma_f32_16x16x32_bf16 v[32:35], v[176:179], v[200:203], v[32:35]
	v_mfma_f32_16x16x32_bf16 v[36:39], v[168:171], v[200:203], 0
	v_mfma_f32_16x16x32_bf16 v[36:39], v[160:163], v[196:199], v[36:39]
	v_mfma_f32_16x16x32_bf16 v[20:23], v[160:163], v[204:207], 0
	v_mfma_f32_16x16x32_bf16 v[20:23], v[168:171], v[208:211], v[20:23]
	s_setprio 2
	s_barrier
; #define PG8_STAGE(bufoff, gbase, voff) do { _Pragma("unroll") for (int _i = 0; _i < 2; ++_i) \
;         __builtin_amdgcn_global_load_lds((const unsigned*)((const char*)(gbase) + (voff)[_i]), (PG8_LAS unsigned*)(lds + (bufoff) + ldsw + _i * 8192), 16, 0, 0); } while (0)
; #define PG8_LDA(dst, b, h) do { _Pragma("unroll") for (int m = 0; m < 4; ++m) _Pragma("unroll") for (int k = 0; k < 2; ++k) dst[m][k] = *(const PG8_LAS bf16x8*)(lds + PG8_SA(b, h) + aoff + m * 2048 + k * 1024); } while (0)
; #define PG8_LDB(dst, b, h) do { _Pragma("unroll") for (int n = 0; n < 2; ++n) _Pragma("unroll") for (int k = 0; k < 2; ++k) dst[n][k] = *(const PG8_LAS bf16x8*)(lds + PG8_SB(b, h) + boff + n * 2048 + k * 1024); } while (0)
; #define PG8_MMA(ai, bj, At, Bt) do { __builtin_amdgcn_s_setprio(1); _Pragma("unroll") for (int m = 0; m < 4; ++m) _Pragma("unroll") for (int n = 0; n < 2; ++n) _Pragma("unroll") for (int k = 0; k < 2; ++k) \
;         acc[ai][bj][m][n] = __builtin_amdgcn_mfma_f32_16x16x32_bf16(Bt[n][k], At[m][k], acc[ai][bj][m][n], 0, 0, 0); __builtin_amdgcn_s_setprio(0); } while (0)
; template <class Epi, class Sched, bool ALIGN_EPI = false, bool SP2 = false>
; __device__ __forceinline__ void gemm_phase(PG8_LAS unsigned char* lds, const Gemm g, const Sched& S, const Epi& E) {
;     ...
;             if constexpr (SP2) {
;             PG8_LDB(B0, 0, 0); PG8_LDB(B1, 0, 1); PG8_SCHED; PG8_LDA(At, 0, 0); PG8_STAGE(PG8_SA(1, 1), a1 + hstepA, voffA);
;             PG8_WAIT_V(8); PG8_WAIT_L(0); PG8_BAR; PG8_MMA(0, 0, At, B0); PG8_MMA(0, 1, At, B1); PG8_BAR; PG8_SCHED;
;             PG8_LDA(At, 0, 1); PG8_STAGE(PG8_SB(0, 0), b2, voffB); PG8_STAGE(PG8_SB(0, 1), b2 + hstepB, voffB); PG8_STAGE(PG8_SA(0, 0), a2, voffA);
;             PG8_WAIT_V(8); PG8_WAIT_L(0); PG8_BAR; PG8_MMA(1, 0, At, B0); PG8_MMA(1, 1, At, B1); PG8_BAR; PG8_SCHED;
;             PG8_LDB(B0, 1, 0); PG8_LDB(B1, 1, 1); PG8_SCHED; PG8_LDA(At, 1, 0); PG8_STAGE(PG8_SA(0, 1), a2 + hstepA, voffA);
;             PG8_WAIT_V(8); PG8_WAIT_L(0); PG8_BAR; PG8_MMA(0, 0, At, B0); PG8_MMA(0, 1, At, B1); PG8_BAR; PG8_SCHED;
;             PG8_LDA(At, 1, 1); PG8_STAGE(PG8_SB(1, 0), b3, voffB); PG8_STAGE(PG8_SB(1, 1), b3 + hstepB, voffB); PG8_STAGE(PG8_SA(1, 0), a3, voffA);
;             PG8_WAIT_V(8); PG8_WAIT_L(0); PG8_BAR; PG8_MMA(1, 0, At, B0); PG8_MMA(1, 1, At, B1); PG8_BAR; PG8_SCHED;
	v_mfma_f32_16x16x32_bf16 v[16:19], v[176:179], v[208:211], 0
	v_mfma_f32_16x16x32_bf16 v[16:19], v[172:175], v[204:207], v[16:19]
	v_mfma_f32_16x16x32_bf16 v[0:3], v[172:175], v[212:215], 0
	v_mfma_f32_16x16x32_bf16 v[0:3], v[176:179], v[216:219], v[0:3]
	v_mfma_f32_16x16x32_bf16 v[4:7], v[168:171], v[216:219], 0
	v_mfma_f32_16x16x32_bf16 v[4:7], v[160:163], v[212:215], v[4:7]
	s_setprio 0
	s_add_i32 s66, 0, 0x18000
	s_add_i32 s67, 0, 0x1c000
	v_add_u32_e32 v140, s66, v190
	v_add_u32_e32 v176, s67, v190
	ds_read_b128 v[128:131], v140
	ds_read_b128 v[132:135], v140 offset:1024
	ds_read_b128 v[136:139], v140 offset:2048
	ds_read_b128 v[140:143], v140 offset:3072
	ds_read_b128 v[160:163], v176
	ds_read_b128 v[168:171], v176 offset:1024
	ds_read_b128 v[172:175], v176 offset:2048
	ds_read_b128 v[176:179], v176 offset:3072
	s_add_u32 s38, s38, 0x490000
	s_addc_u32 s39, s39, 0
	s_mov_b32 m0, s45
	ds_read_b128 v[180:183], v194 offset:32768
	ds_read_b128 v[184:187], v194 offset:33792
	ds_read_b128 v[196:199], v194 offset:34816
	ds_read_b128 v[200:203], v194 offset:35840
	ds_read_b128 v[204:207], v194 offset:36864
	ds_read_b128 v[208:211], v194 offset:37888
	ds_read_b128 v[212:215], v194 offset:38912
	ds_read_b128 v[216:219], v194 offset:39936
	global_load_lds_dwordx4 v144, s[38:39]
	s_mov_b32 m0, s46
	s_nop 0
	global_load_lds_dwordx4 v148, s[38:39]
	s_waitcnt vmcnt(8)
	s_waitcnt lgkmcnt(0)
	s_barrier
	s_setprio 1
	s_waitcnt lgkmcnt(0)
	v_mfma_f32_16x16x32_bf16 v[124:127], v[128:131], v[180:183], v[124:127]
	v_mfma_f32_16x16x32_bf16 v[124:127], v[132:135], v[184:187], v[124:127]
	v_mfma_f32_16x16x32_bf16 v[120:123], v[140:143], v[184:187], v[120:123]
	v_mfma_f32_16x16x32_bf16 v[120:123], v[136:139], v[180:183], v[120:123]
	v_mfma_f32_16x16x32_bf16 v[104:107], v[136:139], v[196:199], v[104:107]
	v_mfma_f32_16x16x32_bf16 v[104:107], v[140:143], v[200:203], v[104:107]
	v_mfma_f32_16x16x32_bf16 v[108:111], v[132:135], v[200:203], v[108:111]
	v_mfma_f32_16x16x32_bf16 v[108:111], v[128:131], v[196:199], v[108:111]
	v_mfma_f32_16x16x32_bf16 v[92:95], v[128:131], v[204:207], v[92:95]
	v_mfma_f32_16x16x32_bf16 v[92:95], v[132:135], v[208:211], v[92:95]
	v_mfma_f32_16x16x32_bf16 v[88:91], v[140:143], v[208:211], v[88:91]
	v_mfma_f32_16x16x32_bf16 v[88:91], v[136:139], v[204:207], v[88:91]
	v_mfma_f32_16x16x32_bf16 v[72:75], v[136:139], v[212:215], v[72:75]
	v_mfma_f32_16x16x32_bf16 v[72:75], v[140:143], v[216:219], v[72:75]
	v_mfma_f32_16x16x32_bf16 v[76:79], v[132:135], v[216:219], v[76:79]
	v_mfma_f32_16x16x32_bf16 v[76:79], v[128:131], v[212:215], v[76:79]
	v_mfma_f32_16x16x32_bf16 v[116:119], v[160:163], v[180:183], v[116:119]
	v_mfma_f32_16x16x32_bf16 v[116:119], v[168:171], v[184:187], v[116:119]
	v_mfma_f32_16x16x32_bf16 v[112:115], v[176:179], v[184:187], v[112:115]
	v_mfma_f32_16x16x32_bf16 v[112:115], v[172:175], v[180:183], v[112:115]
	v_mfma_f32_16x16x32_bf16 v[96:99], v[172:175], v[196:199], v[96:99]
	v_mfma_f32_16x16x32_bf16 v[96:99], v[176:179], v[200:203], v[96:99]
	v_mfma_f32_16x16x32_bf16 v[100:103], v[168:171], v[200:203], v[100:103]
	v_mfma_f32_16x16x32_bf16 v[100:103], v[160:163], v[196:199], v[100:103]
	v_mfma_f32_16x16x32_bf16 v[84:87], v[160:163], v[204:207], v[84:87]
	v_mfma_f32_16x16x32_bf16 v[84:87], v[168:171], v[208:211], v[84:87]
	s_setprio 2
	s_barrier
	v_mfma_f32_16x16x32_bf16 v[80:83], v[176:179], v[208:211], v[80:83]
	v_mfma_f32_16x16x32_bf16 v[80:83], v[172:175], v[204:207], v[80:83]
	v_mfma_f32_16x16x32_bf16 v[64:67], v[172:175], v[212:215], v[64:67]
	v_mfma_f32_16x16x32_bf16 v[64:67], v[176:179], v[216:219], v[64:67]
	v_mfma_f32_16x16x32_bf16 v[68:71], v[168:171], v[216:219], v[68:71]
	v_mfma_f32_16x16x32_bf16 v[68:71], v[160:163], v[212:215], v[68:71]
	s_setprio 0
	s_add_i32 s38, s66, s40
	s_mov_b32 m0, s38
	ds_read_b128 v[180:183], v194 offset:49152
	ds_read_b128 v[184:187], v194 offset:50176
	ds_read_b128 v[196:199], v194 offset:51200
	ds_read_b128 v[200:203], v194 offset:52224
	ds_read_b128 v[204:207], v194 offset:53248
	ds_read_b128 v[208:211], v194 offset:54272
	ds_read_b128 v[212:215], v194 offset:55296
	ds_read_b128 v[216:219], v194 offset:56320
	global_load_lds_dwordx4 v146, s[98:99]
	s_add_i32 m0, s38, 0x2000
	s_add_u32 s36, s36, 0x200080
	s_addc_u32 s37, s37, 0
	s_add_i32 s38, s67, s40
	global_load_lds_dwordx4 v150, s[98:99]
	s_mov_b32 m0, s38
	s_nop 0
	global_load_lds_dwordx4 v146, s[36:37]
	s_add_i32 m0, s38, 0x2000
	s_nop 0
	global_load_lds_dwordx4 v150, s[36:37]
	s_mov_b32 m0, s47
	s_nop 0
	global_load_lds_dwordx4 v144, s[100:101]
	s_mov_b32 m0, s48
	s_nop 0
	global_load_lds_dwordx4 v148, s[100:101]
	s_waitcnt vmcnt(8)
	s_waitcnt lgkmcnt(0)
	s_barrier
	s_setprio 1
	s_waitcnt lgkmcnt(0)
	v_mfma_f32_16x16x32_bf16 v[60:63], v[128:131], v[180:183], v[60:63]
	v_mfma_f32_16x16x32_bf16 v[60:63], v[132:135], v[184:187], v[60:63]
	v_mfma_f32_16x16x32_bf16 v[56:59], v[140:143], v[184:187], v[56:59]
	v_mfma_f32_16x16x32_bf16 v[56:59], v[136:139], v[180:183], v[56:59]
	v_mfma_f32_16x16x32_bf16 v[40:43], v[136:139], v[196:199], v[40:43]
	v_mfma_f32_16x16x32_bf16 v[40:43], v[140:143], v[200:203], v[40:43]
	v_mfma_f32_16x16x32_bf16 v[44:47], v[132:135], v[200:203], v[44:47]
	v_mfma_f32_16x16x32_bf16 v[44:47], v[128:131], v[196:199], v[44:47]
	v_mfma_f32_16x16x32_bf16 v[28:31], v[128:131], v[204:207], v[28:31]
	v_mfma_f32_16x16x32_bf16 v[28:31], v[132:135], v[208:211], v[28:31]
	v_mfma_f32_16x16x32_bf16 v[24:27], v[140:143], v[208:211], v[24:27]
	v_mfma_f32_16x16x32_bf16 v[24:27], v[136:139], v[204:207], v[24:27]
	v_mfma_f32_16x16x32_bf16 v[8:11], v[136:139], v[212:215], v[8:11]
	v_mfma_f32_16x16x32_bf16 v[8:11], v[140:143], v[216:219], v[8:11]
	v_mfma_f32_16x16x32_bf16 v[12:15], v[132:135], v[216:219], v[12:15]
	v_mfma_f32_16x16x32_bf16 v[12:15], v[128:131], v[212:215], v[12:15]
	v_mfma_f32_16x16x32_bf16 v[52:55], v[160:163], v[180:183], v[52:55]
	v_mfma_f32_16x16x32_bf16 v[52:55], v[168:171], v[184:187], v[52:55]
	v_mfma_f32_16x16x32_bf16 v[48:51], v[176:179], v[184:187], v[48:51]
	v_mfma_f32_16x16x32_bf16 v[48:51], v[172:175], v[180:183], v[48:51]
	v_mfma_f32_16x16x32_bf16 v[32:35], v[172:175], v[196:199], v[32:35]
	v_mfma_f32_16x16x32_bf16 v[32:35], v[176:179], v[200:203], v[32:35]
	v_mfma_f32_16x16x32_bf16 v[36:39], v[168:171], v[200:203], v[36:39]
	v_mfma_f32_16x16x32_bf16 v[36:39], v[160:163], v[196:199], v[36:39]
	v_mfma_f32_16x16x32_bf16 v[20:23], v[160:163], v[204:207], v[20:23]
	v_mfma_f32_16x16x32_bf16 v[20:23], v[168:171], v[208:211], v[20:23]
	s_setprio 2
	s_barrier
; #define PG8_STAGE(bufoff, gbase, voff) do { _Pragma("unroll") for (int _i = 0; _i < 2; ++_i) \
;         __builtin_amdgcn_global_load_lds((const unsigned*)((const char*)(gbase) + (voff)[_i]), (PG8_LAS unsigned*)(lds + (bufoff) + ldsw + _i * 8192), 16, 0, 0); } while (0)
; #define PG8_LDA(dst, b, h) do { _Pragma("unroll") for (int m = 0; m < 4; ++m) _Pragma("unroll") for (int k = 0; k < 2; ++k) dst[m][k] = *(const PG8_LAS bf16x8*)(lds + PG8_SA(b, h) + aoff + m * 2048 + k * 1024); } while (0)
; #define PG8_BAR __builtin_amdgcn_s_barrier()
; template <class Epi, class Sched, bool ALIGN_EPI = false, bool SP2 = false>
; __device__ __forceinline__ void gemm_phase(PG8_LAS unsigned char* lds, const Gemm g, const Sched& S, const Epi& E) {
;     ...
;         for (int t = 0; t < nt; t += 2) {
;             const bool last = (t == nt - 2);
;             const char* a1 = cA + (size_t)(t + 1) * kstep + (t >= g.kj_t ? g.kj_bytes : 0);
;             const char* a2 = last ? nA : cA + (size_t)(t + 2) * kstep + (t + 2 >= g.kj_t ? g.kj_bytes : 0); const char* b2 = last ? nB : cB + (size_t)(t + 2) * kstep;
;             const char* a3 = a2 + kstep; const char* b3 = b2 + kstep;
;             if (last && has_next) S.a_ready(nxt);
;             if constexpr (Epi::MIDK) { if (t == g.kj_t) E.midk(acc, cur, wr, fr); }
;             if constexpr (SP2) {
;             PG8_LDB(B0, 0, 0); PG8_LDB(B1, 0, 1); PG8_SCHED; PG8_LDA(At, 0, 0); PG8_STAGE(PG8_SA(1, 1), a1 + hstepA, voffA);
;             PG8_WAIT_V(8); PG8_WAIT_L(0); PG8_BAR; PG8_MMA(0, 0, At, B0); PG8_MMA(0, 1, At, B1); PG8_BAR; PG8_SCHED;
;             PG8_LDA(At, 0, 1); PG8_STAGE(PG8_SB(0, 0), b2, voffB); PG8_STAGE(PG8_SB(0, 1), b2 + hstepB, voffB); PG8_STAGE(PG8_SA(0, 0), a2, voffA);
;             PG8_WAIT_V(8); PG8_WAIT_L(0); PG8_BAR; PG8_MMA(1, 0, At, B0); PG8_MMA(1, 1, At, B1); PG8_BAR; PG8_SCHED;
;             PG8_LDB(B0, 1, 0); PG8_LDB(B1, 1, 1); PG8_SCHED; PG8_LDA(At, 1, 0); PG8_STAGE(PG8_SA(0, 1), a2 + hstepA, voffA);
;             PG8_WAIT_V(8); PG8_WAIT_L(0); PG8_BAR; PG8_MMA(0, 0, At, B0); PG8_MMA(0, 1, At, B1); PG8_BAR; PG8_SCHED;
;             PG8_LDA(At, 1, 1); PG8_STAGE(PG8_SB(1, 0), b3, voffB); PG8_STAGE(PG8_SB(1, 1), b3 + hstepB, voffB); PG8_STAGE(PG8_SA(1, 0), a3, voffA);
;             PG8_WAIT_V(8); PG8_WAIT_L(0); PG8_BAR; PG8_MMA(1, 0, At, B0); PG8_MMA(1, 1, At, B1); PG8_BAR; PG8_SCHED;
	v_mfma_f32_16x16x32_bf16 v[16:19], v[176:179], v[208:211], v[16:19]
	v_mfma_f32_16x16x32_bf16 v[16:19], v[172:175], v[204:207], v[16:19]
	v_mfma_f32_16x16x32_bf16 v[0:3], v[172:175], v[212:215], v[0:3]
	v_mfma_f32_16x16x32_bf16 v[0:3], v[176:179], v[216:219], v[0:3]
	v_mfma_f32_16x16x32_bf16 v[4:7], v[168:171], v[216:219], v[4:7]
	v_mfma_f32_16x16x32_bf16 v[4:7], v[160:163], v[212:215], v[4:7]
	s_setprio 0
	s_add_i32 s65, s65, 2
	s_add_u32 s6, s6, 0x100
	s_addc_u32 s7, s7, 0
	s_add_u32 s63, s63, 0x100
	s_addc_u32 s64, s64, 0
.LBB0_882:
	ds_read_b128 v[128:131], v192
	ds_read_b128 v[132:135], v192 offset:1024
	ds_read_b128 v[136:139], v192 offset:2048
	ds_read_b128 v[140:143], v192 offset:3072
	ds_read_b128 v[160:163], v193
	ds_read_b128 v[168:171], v193 offset:1024
	ds_read_b128 v[172:175], v193 offset:2048
	ds_read_b128 v[176:179], v193 offset:3072
	s_add_u32 s36, s6, 0xffb70080
	s_addc_u32 s37, s7, -1
	s_cmpk_eq_i32 s65, 0x7c
	s_cselect_b32 s39, s29, s37
	s_cselect_b32 s38, s28, s36
	s_cselect_b32 s37, s27, s64
	s_cselect_b32 s36, s35, s63
	s_add_u32 s98, s36, 0x80
	s_addc_u32 s99, s37, 0
	s_add_u32 s100, s38, 0x80
	s_addc_u32 s101, s39, 0
	s_add_i32 m0, s41, 0xc000
	ds_read_b128 v[180:183], v194
	ds_read_b128 v[184:187], v194 offset:1024
	ds_read_b128 v[196:199], v194 offset:2048
	ds_read_b128 v[200:203], v194 offset:3072
	ds_read_b128 v[204:207], v194 offset:4096
	ds_read_b128 v[208:211], v194 offset:5120
	ds_read_b128 v[212:215], v194 offset:6144
	ds_read_b128 v[216:219], v194 offset:7168
	global_load_lds_dwordx4 v152, s[6:7]
	s_add_i32 m0, s41, 0xe000
	s_nop 0
	global_load_lds_dwordx4 v154, s[6:7]
	s_waitcnt vmcnt(8)
	s_waitcnt lgkmcnt(0)
	s_barrier
	s_setprio 1
	s_waitcnt lgkmcnt(0)
	v_mfma_f32_16x16x32_bf16 v[124:127], v[128:131], v[180:183], v[124:127]
	v_mfma_f32_16x16x32_bf16 v[124:127], v[132:135], v[184:187], v[124:127]
	v_mfma_f32_16x16x32_bf16 v[120:123], v[140:143], v[184:187], v[120:123]
	v_mfma_f32_16x16x32_bf16 v[120:123], v[136:139], v[180:183], v[120:123]
	v_mfma_f32_16x16x32_bf16 v[104:107], v[136:139], v[196:199], v[104:107]
	v_mfma_f32_16x16x32_bf16 v[104:107], v[140:143], v[200:203], v[104:107]
	v_mfma_f32_16x16x32_bf16 v[108:111], v[132:135], v[200:203], v[108:111]
	v_mfma_f32_16x16x32_bf16 v[108:111], v[128:131], v[196:199], v[108:111]
	v_mfma_f32_16x16x32_bf16 v[92:95], v[128:131], v[204:207], v[92:95]
	v_mfma_f32_16x16x32_bf16 v[92:95], v[132:135], v[208:211], v[92:95]
	v_mfma_f32_16x16x32_bf16 v[88:91], v[140:143], v[208:211], v[88:91]
	v_mfma_f32_16x16x32_bf16 v[88:91], v[136:139], v[204:207], v[88:91]
	v_mfma_f32_16x16x32_bf16 v[72:75], v[136:139], v[212:215], v[72:75]
	v_mfma_f32_16x16x32_bf16 v[72:75], v[140:143], v[216:219], v[72:75]
	v_mfma_f32_16x16x32_bf16 v[76:79], v[132:135], v[216:219], v[76:79]
	v_mfma_f32_16x16x32_bf16 v[76:79], v[128:131], v[212:215], v[76:79]
	v_mfma_f32_16x16x32_bf16 v[116:119], v[160:163], v[180:183], v[116:119]
	v_mfma_f32_16x16x32_bf16 v[116:119], v[168:171], v[184:187], v[116:119]
	v_mfma_f32_16x16x32_bf16 v[112:115], v[176:179], v[184:187], v[112:115]
	v_mfma_f32_16x16x32_bf16 v[112:115], v[172:175], v[180:183], v[112:115]
	v_mfma_f32_16x16x32_bf16 v[96:99], v[172:175], v[196:199], v[96:99]
	v_mfma_f32_16x16x32_bf16 v[96:99], v[176:179], v[200:203], v[96:99]
	v_mfma_f32_16x16x32_bf16 v[100:103], v[168:171], v[200:203], v[100:103]
	v_mfma_f32_16x16x32_bf16 v[100:103], v[160:163], v[196:199], v[100:103]
	v_mfma_f32_16x16x32_bf16 v[84:87], v[160:163], v[204:207], v[84:87]
	v_mfma_f32_16x16x32_bf16 v[84:87], v[168:171], v[208:211], v[84:87]
	s_setprio 2
	s_barrier
	v_mfma_f32_16x16x32_bf16 v[80:83], v[176:179], v[208:211], v[80:83]
	v_mfma_f32_16x16x32_bf16 v[80:83], v[172:175], v[204:207], v[80:83]
	v_mfma_f32_16x16x32_bf16 v[64:67], v[172:175], v[212:215], v[64:67]
	v_mfma_f32_16x16x32_bf16 v[64:67], v[176:179], v[216:219], v[64:67]
	v_mfma_f32_16x16x32_bf16 v[68:71], v[168:171], v[216:219], v[68:71]
	v_mfma_f32_16x16x32_bf16 v[68:71], v[160:163], v[212:215], v[68:71]
	s_setprio 0
	s_add_i32 s66, s52, s40
	s_mov_b32 m0, s66
	ds_read_b128 v[180:183], v194 offset:16384
	ds_read_b128 v[184:187], v194 offset:17408
	ds_read_b128 v[196:199], v194 offset:18432
	ds_read_b128 v[200:203], v194 offset:19456
	ds_read_b128 v[204:207], v194 offset:20480
	ds_read_b128 v[208:211], v194 offset:21504
	ds_read_b128 v[212:215], v194 offset:22528
	ds_read_b128 v[216:219], v194 offset:23552
	global_load_lds_dwordx4 v146, s[36:37]
	s_add_i32 m0, s66, 0x2000
	s_add_u32 s66, s36, 0x200000
	s_addc_u32 s67, s37, 0
	s_add_i32 s68, s53, s40
	global_load_lds_dwordx4 v150, s[36:37]
	s_mov_b32 m0, s68
	s_nop 0
	global_load_lds_dwordx4 v146, s[66:67]
	s_add_i32 m0, s68, 0x2000
	s_nop 0
	global_load_lds_dwordx4 v150, s[66:67]
	s_mov_b32 m0, s41
	s_nop 0
	global_load_lds_dwordx4 v144, s[38:39]
	s_mov_b32 m0, s44
	s_nop 0
	global_load_lds_dwordx4 v148, s[38:39]
	s_waitcnt vmcnt(8)
	s_waitcnt lgkmcnt(0)
	s_barrier
; #define PG8_STAGE(bufoff, gbase, voff) do { _Pragma("unroll") for (int _i = 0; _i < 2; ++_i) \
;         __builtin_amdgcn_global_load_lds((const unsigned*)((const char*)(gbase) + (voff)[_i]), (PG8_LAS unsigned*)(lds + (bufoff) + ldsw + _i * 8192), 16, 0, 0); } while (0)
; #define PG8_LDA(dst, b, h) do { _Pragma("unroll") for (int m = 0; m < 4; ++m) _Pragma("unroll") for (int k = 0; k < 2; ++k) dst[m][k] = *(const PG8_LAS bf16x8*)(lds + PG8_SA(b, h) + aoff + m * 2048 + k * 1024); } while (0)
; #define PG8_LDB(dst, b, h) do { _Pragma("unroll") for (int n = 0; n < 2; ++n) _Pragma("unroll") for (int k = 0; k < 2; ++k) dst[n][k] = *(const PG8_LAS bf16x8*)(lds + PG8_SB(b, h) + boff + n * 2048 + k * 1024); } while (0)
; #define PG8_MMA(ai, bj, At, Bt) do { __builtin_amdgcn_s_setprio(1); _Pragma("unroll") for (int m = 0; m < 4; ++m) _Pragma("unroll") for (int n = 0; n < 2; ++n) _Pragma("unroll") for (int k = 0; k < 2; ++k) \
;         acc[ai][bj][m][n] = __builtin_amdgcn_mfma_f32_16x16x32_bf16(Bt[n][k], At[m][k], acc[ai][bj][m][n], 0, 0, 0); __builtin_amdgcn_s_setprio(0); } while (0)
; template <class Epi, class Sched, bool ALIGN_EPI = false, bool SP2 = false>
; __device__ __forceinline__ void gemm_phase(PG8_LAS unsigned char* lds, const Gemm g, const Sched& S, const Epi& E) {
;     ...
;             if constexpr (SP2) {
;             PG8_LDB(B0, 0, 0); PG8_LDB(B1, 0, 1); PG8_SCHED; PG8_LDA(At, 0, 0); PG8_STAGE(PG8_SA(1, 1), a1 + hstepA, voffA);
;             PG8_WAIT_V(8); PG8_WAIT_L(0); PG8_BAR; PG8_MMA(0, 0, At, B0); PG8_MMA(0, 1, At, B1); PG8_BAR; PG8_SCHED;
;             PG8_LDA(At, 0, 1); PG8_STAGE(PG8_SB(0, 0), b2, voffB); PG8_STAGE(PG8_SB(0, 1), b2 + hstepB, voffB); PG8_STAGE(PG8_SA(0, 0), a2, voffA);
;             PG8_WAIT_V(8); PG8_WAIT_L(0); PG8_BAR; PG8_MMA(1, 0, At, B0); PG8_MMA(1, 1, At, B1); PG8_BAR; PG8_SCHED;
;             PG8_LDB(B0, 1, 0); PG8_LDB(B1, 1, 1); PG8_SCHED; PG8_LDA(At, 1, 0); PG8_STAGE(PG8_SA(0, 1), a2 + hstepA, voffA);
;             PG8_WAIT_V(8); PG8_WAIT_L(0); PG8_BAR; PG8_MMA(0, 0, At, B0); PG8_MMA(0, 1, At, B1); PG8_BAR; PG8_SCHED;
;             PG8_LDA(At, 1, 1); PG8_STAGE(PG8_SB(1, 0), b3, voffB); PG8_STAGE(PG8_SB(1, 1), b3 + hstepB, voffB); PG8_STAGE(PG8_SA(1, 0), a3, voffA);
;             PG8_WAIT_V(8); PG8_WAIT_L(0); PG8_BAR; PG8_MMA(1, 0, At, B0); PG8_MMA(1, 1, At, B1); PG8_BAR; PG8_SCHED;
	s_setprio 1
	s_waitcnt lgkmcnt(0)
	v_mfma_f32_16x16x32_bf16 v[60:63], v[128:131], v[180:183], v[60:63]
	v_mfma_f32_16x16x32_bf16 v[60:63], v[132:135], v[184:187], v[60:63]
	v_mfma_f32_16x16x32_bf16 v[56:59], v[140:143], v[184:187], v[56:59]
	v_mfma_f32_16x16x32_bf16 v[56:59], v[136:139], v[180:183], v[56:59]
	v_mfma_f32_16x16x32_bf16 v[40:43], v[136:139], v[196:199], v[40:43]
	v_mfma_f32_16x16x32_bf16 v[40:43], v[140:143], v[200:203], v[40:43]
	v_mfma_f32_16x16x32_bf16 v[44:47], v[132:135], v[200:203], v[44:47]
	v_mfma_f32_16x16x32_bf16 v[44:47], v[128:131], v[196:199], v[44:47]
	v_mfma_f32_16x16x32_bf16 v[28:31], v[128:131], v[204:207], v[28:31]
	v_mfma_f32_16x16x32_bf16 v[28:31], v[132:135], v[208:211], v[28:31]
	v_mfma_f32_16x16x32_bf16 v[24:27], v[140:143], v[208:211], v[24:27]
	v_mfma_f32_16x16x32_bf16 v[24:27], v[136:139], v[204:207], v[24:27]
	v_mfma_f32_16x16x32_bf16 v[8:11], v[136:139], v[212:215], v[8:11]
	v_mfma_f32_16x16x32_bf16 v[8:11], v[140:143], v[216:219], v[8:11]
	v_mfma_f32_16x16x32_bf16 v[12:15], v[132:135], v[216:219], v[12:15]
	v_mfma_f32_16x16x32_bf16 v[12:15], v[128:131], v[212:215], v[12:15]
	v_mfma_f32_16x16x32_bf16 v[52:55], v[160:163], v[180:183], v[52:55]
	v_mfma_f32_16x16x32_bf16 v[52:55], v[168:171], v[184:187], v[52:55]
	v_mfma_f32_16x16x32_bf16 v[48:51], v[176:179], v[184:187], v[48:51]
	v_mfma_f32_16x16x32_bf16 v[48:51], v[172:175], v[180:183], v[48:51]
	v_mfma_f32_16x16x32_bf16 v[32:35], v[172:175], v[196:199], v[32:35]
	v_mfma_f32_16x16x32_bf16 v[32:35], v[176:179], v[200:203], v[32:35]
	v_mfma_f32_16x16x32_bf16 v[36:39], v[168:171], v[200:203], v[36:39]
	v_mfma_f32_16x16x32_bf16 v[36:39], v[160:163], v[196:199], v[36:39]
	v_mfma_f32_16x16x32_bf16 v[20:23], v[160:163], v[204:207], v[20:23]
	v_mfma_f32_16x16x32_bf16 v[20:23], v[168:171], v[208:211], v[20:23]
	s_setprio 2
	s_barrier
	v_mfma_f32_16x16x32_bf16 v[16:19], v[176:179], v[208:211], v[16:19]
	v_mfma_f32_16x16x32_bf16 v[16:19], v[172:175], v[204:207], v[16:19]
	v_mfma_f32_16x16x32_bf16 v[0:3], v[172:175], v[212:215], v[0:3]
	v_mfma_f32_16x16x32_bf16 v[0:3], v[176:179], v[216:219], v[0:3]
	v_mfma_f32_16x16x32_bf16 v[4:7], v[168:171], v[216:219], v[4:7]
	v_mfma_f32_16x16x32_bf16 v[4:7], v[160:163], v[212:215], v[4:7]
	s_setprio 0
	s_add_i32 s66, 0, 0x18000
	s_add_i32 s67, 0, 0x1c000
	v_add_u32_e32 v140, s66, v190
	v_add_u32_e32 v176, s67, v190
	ds_read_b128 v[128:131], v140
	ds_read_b128 v[132:135], v140 offset:1024
	ds_read_b128 v[136:139], v140 offset:2048
	ds_read_b128 v[140:143], v140 offset:3072
	ds_read_b128 v[160:163], v176
	ds_read_b128 v[168:171], v176 offset:1024
	ds_read_b128 v[172:175], v176 offset:2048
	ds_read_b128 v[176:179], v176 offset:3072
	s_add_u32 s38, s38, 0x490000
	s_addc_u32 s39, s39, 0
	s_mov_b32 m0, s45
	ds_read_b128 v[180:183], v194 offset:32768
	ds_read_b128 v[184:187], v194 offset:33792
	ds_read_b128 v[196:199], v194 offset:34816
	ds_read_b128 v[200:203], v194 offset:35840
	ds_read_b128 v[204:207], v194 offset:36864
	ds_read_b128 v[208:211], v194 offset:37888
	ds_read_b128 v[212:215], v194 offset:38912
	ds_read_b128 v[216:219], v194 offset:39936
	global_load_lds_dwordx4 v144, s[38:39]
	s_mov_b32 m0, s46
	s_nop 0
	global_load_lds_dwordx4 v148, s[38:39]
	s_waitcnt vmcnt(8)
	s_waitcnt lgkmcnt(0)
	s_barrier
	s_setprio 1
	s_waitcnt lgkmcnt(0)
	v_mfma_f32_16x16x32_bf16 v[124:127], v[128:131], v[180:183], v[124:127]
	v_mfma_f32_16x16x32_bf16 v[124:127], v[132:135], v[184:187], v[124:127]
	v_mfma_f32_16x16x32_bf16 v[120:123], v[140:143], v[184:187], v[120:123]
	v_mfma_f32_16x16x32_bf16 v[120:123], v[136:139], v[180:183], v[120:123]
	v_mfma_f32_16x16x32_bf16 v[104:107], v[136:139], v[196:199], v[104:107]
	v_mfma_f32_16x16x32_bf16 v[104:107], v[140:143], v[200:203], v[104:107]
	v_mfma_f32_16x16x32_bf16 v[108:111], v[132:135], v[200:203], v[108:111]
	v_mfma_f32_16x16x32_bf16 v[108:111], v[128:131], v[196:199], v[108:111]
	v_mfma_f32_16x16x32_bf16 v[92:95], v[128:131], v[204:207], v[92:95]
	v_mfma_f32_16x16x32_bf16 v[92:95], v[132:135], v[208:211], v[92:95]
	v_mfma_f32_16x16x32_bf16 v[88:91], v[140:143], v[208:211], v[88:91]
	v_mfma_f32_16x16x32_bf16 v[88:91], v[136:139], v[204:207], v[88:91]
	v_mfma_f32_16x16x32_bf16 v[72:75], v[136:139], v[212:215], v[72:75]
	v_mfma_f32_16x16x32_bf16 v[72:75], v[140:143], v[216:219], v[72:75]
	v_mfma_f32_16x16x32_bf16 v[76:79], v[132:135], v[216:219], v[76:79]
	v_mfma_f32_16x16x32_bf16 v[76:79], v[128:131], v[212:215], v[76:79]
	v_mfma_f32_16x16x32_bf16 v[116:119], v[160:163], v[180:183], v[116:119]
	v_mfma_f32_16x16x32_bf16 v[116:119], v[168:171], v[184:187], v[116:119]
	v_mfma_f32_16x16x32_bf16 v[112:115], v[176:179], v[184:187], v[112:115]
	v_mfma_f32_16x16x32_bf16 v[112:115], v[172:175], v[180:183], v[112:115]
	v_mfma_f32_16x16x32_bf16 v[96:99], v[172:175], v[196:199], v[96:99]
	v_mfma_f32_16x16x32_bf16 v[96:99], v[176:179], v[200:203], v[96:99]
	v_mfma_f32_16x16x32_bf16 v[100:103], v[168:171], v[200:203], v[100:103]
	v_mfma_f32_16x16x32_bf16 v[100:103], v[160:163], v[196:199], v[100:103]
	v_mfma_f32_16x16x32_bf16 v[84:87], v[160:163], v[204:207], v[84:87]
	v_mfma_f32_16x16x32_bf16 v[84:87], v[168:171], v[208:211], v[84:87]
	s_setprio 2
	s_barrier
; #define PG8_STAGE(bufoff, gbase, voff) do { _Pragma("unroll") for (int _i = 0; _i < 2; ++_i) \
;         __builtin_amdgcn_global_load_lds((const unsigned*)((const char*)(gbase) + (voff)[_i]), (PG8_LAS unsigned*)(lds + (bufoff) + ldsw + _i * 8192), 16, 0, 0); } while (0)
; #define PG8_LDA(dst, b, h) do { _Pragma("unroll") for (int m = 0; m < 4; ++m) _Pragma("unroll") for (int k = 0; k < 2; ++k) dst[m][k] = *(const PG8_LAS bf16x8*)(lds + PG8_SA(b, h) + aoff + m * 2048 + k * 1024); } while (0)
; #define PG8_BAR __builtin_amdgcn_s_barrier()
; template <class Epi, class Sched, bool ALIGN_EPI = false, bool SP2 = false>
; __device__ __forceinline__ void gemm_phase(PG8_LAS unsigned char* lds, const Gemm g, const Sched& S, const Epi& E) {
;     ...
;         for (int t = 0; t < nt; t += 2) {
;             const bool last = (t == nt - 2);
;             const char* a1 = cA + (size_t)(t + 1) * kstep + (t >= g.kj_t ? g.kj_bytes : 0);
;             const char* a2 = last ? nA : cA + (size_t)(t + 2) * kstep + (t + 2 >= g.kj_t ? g.kj_bytes : 0); const char* b2 = last ? nB : cB + (size_t)(t + 2) * kstep;
;             const char* a3 = a2 + kstep; const char* b3 = b2 + kstep;
;             if (last && has_next) S.a_ready(nxt);
;             if constexpr (Epi::MIDK) { if (t == g.kj_t) E.midk(acc, cur, wr, fr); }
;             if constexpr (SP2) {
;             PG8_LDB(B0, 0, 0); PG8_LDB(B1, 0, 1); PG8_SCHED; PG8_LDA(At, 0, 0); PG8_STAGE(PG8_SA(1, 1), a1 + hstepA, voffA);
;             PG8_WAIT_V(8); PG8_WAIT_L(0); PG8_BAR; PG8_MMA(0, 0, At, B0); PG8_MMA(0, 1, At, B1); PG8_BAR; PG8_SCHED;
;             PG8_LDA(At, 0, 1); PG8_STAGE(PG8_SB(0, 0), b2, voffB); PG8_STAGE(PG8_SB(0, 1), b2 + hstepB, voffB); PG8_STAGE(PG8_SA(0, 0), a2, voffA);
;             PG8_WAIT_V(8); PG8_WAIT_L(0); PG8_BAR; PG8_MMA(1, 0, At, B0); PG8_MMA(1, 1, At, B1); PG8_BAR; PG8_SCHED;
;             PG8_LDB(B0, 1, 0); PG8_LDB(B1, 1, 1); PG8_SCHED; PG8_LDA(At, 1, 0); PG8_STAGE(PG8_SA(0, 1), a2 + hstepA, voffA);
;             PG8_WAIT_V(8); PG8_WAIT_L(0); PG8_BAR; PG8_MMA(0, 0, At, B0); PG8_MMA(0, 1, At, B1); PG8_BAR; PG8_SCHED;
;             PG8_LDA(At, 1, 1); PG8_STAGE(PG8_SB(1, 0), b3, voffB); PG8_STAGE(PG8_SB(1, 1), b3 + hstepB, voffB); PG8_STAGE(PG8_SA(1, 0), a3, voffA);
;             PG8_WAIT_V(8); PG8_WAIT_L(0); PG8_BAR; PG8_MMA(1, 0, At, B0); PG8_MMA(1, 1, At, B1); PG8_BAR; PG8_SCHED;
	v_mfma_f32_16x16x32_bf16 v[80:83], v[176:179], v[208:211], v[80:83]
	v_mfma_f32_16x16x32_bf16 v[80:83], v[172:175], v[204:207], v[80:83]
	v_mfma_f32_16x16x32_bf16 v[64:67], v[172:175], v[212:215], v[64:67]
	v_mfma_f32_16x16x32_bf16 v[64:67], v[176:179], v[216:219], v[64:67]
	v_mfma_f32_16x16x32_bf16 v[68:71], v[168:171], v[216:219], v[68:71]
	v_mfma_f32_16x16x32_bf16 v[68:71], v[160:163], v[212:215], v[68:71]
	s_setprio 0
	s_add_i32 s38, s66, s40
	s_mov_b32 m0, s38
	ds_read_b128 v[180:183], v194 offset:49152
	ds_read_b128 v[184:187], v194 offset:50176
	ds_read_b128 v[196:199], v194 offset:51200
	ds_read_b128 v[200:203], v194 offset:52224
	ds_read_b128 v[204:207], v194 offset:53248
	ds_read_b128 v[208:211], v194 offset:54272
	ds_read_b128 v[212:215], v194 offset:55296
	ds_read_b128 v[216:219], v194 offset:56320
	global_load_lds_dwordx4 v146, s[98:99]
	s_add_i32 m0, s38, 0x2000
	s_add_u32 s36, s36, 0x200080
	s_addc_u32 s37, s37, 0
	s_add_i32 s38, s67, s40
	global_load_lds_dwordx4 v150, s[98:99]
	s_mov_b32 m0, s38
	s_nop 0
	global_load_lds_dwordx4 v146, s[36:37]
	s_add_i32 m0, s38, 0x2000
	s_nop 0
	global_load_lds_dwordx4 v150, s[36:37]
	s_mov_b32 m0, s47
	s_nop 0
	global_load_lds_dwordx4 v144, s[100:101]
	s_mov_b32 m0, s48
	s_nop 0
	global_load_lds_dwordx4 v148, s[100:101]
	s_waitcnt vmcnt(8)
	s_waitcnt lgkmcnt(0)
	s_barrier
	s_setprio 1
	s_waitcnt lgkmcnt(0)
	v_mfma_f32_16x16x32_bf16 v[60:63], v[128:131], v[180:183], v[60:63]
	v_mfma_f32_16x16x32_bf16 v[60:63], v[132:135], v[184:187], v[60:63]
	v_mfma_f32_16x16x32_bf16 v[56:59], v[140:143], v[184:187], v[56:59]
	v_mfma_f32_16x16x32_bf16 v[56:59], v[136:139], v[180:183], v[56:59]
	v_mfma_f32_16x16x32_bf16 v[40:43], v[136:139], v[196:199], v[40:43]
	v_mfma_f32_16x16x32_bf16 v[40:43], v[140:143], v[200:203], v[40:43]
	v_mfma_f32_16x16x32_bf16 v[44:47], v[132:135], v[200:203], v[44:47]
	v_mfma_f32_16x16x32_bf16 v[44:47], v[128:131], v[196:199], v[44:47]
	v_mfma_f32_16x16x32_bf16 v[28:31], v[128:131], v[204:207], v[28:31]
	v_mfma_f32_16x16x32_bf16 v[28:31], v[132:135], v[208:211], v[28:31]
	v_mfma_f32_16x16x32_bf16 v[24:27], v[140:143], v[208:211], v[24:27]
	v_mfma_f32_16x16x32_bf16 v[24:27], v[136:139], v[204:207], v[24:27]
	v_mfma_f32_16x16x32_bf16 v[8:11], v[136:139], v[212:215], v[8:11]
	v_mfma_f32_16x16x32_bf16 v[8:11], v[140:143], v[216:219], v[8:11]
	v_mfma_f32_16x16x32_bf16 v[12:15], v[132:135], v[216:219], v[12:15]
	v_mfma_f32_16x16x32_bf16 v[12:15], v[128:131], v[212:215], v[12:15]
	v_mfma_f32_16x16x32_bf16 v[52:55], v[160:163], v[180:183], v[52:55]
	v_mfma_f32_16x16x32_bf16 v[52:55], v[168:171], v[184:187], v[52:55]
	v_mfma_f32_16x16x32_bf16 v[48:51], v[176:179], v[184:187], v[48:51]
	v_mfma_f32_16x16x32_bf16 v[48:51], v[172:175], v[180:183], v[48:51]
	v_mfma_f32_16x16x32_bf16 v[32:35], v[172:175], v[196:199], v[32:35]
	v_mfma_f32_16x16x32_bf16 v[32:35], v[176:179], v[200:203], v[32:35]
	v_mfma_f32_16x16x32_bf16 v[36:39], v[168:171], v[200:203], v[36:39]
	v_mfma_f32_16x16x32_bf16 v[36:39], v[160:163], v[196:199], v[36:39]
	v_mfma_f32_16x16x32_bf16 v[20:23], v[160:163], v[204:207], v[20:23]
	v_mfma_f32_16x16x32_bf16 v[20:23], v[168:171], v[208:211], v[20:23]
	s_setprio 2
	s_barrier
	v_mfma_f32_16x16x32_bf16 v[16:19], v[176:179], v[208:211], v[16:19]
	v_mfma_f32_16x16x32_bf16 v[16:19], v[172:175], v[204:207], v[16:19]
	v_mfma_f32_16x16x32_bf16 v[0:3], v[172:175], v[212:215], v[0:3]
	v_mfma_f32_16x16x32_bf16 v[0:3], v[176:179], v[216:219], v[0:3]
	v_mfma_f32_16x16x32_bf16 v[4:7], v[168:171], v[216:219], v[4:7]
	v_mfma_f32_16x16x32_bf16 v[4:7], v[160:163], v[212:215], v[4:7]
	s_setprio 0
	s_add_i32 s65, s65, 2
	s_add_u32 s6, s6, 0x100
	s_addc_u32 s7, s7, 0
	s_add_u32 s63, s63, 0x100
	s_addc_u32 s64, s64, 0
	s_cmpk_gt_u32 s65, 0x7d
	s_cbranch_scc0 .LBB0_882
	s_and_b64 vcc, exec, s[22:23]
	s_cbranch_vccz .LBB0_885
	s_barrier
